# indexer pass 0: whole-tile software pipeline, VALU of the previous head interleaved between the MFMAs, q reads issued one iteration earlier
# baseline (speedup 1.0000x reference)
; #define LAS __attribute__((address_space(3)))
; __device__ __forceinline__ void sel_unit(LAS char* lds, int b, int u, const bf16_t* QI, const bf16_t* KIDX, const float* WIDX, unsigned long long* MASK) {
;     ...
;     const LAS float* wl = (const LAS float*)(lds + L_W) + q16;
;     __syncthreads();
;     const int nj = (c - wid + 8) >> 3;
;     u32x4 sc[8][4];
; #pragma unroll
;     for (int j = 0; j < 8; ++j) {
;         if (j < nj) {
;             int t = wid + 8 * j; asm volatile("" : "+s"(t));
; #pragma unroll
;             for (int kh = 0; kh < 2; ++kh) {
;             bf16x8 kf[2][2];
; #pragma unroll
;             for (int kb = 0; kb < 2; ++kb)
; #pragma unroll
;                 for (int ks = 0; ks < 2; ++ks) kf[kb][ks] = *(const bf16x8*)(KIDX + (rowbase + 64 * t + 32 * kh + 16 * kb + q16) * 64 + 32 * ks + 8 * kg);
; #pragma unroll
;             for (int kb = 0; kb < 2; ++kb) {
;                 f32x4 s = (f32x4){0.f, 0.f, 0.f, 0.f};
; #pragma unroll
;                 for (int hh = 0; hh < 8; ++hh) {
;                     f32x4 a = (f32x4){0.f, 0.f, 0.f, 0.f};
; #pragma unroll
;                     for (int ks = 0; ks < 2; ++ks) {
;                         const bf16x8 qv = *(const LAS bf16x8*)(lds + L_QI + q16 * 1024 + (((hh * 8 + 4 * ks + kg) ^ q16) << 4));
;                         a = __builtin_amdgcn_mfma_f32_16x16x32_bf16(kf[kb][ks], qv, a, 0, 0, 0);
;                     }
;                     const float wh = wl[hh * 16];
; #pragma unroll
;                     for (int i = 0; i < 4; ++i) s[i] += wh * fmaxf(a[i], 0.f);
.LBB0_656:
	s_or_b64 exec, exec, s[2:3]
	s_ashr_i32 s46, s47, 6
	s_sub_i32 s2, s34, s46
	s_add_i32 s2, s2, 8
	s_ashr_i32 s4, s2, 3
	v_bfe_u32 v2, v2, 4, 2
	v_lshl_add_u32 v60, v59, 2, 0
	v_or_b32_e32 v18, s0, v59
	s_movk_i32 s0, 0x3fc
	s_cmp_gt_i32 s4, 0
	v_lshlrev_b32_e32 v0, 4, v2
	v_mad_u32_u24 v150, v59, s0, v60
	s_movk_i32 s0, 0xfc04
	s_cselect_b64 s[22:23], -1, 0
	v_mov_b32_e32 v19, s1
	v_lshl_add_u64 v[20:21], s[62:63], 0, v[0:1]
	v_mad_i32_i24 v0, v59, s0, v150
	s_and_b64 vcc, exec, s[22:23]
	v_xor_b32_e32 v182, v2, v59
	v_bitop3_b32 v183, v2, v59, 4 bitop3:0x36
	v_add_u32_e32 v137, 0x8800, v60
	v_bitop3_b32 v184, v2, v59, 8 bitop3:0x36
	v_bitop3_b32 v185, v2, v59, 12 bitop3:0x36
	v_bitop3_b32 v179, v2, v59, 16 bitop3:0x36
	v_bitop3_b32 v180, v2, v59, 20 bitop3:0x36
	v_bitop3_b32 v176, v2, v59, 24 bitop3:0x36
	v_bitop3_b32 v159, v2, v59, 28 bitop3:0x36
	v_bitop3_b32 v158, v2, v59, 32 bitop3:0x36
	v_bitop3_b32 v157, v2, v59, 36 bitop3:0x36
	v_bitop3_b32 v156, v2, v59, 40 bitop3:0x36
	v_bitop3_b32 v155, v2, v59, 44 bitop3:0x36
	v_bitop3_b32 v154, v2, v59, 48 bitop3:0x36
	v_bitop3_b32 v153, v2, v59, 52 bitop3:0x36
	v_bitop3_b32 v152, v2, v59, 56 bitop3:0x36
	v_bitop3_b32 v151, v2, v59, 60 bitop3:0x36
	v_lshl_add_u32 v182, v182, 4, v150
	v_lshl_add_u32 v183, v183, 4, v150
	v_lshl_add_u32 v184, v184, 4, v150
	v_lshl_add_u32 v185, v185, 4, v150
	v_lshl_add_u32 v179, v179, 4, v150
	v_lshl_add_u32 v180, v180, 4, v150
	v_lshl_add_u32 v176, v176, 4, v150
	v_lshl_add_u32 v159, v159, 4, v150
	v_lshl_add_u32 v158, v158, 4, v150
	v_lshl_add_u32 v157, v157, 4, v150
	v_lshl_add_u32 v156, v156, 4, v150
	v_lshl_add_u32 v155, v155, 4, v150
	v_lshl_add_u32 v154, v154, 4, v150
	v_lshl_add_u32 v153, v153, 4, v150
	v_lshl_add_u32 v152, v152, 4, v150
	v_lshl_add_u32 v151, v151, 4, v150
	s_waitcnt lgkmcnt(0)
	s_barrier
	s_cbranch_vccz .LBB0_658
	s_mov_b32 s0, s46
	s_lshl_b32 s0, s0, 6
	s_ashr_i32 s1, s0, 31
	v_lshl_add_u64 v[2:3], v[18:19], 0, s[0:1]
	v_lshlrev_b64 v[2:3], 7, v[2:3]
	v_lshl_add_u64 v[22:23], v[20:21], 0, v[2:3]
	v_bfrev_b32_e32 v8, 1
	global_load_dwordx4 v[26:29], v[22:23], off
	global_load_dwordx4 v[30:33], v[22:23], off offset:64
	global_load_dwordx4 v[34:37], v[22:23], off offset:2048
	global_load_dwordx4 v[38:41], v[22:23], off offset:2112
	ds_read_b128 v[230:233], v182
	ds_read_b128 v[234:237], v183
	ds_read_b32 v6, v137 offset:320
	ds_read_b128 v[238:241], v184
	ds_read_b128 v[242:245], v185
	ds_read_b32 v7, v137 offset:384
	s_waitcnt vmcnt(0)
	v_add_co_u32_e32 v22, vcc, s96, v22
	s_nop 1
	v_addc_co_u32_e32 v23, vcc, 0, v23, vcc
	global_load_dwordx4 v[42:45], v[22:23], off
	global_load_dwordx4 v[46:49], v[22:23], off offset:64
	global_load_dwordx4 v[50:53], v[22:23], off offset:2048
	global_load_dwordx4 v[2:5], v[22:23], off offset:2112
	s_waitcnt lgkmcnt(4)
	v_mfma_f32_16x16x32_bf16 v[246:249], v[26:29], v[230:233], 0
	v_mfma_f32_16x16x32_bf16 v[250:253], v[34:37], v[230:233], 0
	v_mfma_f32_16x16x32_bf16 v[246:249], v[30:33], v[234:237], v[246:249]
	v_mfma_f32_16x16x32_bf16 v[250:253], v[38:41], v[234:237], v[250:253]
	ds_read_b128 v[230:233], v179
	ds_read_b128 v[234:237], v180
	ds_read_b32 v217, v137 offset:448
	s_waitcnt lgkmcnt(4)
	s_nop 1
	v_mfma_f32_16x16x32_bf16 v[206:209], v[26:29], v[238:241], 0
	v_max_f32_e32 v9, 0, v246
	v_max_f32_e32 v200, 0, v247
	v_max_f32_e32 v201, 0, v248
	v_max_f32_e32 v216, 0, v249
	v_mfma_f32_16x16x32_bf16 v[210:213], v[34:37], v[238:241], 0
	v_mul_f32_e32 v62, v6, v9
	v_mul_f32_e32 v61, v6, v200
	v_mul_f32_e32 v64, v6, v201
	v_mul_f32_e32 v63, v6, v216
	v_mfma_f32_16x16x32_bf16 v[206:209], v[30:33], v[242:245], v[206:209]
	v_max_f32_e32 v9, 0, v250
	v_max_f32_e32 v200, 0, v251
	v_max_f32_e32 v201, 0, v252
	v_max_f32_e32 v216, 0, v253
	v_mfma_f32_16x16x32_bf16 v[210:213], v[38:41], v[242:245], v[210:213]
	v_mul_f32_e32 v66, v6, v9
	v_mul_f32_e32 v65, v6, v200
	v_mul_f32_e32 v68, v6, v201
	v_mul_f32_e32 v67, v6, v216
	ds_read_b128 v[238:241], v176
	ds_read_b128 v[242:245], v159
	ds_read_b32 v6, v137 offset:512
	s_waitcnt lgkmcnt(4)
	v_mfma_f32_16x16x32_bf16 v[246:249], v[26:29], v[230:233], 0
	v_max_f32_e32 v9, 0, v206
	v_max_f32_e32 v200, 0, v207
	v_max_f32_e32 v201, 0, v208
	v_max_f32_e32 v216, 0, v209
	v_mfma_f32_16x16x32_bf16 v[250:253], v[34:37], v[230:233], 0
	v_fmac_f32_e32 v62, v7, v9
	v_fmac_f32_e32 v61, v7, v200
	v_fmac_f32_e32 v64, v7, v201
	v_fmac_f32_e32 v63, v7, v216
	v_mfma_f32_16x16x32_bf16 v[246:249], v[30:33], v[234:237], v[246:249]
	v_max_f32_e32 v9, 0, v210
	v_max_f32_e32 v200, 0, v211
	v_max_f32_e32 v201, 0, v212
	v_max_f32_e32 v216, 0, v213
	v_mfma_f32_16x16x32_bf16 v[250:253], v[38:41], v[234:237], v[250:253]
	v_fmac_f32_e32 v66, v7, v9
	v_fmac_f32_e32 v65, v7, v200
	v_fmac_f32_e32 v68, v7, v201
	v_fmac_f32_e32 v67, v7, v216
	ds_read_b128 v[230:233], v158
	ds_read_b128 v[234:237], v157
	ds_read_b32 v7, v137 offset:576
	s_waitcnt lgkmcnt(4)
	v_mfma_f32_16x16x32_bf16 v[206:209], v[26:29], v[238:241], 0
	v_max_f32_e32 v9, 0, v246
	v_max_f32_e32 v200, 0, v247
	v_max_f32_e32 v201, 0, v248
	v_max_f32_e32 v216, 0, v249
	v_mfma_f32_16x16x32_bf16 v[210:213], v[34:37], v[238:241], 0
	v_fmac_f32_e32 v62, v217, v9
	v_fmac_f32_e32 v61, v217, v200
	v_fmac_f32_e32 v64, v217, v201
	v_fmac_f32_e32 v63, v217, v216
	v_mfma_f32_16x16x32_bf16 v[206:209], v[30:33], v[242:245], v[206:209]
	v_max_f32_e32 v9, 0, v250
	v_max_f32_e32 v200, 0, v251
	v_max_f32_e32 v201, 0, v252
	v_max_f32_e32 v216, 0, v253
	v_mfma_f32_16x16x32_bf16 v[210:213], v[38:41], v[242:245], v[210:213]
	v_fmac_f32_e32 v66, v217, v9
	v_fmac_f32_e32 v65, v217, v200
	v_fmac_f32_e32 v68, v217, v201
	v_fmac_f32_e32 v67, v217, v216
	ds_read_b128 v[238:241], v156
	ds_read_b128 v[242:245], v155
	ds_read_b32 v217, v137 offset:640
	s_waitcnt lgkmcnt(4)
; #define LAS __attribute__((address_space(3)))
; #define SEL_HADD(idx_) __hip_atomic_fetch_add(&hist[(idx_)], 1u, __ATOMIC_RELAXED, __HIP_MEMORY_SCOPE_WORKGROUP)
; __device__ __forceinline__ unsigned fkey(float f) { const unsigned u = __float_as_uint(f); return (u & 0x80000000u) ? ~u : (u | 0x80000000u); }
; __device__ __forceinline__ void sel_unit(LAS char* lds, int b, int u, const bf16_t* QI, const bf16_t* KIDX, const float* WIDX, unsigned long long* MASK) {
;     ...
;             for (int kh = 0; kh < 2; ++kh) {
;             bf16x8 kf[2][2];
; #pragma unroll
;             for (int kb = 0; kb < 2; ++kb)
; #pragma unroll
;                 for (int ks = 0; ks < 2; ++ks) kf[kb][ks] = *(const bf16x8*)(KIDX + (rowbase + 64 * t + 32 * kh + 16 * kb + q16) * 64 + 32 * ks + 8 * kg);
; #pragma unroll
;             for (int kb = 0; kb < 2; ++kb) {
;                 f32x4 s = (f32x4){0.f, 0.f, 0.f, 0.f};
; #pragma unroll
;                 for (int hh = 0; hh < 8; ++hh) {
;                     f32x4 a = (f32x4){0.f, 0.f, 0.f, 0.f};
; #pragma unroll
;                     for (int ks = 0; ks < 2; ++ks) {
;                         const bf16x8 qv = *(const LAS bf16x8*)(lds + L_QI + q16 * 1024 + (((hh * 8 + 4 * ks + kg) ^ q16) << 4));
;                         a = __builtin_amdgcn_mfma_f32_16x16x32_bf16(kf[kb][ks], qv, a, 0, 0, 0);
;                     }
;                     const float wh = wl[hh * 16];
; #pragma unroll
;                     for (int i = 0; i < 4; ++i) s[i] += wh * fmaxf(a[i], 0.f);
;                 }
;                 u32x4 kk; kk.x = fkey(s[0]); kk.y = fkey(s[1]); kk.z = fkey(s[2]); kk.w = fkey(s[3]);
;                 sc[j][2 * kh + kb] = kk;
; #pragma unroll
;                 for (int i = 0; i < 4; ++i) SEL_HADD((kk[i] >> 24) * 16 + q16);
	v_mfma_f32_16x16x32_bf16 v[246:249], v[26:29], v[230:233], 0
	v_max_f32_e32 v9, 0, v206
	v_max_f32_e32 v200, 0, v207
	v_max_f32_e32 v201, 0, v208
	v_max_f32_e32 v216, 0, v209
	v_mfma_f32_16x16x32_bf16 v[250:253], v[34:37], v[230:233], 0
	v_fmac_f32_e32 v62, v6, v9
	v_fmac_f32_e32 v61, v6, v200
	v_fmac_f32_e32 v64, v6, v201
	v_fmac_f32_e32 v63, v6, v216
	v_mfma_f32_16x16x32_bf16 v[246:249], v[30:33], v[234:237], v[246:249]
	v_max_f32_e32 v9, 0, v210
	v_max_f32_e32 v200, 0, v211
	v_max_f32_e32 v201, 0, v212
	v_max_f32_e32 v216, 0, v213
	v_mfma_f32_16x16x32_bf16 v[250:253], v[38:41], v[234:237], v[250:253]
	v_fmac_f32_e32 v66, v6, v9
	v_fmac_f32_e32 v65, v6, v200
	v_fmac_f32_e32 v68, v6, v201
	v_fmac_f32_e32 v67, v6, v216
	ds_read_b128 v[230:233], v154
	ds_read_b128 v[234:237], v153
	ds_read_b32 v6, v137 offset:704
	s_waitcnt lgkmcnt(4)
	v_mfma_f32_16x16x32_bf16 v[206:209], v[26:29], v[238:241], 0
	v_max_f32_e32 v9, 0, v246
	v_max_f32_e32 v200, 0, v247
	v_max_f32_e32 v201, 0, v248
	v_max_f32_e32 v216, 0, v249
	v_mfma_f32_16x16x32_bf16 v[210:213], v[34:37], v[238:241], 0
	v_fmac_f32_e32 v62, v7, v9
	v_fmac_f32_e32 v61, v7, v200
	v_fmac_f32_e32 v64, v7, v201
	v_fmac_f32_e32 v63, v7, v216
	v_mfma_f32_16x16x32_bf16 v[206:209], v[30:33], v[242:245], v[206:209]
	v_max_f32_e32 v9, 0, v250
	v_max_f32_e32 v200, 0, v251
	v_max_f32_e32 v201, 0, v252
	v_max_f32_e32 v216, 0, v253
	v_mfma_f32_16x16x32_bf16 v[210:213], v[38:41], v[242:245], v[210:213]
	v_fmac_f32_e32 v66, v7, v9
	v_fmac_f32_e32 v65, v7, v200
	v_fmac_f32_e32 v68, v7, v201
	v_fmac_f32_e32 v67, v7, v216
	ds_read_b128 v[238:241], v152
	ds_read_b128 v[242:245], v151
	ds_read_b32 v7, v137 offset:768
	s_waitcnt lgkmcnt(4)
	v_mfma_f32_16x16x32_bf16 v[246:249], v[26:29], v[230:233], 0
	v_max_f32_e32 v9, 0, v206
	v_max_f32_e32 v200, 0, v207
	v_max_f32_e32 v201, 0, v208
	v_max_f32_e32 v216, 0, v209
	v_mfma_f32_16x16x32_bf16 v[250:253], v[34:37], v[230:233], 0
	v_fmac_f32_e32 v62, v217, v9
	v_fmac_f32_e32 v61, v217, v200
	v_fmac_f32_e32 v64, v217, v201
	v_fmac_f32_e32 v63, v217, v216
	v_mfma_f32_16x16x32_bf16 v[246:249], v[30:33], v[234:237], v[246:249]
	v_max_f32_e32 v9, 0, v210
	v_max_f32_e32 v200, 0, v211
	v_max_f32_e32 v201, 0, v212
	v_max_f32_e32 v216, 0, v213
	v_mfma_f32_16x16x32_bf16 v[250:253], v[38:41], v[234:237], v[250:253]
	v_fmac_f32_e32 v66, v217, v9
	v_fmac_f32_e32 v65, v217, v200
	v_fmac_f32_e32 v68, v217, v201
	v_fmac_f32_e32 v67, v217, v216
	ds_read_b128 v[230:233], v182
	ds_read_b128 v[234:237], v183
	ds_read_b32 v217, v137 offset:320
	s_waitcnt lgkmcnt(4)
	v_mfma_f32_16x16x32_bf16 v[206:209], v[26:29], v[238:241], 0
	v_max_f32_e32 v9, 0, v246
	v_max_f32_e32 v200, 0, v247
	v_max_f32_e32 v201, 0, v248
	v_max_f32_e32 v216, 0, v249
	v_mfma_f32_16x16x32_bf16 v[210:213], v[34:37], v[238:241], 0
	v_fmac_f32_e32 v62, v6, v9
	v_fmac_f32_e32 v61, v6, v200
	v_fmac_f32_e32 v64, v6, v201
	v_fmac_f32_e32 v63, v6, v216
	v_mfma_f32_16x16x32_bf16 v[206:209], v[30:33], v[242:245], v[206:209]
	v_max_f32_e32 v9, 0, v250
	v_max_f32_e32 v200, 0, v251
	v_max_f32_e32 v201, 0, v252
	v_max_f32_e32 v216, 0, v253
	v_mfma_f32_16x16x32_bf16 v[210:213], v[38:41], v[242:245], v[210:213]
	v_fmac_f32_e32 v66, v6, v9
	v_fmac_f32_e32 v65, v6, v200
	v_fmac_f32_e32 v68, v6, v201
	v_fmac_f32_e32 v67, v6, v216
	ds_read_b128 v[238:241], v184
	ds_read_b128 v[242:245], v185
	ds_read_b32 v6, v137 offset:384
	s_waitcnt vmcnt(0)
	s_cmp_lt_i32 s4, 2
	s_cbranch_scc1 .Lp0_nopf_0
	v_add_co_u32_e32 v22, vcc, 0xf000, v22
	s_nop 1
	v_addc_co_u32_e32 v23, vcc, 0, v23, vcc
	global_load_dwordx4 v[26:29], v[22:23], off
	global_load_dwordx4 v[30:33], v[22:23], off offset:64
	global_load_dwordx4 v[34:37], v[22:23], off offset:2048
	global_load_dwordx4 v[38:41], v[22:23], off offset:2112
.Lp0_nopf_0:
	s_waitcnt lgkmcnt(4)
	v_mfma_f32_16x16x32_bf16 v[246:249], v[42:45], v[230:233], 0
	v_max_f32_e32 v9, 0, v206
	v_max_f32_e32 v200, 0, v207
	v_max_f32_e32 v201, 0, v208
	v_max_f32_e32 v216, 0, v209
	v_fmac_f32_e32 v62, v7, v9
	v_fmac_f32_e32 v61, v7, v200
	v_fmac_f32_e32 v64, v7, v201
	v_fmac_f32_e32 v63, v7, v216
	v_max_f32_e32 v9, 0, v210
	v_max_f32_e32 v200, 0, v211
	v_max_f32_e32 v201, 0, v212
	v_max_f32_e32 v216, 0, v213
	v_fmac_f32_e32 v66, v7, v9
	v_fmac_f32_e32 v65, v7, v200
	v_mfma_f32_16x16x32_bf16 v[250:253], v[50:53], v[230:233], 0
	v_fmac_f32_e32 v68, v7, v201
	v_fmac_f32_e32 v67, v7, v216
	v_ashrrev_i32_e32 v9, 31, v62
	v_bitop3_b32 v62, v9, v62, v8 bitop3:0x36
	v_ashrrev_i32_e32 v200, 31, v61
	v_bitop3_b32 v61, v200, v61, v8 bitop3:0x36
	v_ashrrev_i32_e32 v201, 31, v64
	v_bitop3_b32 v64, v201, v64, v8 bitop3:0x36
	v_ashrrev_i32_e32 v216, 31, v63
	v_bitop3_b32 v63, v216, v63, v8 bitop3:0x36
	v_ashrrev_i32_e32 v9, 31, v66
	v_bitop3_b32 v66, v9, v66, v8 bitop3:0x36
	v_ashrrev_i32_e32 v200, 31, v65
	v_bitop3_b32 v65, v200, v65, v8 bitop3:0x36
	v_mfma_f32_16x16x32_bf16 v[246:249], v[46:49], v[234:237], v[246:249]
	v_ashrrev_i32_e32 v201, 31, v68
	v_bitop3_b32 v68, v201, v68, v8 bitop3:0x36
	v_ashrrev_i32_e32 v216, 31, v67
	v_bitop3_b32 v67, v216, v67, v8 bitop3:0x36
	v_lshrrev_b32_e32 v9, 24, v62
	v_lshl_add_u32 v9, v9, 6, v0
	ds_add_u32 v9, v205 offset:16384
	v_lshrrev_b32_e32 v200, 24, v61
	v_lshl_add_u32 v200, v200, 6, v0
	ds_add_u32 v200, v205 offset:16384
	v_lshrrev_b32_e32 v201, 24, v64
	v_lshl_add_u32 v201, v201, 6, v0
	ds_add_u32 v201, v205 offset:16384
	v_lshrrev_b32_e32 v216, 24, v63
	v_mfma_f32_16x16x32_bf16 v[250:253], v[2:5], v[234:237], v[250:253]
	v_lshl_add_u32 v216, v216, 6, v0
	ds_add_u32 v216, v205 offset:16384
	v_lshrrev_b32_e32 v9, 24, v66
	v_lshl_add_u32 v9, v9, 6, v0
	ds_add_u32 v9, v205 offset:16384
	v_lshrrev_b32_e32 v200, 24, v65
	v_lshl_add_u32 v200, v200, 6, v0
	ds_add_u32 v200, v205 offset:16384
	v_lshrrev_b32_e32 v201, 24, v68
	v_lshl_add_u32 v201, v201, 6, v0
	ds_add_u32 v201, v205 offset:16384
	v_lshrrev_b32_e32 v216, 24, v67
	v_lshl_add_u32 v216, v216, 6, v0
	ds_add_u32 v216, v205 offset:16384
	ds_read_b128 v[230:233], v179
	ds_read_b128 v[234:237], v180
	ds_read_b32 v7, v137 offset:448
	s_waitcnt lgkmcnt(12)
; #define LAS __attribute__((address_space(3)))
; __device__ __forceinline__ void sel_unit(LAS char* lds, int b, int u, const bf16_t* QI, const bf16_t* KIDX, const float* WIDX, unsigned long long* MASK) {
;     ...
;             for (int kh = 0; kh < 2; ++kh) {
;             bf16x8 kf[2][2];
; #pragma unroll
;             for (int kb = 0; kb < 2; ++kb)
; #pragma unroll
;                 for (int ks = 0; ks < 2; ++ks) kf[kb][ks] = *(const bf16x8*)(KIDX + (rowbase + 64 * t + 32 * kh + 16 * kb + q16) * 64 + 32 * ks + 8 * kg);
; #pragma unroll
;             for (int kb = 0; kb < 2; ++kb) {
;                 f32x4 s = (f32x4){0.f, 0.f, 0.f, 0.f};
; #pragma unroll
;                 for (int hh = 0; hh < 8; ++hh) {
;                     f32x4 a = (f32x4){0.f, 0.f, 0.f, 0.f};
; #pragma unroll
;                     for (int ks = 0; ks < 2; ++ks) {
;                         const bf16x8 qv = *(const LAS bf16x8*)(lds + L_QI + q16 * 1024 + (((hh * 8 + 4 * ks + kg) ^ q16) << 4));
;                         a = __builtin_amdgcn_mfma_f32_16x16x32_bf16(kf[kb][ks], qv, a, 0, 0, 0);
;                     }
;                     const float wh = wl[hh * 16];
; #pragma unroll
;                     for (int i = 0; i < 4; ++i) s[i] += wh * fmaxf(a[i], 0.f);
	v_mfma_f32_16x16x32_bf16 v[206:209], v[42:45], v[238:241], 0
	v_max_f32_e32 v9, 0, v246
	v_max_f32_e32 v200, 0, v247
	v_max_f32_e32 v201, 0, v248
	v_max_f32_e32 v216, 0, v249
	v_mfma_f32_16x16x32_bf16 v[210:213], v[50:53], v[238:241], 0
	v_mul_f32_e32 v70, v217, v9
	v_mul_f32_e32 v69, v217, v200
	v_mul_f32_e32 v72, v217, v201
	v_mul_f32_e32 v71, v217, v216
	v_mfma_f32_16x16x32_bf16 v[206:209], v[46:49], v[242:245], v[206:209]
	v_max_f32_e32 v9, 0, v250
	v_max_f32_e32 v200, 0, v251
	v_max_f32_e32 v201, 0, v252
	v_max_f32_e32 v216, 0, v253
	v_mfma_f32_16x16x32_bf16 v[210:213], v[2:5], v[242:245], v[210:213]
	v_mul_f32_e32 v74, v217, v9
	v_mul_f32_e32 v73, v217, v200
	v_mul_f32_e32 v76, v217, v201
	v_mul_f32_e32 v75, v217, v216
	ds_read_b128 v[238:241], v176
	ds_read_b128 v[242:245], v159
	ds_read_b32 v217, v137 offset:512
	s_waitcnt lgkmcnt(4)
	v_mfma_f32_16x16x32_bf16 v[246:249], v[42:45], v[230:233], 0
	v_max_f32_e32 v9, 0, v206
	v_max_f32_e32 v200, 0, v207
	v_max_f32_e32 v201, 0, v208
	v_max_f32_e32 v216, 0, v209
	v_mfma_f32_16x16x32_bf16 v[250:253], v[50:53], v[230:233], 0
	v_fmac_f32_e32 v70, v6, v9
	v_fmac_f32_e32 v69, v6, v200
	v_fmac_f32_e32 v72, v6, v201
	v_fmac_f32_e32 v71, v6, v216
	v_mfma_f32_16x16x32_bf16 v[246:249], v[46:49], v[234:237], v[246:249]
	v_max_f32_e32 v9, 0, v210
	v_max_f32_e32 v200, 0, v211
	v_max_f32_e32 v201, 0, v212
	v_max_f32_e32 v216, 0, v213
	v_mfma_f32_16x16x32_bf16 v[250:253], v[2:5], v[234:237], v[250:253]
	v_fmac_f32_e32 v74, v6, v9
	v_fmac_f32_e32 v73, v6, v200
	v_fmac_f32_e32 v76, v6, v201
	v_fmac_f32_e32 v75, v6, v216
	ds_read_b128 v[230:233], v158
	ds_read_b128 v[234:237], v157
	ds_read_b32 v6, v137 offset:576
	s_waitcnt lgkmcnt(4)
	v_mfma_f32_16x16x32_bf16 v[206:209], v[42:45], v[238:241], 0
	v_max_f32_e32 v9, 0, v246
	v_max_f32_e32 v200, 0, v247
	v_max_f32_e32 v201, 0, v248
	v_max_f32_e32 v216, 0, v249
	v_mfma_f32_16x16x32_bf16 v[210:213], v[50:53], v[238:241], 0
	v_fmac_f32_e32 v70, v7, v9
	v_fmac_f32_e32 v69, v7, v200
	v_fmac_f32_e32 v72, v7, v201
	v_fmac_f32_e32 v71, v7, v216
	v_mfma_f32_16x16x32_bf16 v[206:209], v[46:49], v[242:245], v[206:209]
	v_max_f32_e32 v9, 0, v250
	v_max_f32_e32 v200, 0, v251
	v_max_f32_e32 v201, 0, v252
	v_max_f32_e32 v216, 0, v253
	v_mfma_f32_16x16x32_bf16 v[210:213], v[2:5], v[242:245], v[210:213]
	v_fmac_f32_e32 v74, v7, v9
	v_fmac_f32_e32 v73, v7, v200
	v_fmac_f32_e32 v76, v7, v201
	v_fmac_f32_e32 v75, v7, v216
	ds_read_b128 v[238:241], v156
	ds_read_b128 v[242:245], v155
	ds_read_b32 v7, v137 offset:640
	s_waitcnt lgkmcnt(4)
	v_mfma_f32_16x16x32_bf16 v[246:249], v[42:45], v[230:233], 0
	v_max_f32_e32 v9, 0, v206
	v_max_f32_e32 v200, 0, v207
	v_max_f32_e32 v201, 0, v208
	v_max_f32_e32 v216, 0, v209
	v_mfma_f32_16x16x32_bf16 v[250:253], v[50:53], v[230:233], 0
	v_fmac_f32_e32 v70, v217, v9
	v_fmac_f32_e32 v69, v217, v200
	v_fmac_f32_e32 v72, v217, v201
	v_fmac_f32_e32 v71, v217, v216
	v_mfma_f32_16x16x32_bf16 v[246:249], v[46:49], v[234:237], v[246:249]
	v_max_f32_e32 v9, 0, v210
	v_max_f32_e32 v200, 0, v211
	v_max_f32_e32 v201, 0, v212
	v_max_f32_e32 v216, 0, v213
	v_mfma_f32_16x16x32_bf16 v[250:253], v[2:5], v[234:237], v[250:253]
	v_fmac_f32_e32 v74, v217, v9
	v_fmac_f32_e32 v73, v217, v200
	v_fmac_f32_e32 v76, v217, v201
	v_fmac_f32_e32 v75, v217, v216
	ds_read_b128 v[230:233], v154
	ds_read_b128 v[234:237], v153
	ds_read_b32 v217, v137 offset:704
	s_waitcnt lgkmcnt(4)
	v_mfma_f32_16x16x32_bf16 v[206:209], v[42:45], v[238:241], 0
	v_max_f32_e32 v9, 0, v246
	v_max_f32_e32 v200, 0, v247
	v_max_f32_e32 v201, 0, v248
	v_max_f32_e32 v216, 0, v249
	v_mfma_f32_16x16x32_bf16 v[210:213], v[50:53], v[238:241], 0
	v_fmac_f32_e32 v70, v6, v9
	v_fmac_f32_e32 v69, v6, v200
	v_fmac_f32_e32 v72, v6, v201
	v_fmac_f32_e32 v71, v6, v216
	v_mfma_f32_16x16x32_bf16 v[206:209], v[46:49], v[242:245], v[206:209]
	v_max_f32_e32 v9, 0, v250
	v_max_f32_e32 v200, 0, v251
	v_max_f32_e32 v201, 0, v252
	v_max_f32_e32 v216, 0, v253
	v_mfma_f32_16x16x32_bf16 v[210:213], v[2:5], v[242:245], v[210:213]
	v_fmac_f32_e32 v74, v6, v9
	v_fmac_f32_e32 v73, v6, v200
	v_fmac_f32_e32 v76, v6, v201
	v_fmac_f32_e32 v75, v6, v216
	ds_read_b128 v[238:241], v152
	ds_read_b128 v[242:245], v151
	ds_read_b32 v6, v137 offset:768
	s_waitcnt lgkmcnt(4)
	v_mfma_f32_16x16x32_bf16 v[246:249], v[42:45], v[230:233], 0
	v_max_f32_e32 v9, 0, v206
	v_max_f32_e32 v200, 0, v207
	v_max_f32_e32 v201, 0, v208
	v_max_f32_e32 v216, 0, v209
	v_mfma_f32_16x16x32_bf16 v[250:253], v[50:53], v[230:233], 0
	v_fmac_f32_e32 v70, v7, v9
	v_fmac_f32_e32 v69, v7, v200
	v_fmac_f32_e32 v72, v7, v201
	v_fmac_f32_e32 v71, v7, v216
	v_mfma_f32_16x16x32_bf16 v[246:249], v[46:49], v[234:237], v[246:249]
	v_max_f32_e32 v9, 0, v210
	v_max_f32_e32 v200, 0, v211
	v_max_f32_e32 v201, 0, v212
	v_max_f32_e32 v216, 0, v213
	v_mfma_f32_16x16x32_bf16 v[250:253], v[2:5], v[234:237], v[250:253]
	v_fmac_f32_e32 v74, v7, v9
	v_fmac_f32_e32 v73, v7, v200
	v_fmac_f32_e32 v76, v7, v201
	v_fmac_f32_e32 v75, v7, v216
	s_waitcnt lgkmcnt(1)
	v_mfma_f32_16x16x32_bf16 v[206:209], v[42:45], v[238:241], 0
	v_max_f32_e32 v9, 0, v246
	v_max_f32_e32 v200, 0, v247
	v_max_f32_e32 v201, 0, v248
	v_max_f32_e32 v216, 0, v249
	v_mfma_f32_16x16x32_bf16 v[210:213], v[50:53], v[238:241], 0
	v_fmac_f32_e32 v70, v217, v9
	v_fmac_f32_e32 v69, v217, v200
	v_fmac_f32_e32 v72, v217, v201
	v_fmac_f32_e32 v71, v217, v216
	v_mfma_f32_16x16x32_bf16 v[206:209], v[46:49], v[242:245], v[206:209]
	v_max_f32_e32 v9, 0, v250
	v_max_f32_e32 v200, 0, v251
	v_max_f32_e32 v201, 0, v252
	v_max_f32_e32 v216, 0, v253
	v_mfma_f32_16x16x32_bf16 v[210:213], v[2:5], v[242:245], v[210:213]
	v_fmac_f32_e32 v74, v217, v9
	v_fmac_f32_e32 v73, v217, v200
	v_fmac_f32_e32 v76, v217, v201
	v_fmac_f32_e32 v75, v217, v216
	s_waitcnt lgkmcnt(0)
; #define LAS __attribute__((address_space(3)))
; __device__ __forceinline__ unsigned fkey(float f) { const unsigned u = __float_as_uint(f); return (u & 0x80000000u) ? ~u : (u | 0x80000000u); }
; #define SEL_HADD(idx_) __hip_atomic_fetch_add(&hist[(idx_)], 1u, __ATOMIC_RELAXED, __HIP_MEMORY_SCOPE_WORKGROUP)
; __device__ __forceinline__ void sel_unit(LAS char* lds, int b, int u, const bf16_t* QI, const bf16_t* KIDX, const float* WIDX, unsigned long long* MASK) {
;     ...
;     const LAS float* wl = (const LAS float*)(lds + L_W) + q16;
;     __syncthreads();
;     const int nj = (c - wid + 8) >> 3;
;     u32x4 sc[8][4];
; #pragma unroll
;     for (int j = 0; j < 8; ++j) {
;         if (j < nj) {
;             int t = wid + 8 * j; asm volatile("" : "+s"(t));
; #pragma unroll
;             for (int kh = 0; kh < 2; ++kh) {
;             bf16x8 kf[2][2];
; #pragma unroll
;             for (int kb = 0; kb < 2; ++kb)
; #pragma unroll
;                 for (int ks = 0; ks < 2; ++ks) kf[kb][ks] = *(const bf16x8*)(KIDX + (rowbase + 64 * t + 32 * kh + 16 * kb + q16) * 64 + 32 * ks + 8 * kg);
; #pragma unroll
;             for (int kb = 0; kb < 2; ++kb) {
;                 f32x4 s = (f32x4){0.f, 0.f, 0.f, 0.f};
; #pragma unroll
;                 for (int hh = 0; hh < 8; ++hh) {
;                     f32x4 a = (f32x4){0.f, 0.f, 0.f, 0.f};
; #pragma unroll
;                     for (int ks = 0; ks < 2; ++ks) {
;                         const bf16x8 qv = *(const LAS bf16x8*)(lds + L_QI + q16 * 1024 + (((hh * 8 + 4 * ks + kg) ^ q16) << 4));
;                         a = __builtin_amdgcn_mfma_f32_16x16x32_bf16(kf[kb][ks], qv, a, 0, 0, 0);
;                     }
;                     const float wh = wl[hh * 16];
; #pragma unroll
;                     for (int i = 0; i < 4; ++i) s[i] += wh * fmaxf(a[i], 0.f);
;                 }
;                 u32x4 kk; kk.x = fkey(s[0]); kk.y = fkey(s[1]); kk.z = fkey(s[2]); kk.w = fkey(s[3]);
;                 sc[j][2 * kh + kb] = kk;
; #pragma unroll
;                 for (int i = 0; i < 4; ++i) SEL_HADD((kk[i] >> 24) * 16 + q16);
	v_max_f32_e32 v9, 0, v206
	v_max_f32_e32 v200, 0, v207
	v_max_f32_e32 v201, 0, v208
	v_max_f32_e32 v216, 0, v209
	v_fmac_f32_e32 v70, v6, v9
	v_fmac_f32_e32 v69, v6, v200
	v_fmac_f32_e32 v72, v6, v201
	v_fmac_f32_e32 v71, v6, v216
	v_max_f32_e32 v9, 0, v210
	v_max_f32_e32 v200, 0, v211
	v_max_f32_e32 v201, 0, v212
	v_max_f32_e32 v216, 0, v213
	v_fmac_f32_e32 v74, v6, v9
	v_fmac_f32_e32 v73, v6, v200
	v_fmac_f32_e32 v76, v6, v201
	v_fmac_f32_e32 v75, v6, v216
	v_ashrrev_i32_e32 v9, 31, v70
	v_bitop3_b32 v70, v9, v70, v8 bitop3:0x36
	v_ashrrev_i32_e32 v200, 31, v69
	v_bitop3_b32 v69, v200, v69, v8 bitop3:0x36
	v_ashrrev_i32_e32 v201, 31, v72
	v_bitop3_b32 v72, v201, v72, v8 bitop3:0x36
	v_ashrrev_i32_e32 v216, 31, v71
	v_bitop3_b32 v71, v216, v71, v8 bitop3:0x36
	v_ashrrev_i32_e32 v9, 31, v74
	v_bitop3_b32 v74, v9, v74, v8 bitop3:0x36
	v_ashrrev_i32_e32 v200, 31, v73
	v_bitop3_b32 v73, v200, v73, v8 bitop3:0x36
	v_ashrrev_i32_e32 v201, 31, v76
	v_bitop3_b32 v76, v201, v76, v8 bitop3:0x36
	v_ashrrev_i32_e32 v216, 31, v75
	v_bitop3_b32 v75, v216, v75, v8 bitop3:0x36
	v_lshrrev_b32_e32 v9, 24, v70
	v_lshl_add_u32 v9, v9, 6, v0
	ds_add_u32 v9, v205 offset:16384
	v_lshrrev_b32_e32 v200, 24, v69
	v_lshl_add_u32 v200, v200, 6, v0
	ds_add_u32 v200, v205 offset:16384
	v_lshrrev_b32_e32 v201, 24, v72
	v_lshl_add_u32 v201, v201, 6, v0
	ds_add_u32 v201, v205 offset:16384
	v_lshrrev_b32_e32 v216, 24, v71
	v_lshl_add_u32 v216, v216, 6, v0
	ds_add_u32 v216, v205 offset:16384
	v_lshrrev_b32_e32 v9, 24, v74
	v_lshl_add_u32 v9, v9, 6, v0
	ds_add_u32 v9, v205 offset:16384
	v_lshrrev_b32_e32 v200, 24, v73
	v_lshl_add_u32 v200, v200, 6, v0
	ds_add_u32 v200, v205 offset:16384
	v_lshrrev_b32_e32 v201, 24, v76
	v_lshl_add_u32 v201, v201, 6, v0
	ds_add_u32 v201, v205 offset:16384
	v_lshrrev_b32_e32 v216, 24, v75
	v_lshl_add_u32 v216, v216, 6, v0
	ds_add_u32 v216, v205 offset:16384
.LBB0_658:
	s_cmp_gt_i32 s4, 1
	s_cselect_b64 s[18:19], -1, 0
	s_cmp_lt_i32 s4, 2
	s_cbranch_scc1 .LBB0_660
	ds_read_b128 v[230:233], v182
	ds_read_b128 v[234:237], v183
	ds_read_b32 v6, v137 offset:320
	ds_read_b128 v[238:241], v184
	ds_read_b128 v[242:245], v185
	ds_read_b32 v7, v137 offset:384
	s_waitcnt vmcnt(0)
	v_add_co_u32_e32 v22, vcc, s96, v22
	s_nop 1
	v_addc_co_u32_e32 v23, vcc, 0, v23, vcc
	global_load_dwordx4 v[42:45], v[22:23], off
	global_load_dwordx4 v[46:49], v[22:23], off offset:64
	global_load_dwordx4 v[50:53], v[22:23], off offset:2048
	global_load_dwordx4 v[2:5], v[22:23], off offset:2112
	s_waitcnt lgkmcnt(4)
	v_mfma_f32_16x16x32_bf16 v[246:249], v[26:29], v[230:233], 0
	v_mfma_f32_16x16x32_bf16 v[250:253], v[34:37], v[230:233], 0
	v_mfma_f32_16x16x32_bf16 v[246:249], v[30:33], v[234:237], v[246:249]
	v_mfma_f32_16x16x32_bf16 v[250:253], v[38:41], v[234:237], v[250:253]
	ds_read_b128 v[230:233], v179
	ds_read_b128 v[234:237], v180
	ds_read_b32 v217, v137 offset:448
	s_waitcnt lgkmcnt(4)
	s_nop 1
	v_mfma_f32_16x16x32_bf16 v[206:209], v[26:29], v[238:241], 0
	v_max_f32_e32 v9, 0, v246
	v_max_f32_e32 v200, 0, v247
	v_max_f32_e32 v201, 0, v248
	v_max_f32_e32 v216, 0, v249
	v_mfma_f32_16x16x32_bf16 v[210:213], v[34:37], v[238:241], 0
	v_mul_f32_e32 v78, v6, v9
	v_mul_f32_e32 v77, v6, v200
	v_mul_f32_e32 v80, v6, v201
	v_mul_f32_e32 v79, v6, v216
	v_mfma_f32_16x16x32_bf16 v[206:209], v[30:33], v[242:245], v[206:209]
	v_max_f32_e32 v9, 0, v250
	v_max_f32_e32 v200, 0, v251
	v_max_f32_e32 v201, 0, v252
	v_max_f32_e32 v216, 0, v253
	v_mfma_f32_16x16x32_bf16 v[210:213], v[38:41], v[242:245], v[210:213]
	v_mul_f32_e32 v82, v6, v9
	v_mul_f32_e32 v81, v6, v200
	v_mul_f32_e32 v84, v6, v201
	v_mul_f32_e32 v83, v6, v216
	ds_read_b128 v[238:241], v176
	ds_read_b128 v[242:245], v159
	ds_read_b32 v6, v137 offset:512
	s_waitcnt lgkmcnt(4)
	v_mfma_f32_16x16x32_bf16 v[246:249], v[26:29], v[230:233], 0
	v_max_f32_e32 v9, 0, v206
	v_max_f32_e32 v200, 0, v207
	v_max_f32_e32 v201, 0, v208
	v_max_f32_e32 v216, 0, v209
	v_mfma_f32_16x16x32_bf16 v[250:253], v[34:37], v[230:233], 0
	v_fmac_f32_e32 v78, v7, v9
	v_fmac_f32_e32 v77, v7, v200
	v_fmac_f32_e32 v80, v7, v201
	v_fmac_f32_e32 v79, v7, v216
	v_mfma_f32_16x16x32_bf16 v[246:249], v[30:33], v[234:237], v[246:249]
	v_max_f32_e32 v9, 0, v210
	v_max_f32_e32 v200, 0, v211
	v_max_f32_e32 v201, 0, v212
	v_max_f32_e32 v216, 0, v213
	v_mfma_f32_16x16x32_bf16 v[250:253], v[38:41], v[234:237], v[250:253]
	v_fmac_f32_e32 v82, v7, v9
	v_fmac_f32_e32 v81, v7, v200
	v_fmac_f32_e32 v84, v7, v201
	v_fmac_f32_e32 v83, v7, v216
	ds_read_b128 v[230:233], v158
	ds_read_b128 v[234:237], v157
	ds_read_b32 v7, v137 offset:576
	s_waitcnt lgkmcnt(4)
	v_mfma_f32_16x16x32_bf16 v[206:209], v[26:29], v[238:241], 0
	v_max_f32_e32 v9, 0, v246
	v_max_f32_e32 v200, 0, v247
	v_max_f32_e32 v201, 0, v248
	v_max_f32_e32 v216, 0, v249
	v_mfma_f32_16x16x32_bf16 v[210:213], v[34:37], v[238:241], 0
	v_fmac_f32_e32 v78, v217, v9
	v_fmac_f32_e32 v77, v217, v200
	v_fmac_f32_e32 v80, v217, v201
	v_fmac_f32_e32 v79, v217, v216
	v_mfma_f32_16x16x32_bf16 v[206:209], v[30:33], v[242:245], v[206:209]
	v_max_f32_e32 v9, 0, v250
	v_max_f32_e32 v200, 0, v251
	v_max_f32_e32 v201, 0, v252
	v_max_f32_e32 v216, 0, v253
	v_mfma_f32_16x16x32_bf16 v[210:213], v[38:41], v[242:245], v[210:213]
	v_fmac_f32_e32 v82, v217, v9
	v_fmac_f32_e32 v81, v217, v200
	v_fmac_f32_e32 v84, v217, v201
	v_fmac_f32_e32 v83, v217, v216
	ds_read_b128 v[238:241], v156
	ds_read_b128 v[242:245], v155
	ds_read_b32 v217, v137 offset:640
	s_waitcnt lgkmcnt(4)
; #define LAS __attribute__((address_space(3)))
; #define SEL_HADD(idx_) __hip_atomic_fetch_add(&hist[(idx_)], 1u, __ATOMIC_RELAXED, __HIP_MEMORY_SCOPE_WORKGROUP)
; __device__ __forceinline__ unsigned fkey(float f) { const unsigned u = __float_as_uint(f); return (u & 0x80000000u) ? ~u : (u | 0x80000000u); }
; __device__ __forceinline__ void sel_unit(LAS char* lds, int b, int u, const bf16_t* QI, const bf16_t* KIDX, const float* WIDX, unsigned long long* MASK) {
;     ...
;             for (int kh = 0; kh < 2; ++kh) {
;             bf16x8 kf[2][2];
; #pragma unroll
;             for (int kb = 0; kb < 2; ++kb)
; #pragma unroll
;                 for (int ks = 0; ks < 2; ++ks) kf[kb][ks] = *(const bf16x8*)(KIDX + (rowbase + 64 * t + 32 * kh + 16 * kb + q16) * 64 + 32 * ks + 8 * kg);
; #pragma unroll
;             for (int kb = 0; kb < 2; ++kb) {
;                 f32x4 s = (f32x4){0.f, 0.f, 0.f, 0.f};
; #pragma unroll
;                 for (int hh = 0; hh < 8; ++hh) {
;                     f32x4 a = (f32x4){0.f, 0.f, 0.f, 0.f};
; #pragma unroll
;                     for (int ks = 0; ks < 2; ++ks) {
;                         const bf16x8 qv = *(const LAS bf16x8*)(lds + L_QI + q16 * 1024 + (((hh * 8 + 4 * ks + kg) ^ q16) << 4));
;                         a = __builtin_amdgcn_mfma_f32_16x16x32_bf16(kf[kb][ks], qv, a, 0, 0, 0);
;                     }
;                     const float wh = wl[hh * 16];
; #pragma unroll
;                     for (int i = 0; i < 4; ++i) s[i] += wh * fmaxf(a[i], 0.f);
;                 }
;                 u32x4 kk; kk.x = fkey(s[0]); kk.y = fkey(s[1]); kk.z = fkey(s[2]); kk.w = fkey(s[3]);
;                 sc[j][2 * kh + kb] = kk;
; #pragma unroll
;                 for (int i = 0; i < 4; ++i) SEL_HADD((kk[i] >> 24) * 16 + q16);
	v_mfma_f32_16x16x32_bf16 v[246:249], v[26:29], v[230:233], 0
	v_max_f32_e32 v9, 0, v206
	v_max_f32_e32 v200, 0, v207
	v_max_f32_e32 v201, 0, v208
	v_max_f32_e32 v216, 0, v209
	v_mfma_f32_16x16x32_bf16 v[250:253], v[34:37], v[230:233], 0
	v_fmac_f32_e32 v78, v6, v9
	v_fmac_f32_e32 v77, v6, v200
	v_fmac_f32_e32 v80, v6, v201
	v_fmac_f32_e32 v79, v6, v216
	v_mfma_f32_16x16x32_bf16 v[246:249], v[30:33], v[234:237], v[246:249]
	v_max_f32_e32 v9, 0, v210
	v_max_f32_e32 v200, 0, v211
	v_max_f32_e32 v201, 0, v212
	v_max_f32_e32 v216, 0, v213
	v_mfma_f32_16x16x32_bf16 v[250:253], v[38:41], v[234:237], v[250:253]
	v_fmac_f32_e32 v82, v6, v9
	v_fmac_f32_e32 v81, v6, v200
	v_fmac_f32_e32 v84, v6, v201
	v_fmac_f32_e32 v83, v6, v216
	ds_read_b128 v[230:233], v154
	ds_read_b128 v[234:237], v153
	ds_read_b32 v6, v137 offset:704
	s_waitcnt lgkmcnt(4)
	v_mfma_f32_16x16x32_bf16 v[206:209], v[26:29], v[238:241], 0
	v_max_f32_e32 v9, 0, v246
	v_max_f32_e32 v200, 0, v247
	v_max_f32_e32 v201, 0, v248
	v_max_f32_e32 v216, 0, v249
	v_mfma_f32_16x16x32_bf16 v[210:213], v[34:37], v[238:241], 0
	v_fmac_f32_e32 v78, v7, v9
	v_fmac_f32_e32 v77, v7, v200
	v_fmac_f32_e32 v80, v7, v201
	v_fmac_f32_e32 v79, v7, v216
	v_mfma_f32_16x16x32_bf16 v[206:209], v[30:33], v[242:245], v[206:209]
	v_max_f32_e32 v9, 0, v250
	v_max_f32_e32 v200, 0, v251
	v_max_f32_e32 v201, 0, v252
	v_max_f32_e32 v216, 0, v253
	v_mfma_f32_16x16x32_bf16 v[210:213], v[38:41], v[242:245], v[210:213]
	v_fmac_f32_e32 v82, v7, v9
	v_fmac_f32_e32 v81, v7, v200
	v_fmac_f32_e32 v84, v7, v201
	v_fmac_f32_e32 v83, v7, v216
	ds_read_b128 v[238:241], v152
	ds_read_b128 v[242:245], v151
	ds_read_b32 v7, v137 offset:768
	s_waitcnt lgkmcnt(4)
	v_mfma_f32_16x16x32_bf16 v[246:249], v[26:29], v[230:233], 0
	v_max_f32_e32 v9, 0, v206
	v_max_f32_e32 v200, 0, v207
	v_max_f32_e32 v201, 0, v208
	v_max_f32_e32 v216, 0, v209
	v_mfma_f32_16x16x32_bf16 v[250:253], v[34:37], v[230:233], 0
	v_fmac_f32_e32 v78, v217, v9
	v_fmac_f32_e32 v77, v217, v200
	v_fmac_f32_e32 v80, v217, v201
	v_fmac_f32_e32 v79, v217, v216
	v_mfma_f32_16x16x32_bf16 v[246:249], v[30:33], v[234:237], v[246:249]
	v_max_f32_e32 v9, 0, v210
	v_max_f32_e32 v200, 0, v211
	v_max_f32_e32 v201, 0, v212
	v_max_f32_e32 v216, 0, v213
	v_mfma_f32_16x16x32_bf16 v[250:253], v[38:41], v[234:237], v[250:253]
	v_fmac_f32_e32 v82, v217, v9
	v_fmac_f32_e32 v81, v217, v200
	v_fmac_f32_e32 v84, v217, v201
	v_fmac_f32_e32 v83, v217, v216
	ds_read_b128 v[230:233], v182
	ds_read_b128 v[234:237], v183
	ds_read_b32 v217, v137 offset:320
	s_waitcnt lgkmcnt(4)
	v_mfma_f32_16x16x32_bf16 v[206:209], v[26:29], v[238:241], 0
	v_max_f32_e32 v9, 0, v246
	v_max_f32_e32 v200, 0, v247
	v_max_f32_e32 v201, 0, v248
	v_max_f32_e32 v216, 0, v249
	v_mfma_f32_16x16x32_bf16 v[210:213], v[34:37], v[238:241], 0
	v_fmac_f32_e32 v78, v6, v9
	v_fmac_f32_e32 v77, v6, v200
	v_fmac_f32_e32 v80, v6, v201
	v_fmac_f32_e32 v79, v6, v216
	v_mfma_f32_16x16x32_bf16 v[206:209], v[30:33], v[242:245], v[206:209]
	v_max_f32_e32 v9, 0, v250
	v_max_f32_e32 v200, 0, v251
	v_max_f32_e32 v201, 0, v252
	v_max_f32_e32 v216, 0, v253
	v_mfma_f32_16x16x32_bf16 v[210:213], v[38:41], v[242:245], v[210:213]
	v_fmac_f32_e32 v82, v6, v9
	v_fmac_f32_e32 v81, v6, v200
	v_fmac_f32_e32 v84, v6, v201
	v_fmac_f32_e32 v83, v6, v216
	ds_read_b128 v[238:241], v184
	ds_read_b128 v[242:245], v185
	ds_read_b32 v6, v137 offset:384
	s_waitcnt vmcnt(0)
	s_cmp_lt_i32 s4, 3
	s_cbranch_scc1 .Lp0_nopf_1
	v_add_co_u32_e32 v22, vcc, 0xf000, v22
	s_nop 1
	v_addc_co_u32_e32 v23, vcc, 0, v23, vcc
	global_load_dwordx4 v[26:29], v[22:23], off
	global_load_dwordx4 v[30:33], v[22:23], off offset:64
	global_load_dwordx4 v[34:37], v[22:23], off offset:2048
	global_load_dwordx4 v[38:41], v[22:23], off offset:2112
.Lp0_nopf_1:
	s_waitcnt lgkmcnt(4)
	v_mfma_f32_16x16x32_bf16 v[246:249], v[42:45], v[230:233], 0
	v_max_f32_e32 v9, 0, v206
	v_max_f32_e32 v200, 0, v207
	v_max_f32_e32 v201, 0, v208
	v_max_f32_e32 v216, 0, v209
	v_fmac_f32_e32 v78, v7, v9
	v_fmac_f32_e32 v77, v7, v200
	v_fmac_f32_e32 v80, v7, v201
	v_fmac_f32_e32 v79, v7, v216
	v_max_f32_e32 v9, 0, v210
	v_max_f32_e32 v200, 0, v211
	v_max_f32_e32 v201, 0, v212
	v_max_f32_e32 v216, 0, v213
	v_fmac_f32_e32 v82, v7, v9
	v_fmac_f32_e32 v81, v7, v200
	v_mfma_f32_16x16x32_bf16 v[250:253], v[50:53], v[230:233], 0
	v_fmac_f32_e32 v84, v7, v201
	v_fmac_f32_e32 v83, v7, v216
	v_ashrrev_i32_e32 v9, 31, v78
	v_bitop3_b32 v78, v9, v78, v8 bitop3:0x36
	v_ashrrev_i32_e32 v200, 31, v77
	v_bitop3_b32 v77, v200, v77, v8 bitop3:0x36
	v_ashrrev_i32_e32 v201, 31, v80
	v_bitop3_b32 v80, v201, v80, v8 bitop3:0x36
	v_ashrrev_i32_e32 v216, 31, v79
	v_bitop3_b32 v79, v216, v79, v8 bitop3:0x36
	v_ashrrev_i32_e32 v9, 31, v82
	v_bitop3_b32 v82, v9, v82, v8 bitop3:0x36
	v_ashrrev_i32_e32 v200, 31, v81
	v_bitop3_b32 v81, v200, v81, v8 bitop3:0x36
	v_mfma_f32_16x16x32_bf16 v[246:249], v[46:49], v[234:237], v[246:249]
	v_ashrrev_i32_e32 v201, 31, v84
	v_bitop3_b32 v84, v201, v84, v8 bitop3:0x36
	v_ashrrev_i32_e32 v216, 31, v83
	v_bitop3_b32 v83, v216, v83, v8 bitop3:0x36
	v_lshrrev_b32_e32 v9, 24, v78
	v_lshl_add_u32 v9, v9, 6, v0
	ds_add_u32 v9, v205 offset:16384
	v_lshrrev_b32_e32 v200, 24, v77
	v_lshl_add_u32 v200, v200, 6, v0
	ds_add_u32 v200, v205 offset:16384
	v_lshrrev_b32_e32 v201, 24, v80
	v_lshl_add_u32 v201, v201, 6, v0
	ds_add_u32 v201, v205 offset:16384
	v_lshrrev_b32_e32 v216, 24, v79
	v_mfma_f32_16x16x32_bf16 v[250:253], v[2:5], v[234:237], v[250:253]
	v_lshl_add_u32 v216, v216, 6, v0
	ds_add_u32 v216, v205 offset:16384
	v_lshrrev_b32_e32 v9, 24, v82
	v_lshl_add_u32 v9, v9, 6, v0
	ds_add_u32 v9, v205 offset:16384
	v_lshrrev_b32_e32 v200, 24, v81
	v_lshl_add_u32 v200, v200, 6, v0
	ds_add_u32 v200, v205 offset:16384
	v_lshrrev_b32_e32 v201, 24, v84
	v_lshl_add_u32 v201, v201, 6, v0
	ds_add_u32 v201, v205 offset:16384
	v_lshrrev_b32_e32 v216, 24, v83
	v_lshl_add_u32 v216, v216, 6, v0
	ds_add_u32 v216, v205 offset:16384
	ds_read_b128 v[230:233], v179
	ds_read_b128 v[234:237], v180
	ds_read_b32 v7, v137 offset:448
	s_waitcnt lgkmcnt(12)
; #define LAS __attribute__((address_space(3)))
; __device__ __forceinline__ void sel_unit(LAS char* lds, int b, int u, const bf16_t* QI, const bf16_t* KIDX, const float* WIDX, unsigned long long* MASK) {
;     ...
;             for (int kh = 0; kh < 2; ++kh) {
;             bf16x8 kf[2][2];
; #pragma unroll
;             for (int kb = 0; kb < 2; ++kb)
; #pragma unroll
;                 for (int ks = 0; ks < 2; ++ks) kf[kb][ks] = *(const bf16x8*)(KIDX + (rowbase + 64 * t + 32 * kh + 16 * kb + q16) * 64 + 32 * ks + 8 * kg);
; #pragma unroll
;             for (int kb = 0; kb < 2; ++kb) {
;                 f32x4 s = (f32x4){0.f, 0.f, 0.f, 0.f};
; #pragma unroll
;                 for (int hh = 0; hh < 8; ++hh) {
;                     f32x4 a = (f32x4){0.f, 0.f, 0.f, 0.f};
; #pragma unroll
;                     for (int ks = 0; ks < 2; ++ks) {
;                         const bf16x8 qv = *(const LAS bf16x8*)(lds + L_QI + q16 * 1024 + (((hh * 8 + 4 * ks + kg) ^ q16) << 4));
;                         a = __builtin_amdgcn_mfma_f32_16x16x32_bf16(kf[kb][ks], qv, a, 0, 0, 0);
;                     }
;                     const float wh = wl[hh * 16];
; #pragma unroll
;                     for (int i = 0; i < 4; ++i) s[i] += wh * fmaxf(a[i], 0.f);
	v_mfma_f32_16x16x32_bf16 v[206:209], v[42:45], v[238:241], 0
	v_max_f32_e32 v9, 0, v246
	v_max_f32_e32 v200, 0, v247
	v_max_f32_e32 v201, 0, v248
	v_max_f32_e32 v216, 0, v249
	v_mfma_f32_16x16x32_bf16 v[210:213], v[50:53], v[238:241], 0
	v_mul_f32_e32 v86, v217, v9
	v_mul_f32_e32 v85, v217, v200
	v_mul_f32_e32 v88, v217, v201
	v_mul_f32_e32 v87, v217, v216
	v_mfma_f32_16x16x32_bf16 v[206:209], v[46:49], v[242:245], v[206:209]
	v_max_f32_e32 v9, 0, v250
	v_max_f32_e32 v200, 0, v251
	v_max_f32_e32 v201, 0, v252
	v_max_f32_e32 v216, 0, v253
	v_mfma_f32_16x16x32_bf16 v[210:213], v[2:5], v[242:245], v[210:213]
	v_mul_f32_e32 v90, v217, v9
	v_mul_f32_e32 v89, v217, v200
	v_mul_f32_e32 v92, v217, v201
	v_mul_f32_e32 v91, v217, v216
	ds_read_b128 v[238:241], v176
	ds_read_b128 v[242:245], v159
	ds_read_b32 v217, v137 offset:512
	s_waitcnt lgkmcnt(4)
	v_mfma_f32_16x16x32_bf16 v[246:249], v[42:45], v[230:233], 0
	v_max_f32_e32 v9, 0, v206
	v_max_f32_e32 v200, 0, v207
	v_max_f32_e32 v201, 0, v208
	v_max_f32_e32 v216, 0, v209
	v_mfma_f32_16x16x32_bf16 v[250:253], v[50:53], v[230:233], 0
	v_fmac_f32_e32 v86, v6, v9
	v_fmac_f32_e32 v85, v6, v200
	v_fmac_f32_e32 v88, v6, v201
	v_fmac_f32_e32 v87, v6, v216
	v_mfma_f32_16x16x32_bf16 v[246:249], v[46:49], v[234:237], v[246:249]
	v_max_f32_e32 v9, 0, v210
	v_max_f32_e32 v200, 0, v211
	v_max_f32_e32 v201, 0, v212
	v_max_f32_e32 v216, 0, v213
	v_mfma_f32_16x16x32_bf16 v[250:253], v[2:5], v[234:237], v[250:253]
	v_fmac_f32_e32 v90, v6, v9
	v_fmac_f32_e32 v89, v6, v200
	v_fmac_f32_e32 v92, v6, v201
	v_fmac_f32_e32 v91, v6, v216
	ds_read_b128 v[230:233], v158
	ds_read_b128 v[234:237], v157
	ds_read_b32 v6, v137 offset:576
	s_waitcnt lgkmcnt(4)
	v_mfma_f32_16x16x32_bf16 v[206:209], v[42:45], v[238:241], 0
	v_max_f32_e32 v9, 0, v246
	v_max_f32_e32 v200, 0, v247
	v_max_f32_e32 v201, 0, v248
	v_max_f32_e32 v216, 0, v249
	v_mfma_f32_16x16x32_bf16 v[210:213], v[50:53], v[238:241], 0
	v_fmac_f32_e32 v86, v7, v9
	v_fmac_f32_e32 v85, v7, v200
	v_fmac_f32_e32 v88, v7, v201
	v_fmac_f32_e32 v87, v7, v216
	v_mfma_f32_16x16x32_bf16 v[206:209], v[46:49], v[242:245], v[206:209]
	v_max_f32_e32 v9, 0, v250
	v_max_f32_e32 v200, 0, v251
	v_max_f32_e32 v201, 0, v252
	v_max_f32_e32 v216, 0, v253
	v_mfma_f32_16x16x32_bf16 v[210:213], v[2:5], v[242:245], v[210:213]
	v_fmac_f32_e32 v90, v7, v9
	v_fmac_f32_e32 v89, v7, v200
	v_fmac_f32_e32 v92, v7, v201
	v_fmac_f32_e32 v91, v7, v216
	ds_read_b128 v[238:241], v156
	ds_read_b128 v[242:245], v155
	ds_read_b32 v7, v137 offset:640
	s_waitcnt lgkmcnt(4)
	v_mfma_f32_16x16x32_bf16 v[246:249], v[42:45], v[230:233], 0
	v_max_f32_e32 v9, 0, v206
	v_max_f32_e32 v200, 0, v207
	v_max_f32_e32 v201, 0, v208
	v_max_f32_e32 v216, 0, v209
	v_mfma_f32_16x16x32_bf16 v[250:253], v[50:53], v[230:233], 0
	v_fmac_f32_e32 v86, v217, v9
	v_fmac_f32_e32 v85, v217, v200
	v_fmac_f32_e32 v88, v217, v201
	v_fmac_f32_e32 v87, v217, v216
	v_mfma_f32_16x16x32_bf16 v[246:249], v[46:49], v[234:237], v[246:249]
	v_max_f32_e32 v9, 0, v210
	v_max_f32_e32 v200, 0, v211
	v_max_f32_e32 v201, 0, v212
	v_max_f32_e32 v216, 0, v213
	v_mfma_f32_16x16x32_bf16 v[250:253], v[2:5], v[234:237], v[250:253]
	v_fmac_f32_e32 v90, v217, v9
	v_fmac_f32_e32 v89, v217, v200
	v_fmac_f32_e32 v92, v217, v201
	v_fmac_f32_e32 v91, v217, v216
	ds_read_b128 v[230:233], v154
	ds_read_b128 v[234:237], v153
	ds_read_b32 v217, v137 offset:704
	s_waitcnt lgkmcnt(4)
	v_mfma_f32_16x16x32_bf16 v[206:209], v[42:45], v[238:241], 0
	v_max_f32_e32 v9, 0, v246
	v_max_f32_e32 v200, 0, v247
	v_max_f32_e32 v201, 0, v248
	v_max_f32_e32 v216, 0, v249
	v_mfma_f32_16x16x32_bf16 v[210:213], v[50:53], v[238:241], 0
	v_fmac_f32_e32 v86, v6, v9
	v_fmac_f32_e32 v85, v6, v200
	v_fmac_f32_e32 v88, v6, v201
	v_fmac_f32_e32 v87, v6, v216
	v_mfma_f32_16x16x32_bf16 v[206:209], v[46:49], v[242:245], v[206:209]
	v_max_f32_e32 v9, 0, v250
	v_max_f32_e32 v200, 0, v251
	v_max_f32_e32 v201, 0, v252
	v_max_f32_e32 v216, 0, v253
	v_mfma_f32_16x16x32_bf16 v[210:213], v[2:5], v[242:245], v[210:213]
	v_fmac_f32_e32 v90, v6, v9
	v_fmac_f32_e32 v89, v6, v200
	v_fmac_f32_e32 v92, v6, v201
	v_fmac_f32_e32 v91, v6, v216
	ds_read_b128 v[238:241], v152
	ds_read_b128 v[242:245], v151
	ds_read_b32 v6, v137 offset:768
	s_waitcnt lgkmcnt(4)
	v_mfma_f32_16x16x32_bf16 v[246:249], v[42:45], v[230:233], 0
	v_max_f32_e32 v9, 0, v206
	v_max_f32_e32 v200, 0, v207
	v_max_f32_e32 v201, 0, v208
	v_max_f32_e32 v216, 0, v209
	v_mfma_f32_16x16x32_bf16 v[250:253], v[50:53], v[230:233], 0
	v_fmac_f32_e32 v86, v7, v9
	v_fmac_f32_e32 v85, v7, v200
	v_fmac_f32_e32 v88, v7, v201
	v_fmac_f32_e32 v87, v7, v216
	v_mfma_f32_16x16x32_bf16 v[246:249], v[46:49], v[234:237], v[246:249]
	v_max_f32_e32 v9, 0, v210
	v_max_f32_e32 v200, 0, v211
	v_max_f32_e32 v201, 0, v212
	v_max_f32_e32 v216, 0, v213
	v_mfma_f32_16x16x32_bf16 v[250:253], v[2:5], v[234:237], v[250:253]
	v_fmac_f32_e32 v90, v7, v9
	v_fmac_f32_e32 v89, v7, v200
	v_fmac_f32_e32 v92, v7, v201
	v_fmac_f32_e32 v91, v7, v216
	s_waitcnt lgkmcnt(1)
	v_mfma_f32_16x16x32_bf16 v[206:209], v[42:45], v[238:241], 0
	v_max_f32_e32 v9, 0, v246
	v_max_f32_e32 v200, 0, v247
	v_max_f32_e32 v201, 0, v248
	v_max_f32_e32 v216, 0, v249
	v_mfma_f32_16x16x32_bf16 v[210:213], v[50:53], v[238:241], 0
	v_fmac_f32_e32 v86, v217, v9
	v_fmac_f32_e32 v85, v217, v200
	v_fmac_f32_e32 v88, v217, v201
	v_fmac_f32_e32 v87, v217, v216
	v_mfma_f32_16x16x32_bf16 v[206:209], v[46:49], v[242:245], v[206:209]
	v_max_f32_e32 v9, 0, v250
	v_max_f32_e32 v200, 0, v251
	v_max_f32_e32 v201, 0, v252
	v_max_f32_e32 v216, 0, v253
	v_mfma_f32_16x16x32_bf16 v[210:213], v[2:5], v[242:245], v[210:213]
	v_fmac_f32_e32 v90, v217, v9
	v_fmac_f32_e32 v89, v217, v200
	v_fmac_f32_e32 v92, v217, v201
	v_fmac_f32_e32 v91, v217, v216
	s_waitcnt lgkmcnt(0)
; #define LAS __attribute__((address_space(3)))
; #define SEL_HADD(idx_) __hip_atomic_fetch_add(&hist[(idx_)], 1u, __ATOMIC_RELAXED, __HIP_MEMORY_SCOPE_WORKGROUP)
; __device__ __forceinline__ unsigned fkey(float f) { const unsigned u = __float_as_uint(f); return (u & 0x80000000u) ? ~u : (u | 0x80000000u); }
; __device__ __forceinline__ void sel_unit(LAS char* lds, int b, int u, const bf16_t* QI, const bf16_t* KIDX, const float* WIDX, unsigned long long* MASK) {
;     ...
;     for (int j = 0; j < 8; ++j) {
;         if (j < nj) {
;             int t = wid + 8 * j; asm volatile("" : "+s"(t));
; #pragma unroll
;             for (int kh = 0; kh < 2; ++kh) {
;             bf16x8 kf[2][2];
; #pragma unroll
;             for (int kb = 0; kb < 2; ++kb)
; #pragma unroll
;                 for (int ks = 0; ks < 2; ++ks) kf[kb][ks] = *(const bf16x8*)(KIDX + (rowbase + 64 * t + 32 * kh + 16 * kb + q16) * 64 + 32 * ks + 8 * kg);
; #pragma unroll
;             for (int kb = 0; kb < 2; ++kb) {
;                 f32x4 s = (f32x4){0.f, 0.f, 0.f, 0.f};
; #pragma unroll
;                 for (int hh = 0; hh < 8; ++hh) {
;                     f32x4 a = (f32x4){0.f, 0.f, 0.f, 0.f};
; #pragma unroll
;                     for (int ks = 0; ks < 2; ++ks) {
;                         const bf16x8 qv = *(const LAS bf16x8*)(lds + L_QI + q16 * 1024 + (((hh * 8 + 4 * ks + kg) ^ q16) << 4));
;                         a = __builtin_amdgcn_mfma_f32_16x16x32_bf16(kf[kb][ks], qv, a, 0, 0, 0);
;                     }
;                     const float wh = wl[hh * 16];
; #pragma unroll
;                     for (int i = 0; i < 4; ++i) s[i] += wh * fmaxf(a[i], 0.f);
;                 }
;                 u32x4 kk; kk.x = fkey(s[0]); kk.y = fkey(s[1]); kk.z = fkey(s[2]); kk.w = fkey(s[3]);
;                 sc[j][2 * kh + kb] = kk;
; #pragma unroll
;                 for (int i = 0; i < 4; ++i) SEL_HADD((kk[i] >> 24) * 16 + q16);
	v_max_f32_e32 v9, 0, v206
	v_max_f32_e32 v200, 0, v207
	v_max_f32_e32 v201, 0, v208
	v_max_f32_e32 v216, 0, v209
	v_fmac_f32_e32 v86, v6, v9
	v_fmac_f32_e32 v85, v6, v200
	v_fmac_f32_e32 v88, v6, v201
	v_fmac_f32_e32 v87, v6, v216
	v_max_f32_e32 v9, 0, v210
	v_max_f32_e32 v200, 0, v211
	v_max_f32_e32 v201, 0, v212
	v_max_f32_e32 v216, 0, v213
	v_fmac_f32_e32 v90, v6, v9
	v_fmac_f32_e32 v89, v6, v200
	v_fmac_f32_e32 v92, v6, v201
	v_fmac_f32_e32 v91, v6, v216
	v_ashrrev_i32_e32 v9, 31, v86
	v_bitop3_b32 v86, v9, v86, v8 bitop3:0x36
	v_ashrrev_i32_e32 v200, 31, v85
	v_bitop3_b32 v85, v200, v85, v8 bitop3:0x36
	v_ashrrev_i32_e32 v201, 31, v88
	v_bitop3_b32 v88, v201, v88, v8 bitop3:0x36
	v_ashrrev_i32_e32 v216, 31, v87
	v_bitop3_b32 v87, v216, v87, v8 bitop3:0x36
	v_ashrrev_i32_e32 v9, 31, v90
	v_bitop3_b32 v90, v9, v90, v8 bitop3:0x36
	v_ashrrev_i32_e32 v200, 31, v89
	v_bitop3_b32 v89, v200, v89, v8 bitop3:0x36
	v_ashrrev_i32_e32 v201, 31, v92
	v_bitop3_b32 v92, v201, v92, v8 bitop3:0x36
	v_ashrrev_i32_e32 v216, 31, v91
	v_bitop3_b32 v91, v216, v91, v8 bitop3:0x36
	v_lshrrev_b32_e32 v9, 24, v86
	v_lshl_add_u32 v9, v9, 6, v0
	ds_add_u32 v9, v205 offset:16384
	v_lshrrev_b32_e32 v200, 24, v85
	v_lshl_add_u32 v200, v200, 6, v0
	ds_add_u32 v200, v205 offset:16384
	v_lshrrev_b32_e32 v201, 24, v88
	v_lshl_add_u32 v201, v201, 6, v0
	ds_add_u32 v201, v205 offset:16384
	v_lshrrev_b32_e32 v216, 24, v87
	v_lshl_add_u32 v216, v216, 6, v0
	ds_add_u32 v216, v205 offset:16384
	v_lshrrev_b32_e32 v9, 24, v90
	v_lshl_add_u32 v9, v9, 6, v0
	ds_add_u32 v9, v205 offset:16384
	v_lshrrev_b32_e32 v200, 24, v89
	v_lshl_add_u32 v200, v200, 6, v0
	ds_add_u32 v200, v205 offset:16384
	v_lshrrev_b32_e32 v201, 24, v92
	v_lshl_add_u32 v201, v201, 6, v0
	ds_add_u32 v201, v205 offset:16384
	v_lshrrev_b32_e32 v216, 24, v91
	v_lshl_add_u32 v216, v216, 6, v0
	ds_add_u32 v216, v205 offset:16384
.LBB0_660:
	s_cmp_gt_i32 s4, 2
	s_cselect_b64 s[54:55], -1, 0
	s_cmp_lt_i32 s4, 3
	s_cbranch_scc1 .LBB0_662
	ds_read_b128 v[230:233], v182
	ds_read_b128 v[234:237], v183
	ds_read_b32 v6, v137 offset:320
	ds_read_b128 v[238:241], v184
	ds_read_b128 v[242:245], v185
	ds_read_b32 v7, v137 offset:384
	s_waitcnt vmcnt(0)
	v_add_co_u32_e32 v22, vcc, s96, v22
	s_nop 1
	v_addc_co_u32_e32 v23, vcc, 0, v23, vcc
	global_load_dwordx4 v[42:45], v[22:23], off
	global_load_dwordx4 v[46:49], v[22:23], off offset:64
	global_load_dwordx4 v[50:53], v[22:23], off offset:2048
	global_load_dwordx4 v[2:5], v[22:23], off offset:2112
	s_waitcnt lgkmcnt(4)
	v_mfma_f32_16x16x32_bf16 v[246:249], v[26:29], v[230:233], 0
	v_mfma_f32_16x16x32_bf16 v[250:253], v[34:37], v[230:233], 0
	v_mfma_f32_16x16x32_bf16 v[246:249], v[30:33], v[234:237], v[246:249]
	v_mfma_f32_16x16x32_bf16 v[250:253], v[38:41], v[234:237], v[250:253]
	ds_read_b128 v[230:233], v179
	ds_read_b128 v[234:237], v180
	ds_read_b32 v217, v137 offset:448
	s_waitcnt lgkmcnt(4)
	s_nop 1
	v_mfma_f32_16x16x32_bf16 v[206:209], v[26:29], v[238:241], 0
	v_max_f32_e32 v9, 0, v246
	v_max_f32_e32 v200, 0, v247
	v_max_f32_e32 v201, 0, v248
	v_max_f32_e32 v216, 0, v249
	v_mfma_f32_16x16x32_bf16 v[210:213], v[34:37], v[238:241], 0
	v_mul_f32_e32 v94, v6, v9
	v_mul_f32_e32 v93, v6, v200
	v_mul_f32_e32 v96, v6, v201
	v_mul_f32_e32 v95, v6, v216
	v_mfma_f32_16x16x32_bf16 v[206:209], v[30:33], v[242:245], v[206:209]
	v_max_f32_e32 v9, 0, v250
	v_max_f32_e32 v200, 0, v251
	v_max_f32_e32 v201, 0, v252
	v_max_f32_e32 v216, 0, v253
	v_mfma_f32_16x16x32_bf16 v[210:213], v[38:41], v[242:245], v[210:213]
	v_mul_f32_e32 v98, v6, v9
	v_mul_f32_e32 v97, v6, v200
	v_mul_f32_e32 v100, v6, v201
	v_mul_f32_e32 v99, v6, v216
	ds_read_b128 v[238:241], v176
	ds_read_b128 v[242:245], v159
	ds_read_b32 v6, v137 offset:512
	s_waitcnt lgkmcnt(4)
	v_mfma_f32_16x16x32_bf16 v[246:249], v[26:29], v[230:233], 0
	v_max_f32_e32 v9, 0, v206
	v_max_f32_e32 v200, 0, v207
	v_max_f32_e32 v201, 0, v208
	v_max_f32_e32 v216, 0, v209
	v_mfma_f32_16x16x32_bf16 v[250:253], v[34:37], v[230:233], 0
	v_fmac_f32_e32 v94, v7, v9
	v_fmac_f32_e32 v93, v7, v200
	v_fmac_f32_e32 v96, v7, v201
	v_fmac_f32_e32 v95, v7, v216
	v_mfma_f32_16x16x32_bf16 v[246:249], v[30:33], v[234:237], v[246:249]
	v_max_f32_e32 v9, 0, v210
	v_max_f32_e32 v200, 0, v211
	v_max_f32_e32 v201, 0, v212
	v_max_f32_e32 v216, 0, v213
	v_mfma_f32_16x16x32_bf16 v[250:253], v[38:41], v[234:237], v[250:253]
	v_fmac_f32_e32 v98, v7, v9
	v_fmac_f32_e32 v97, v7, v200
	v_fmac_f32_e32 v100, v7, v201
	v_fmac_f32_e32 v99, v7, v216
	ds_read_b128 v[230:233], v158
	ds_read_b128 v[234:237], v157
	ds_read_b32 v7, v137 offset:576
	s_waitcnt lgkmcnt(4)
	v_mfma_f32_16x16x32_bf16 v[206:209], v[26:29], v[238:241], 0
	v_max_f32_e32 v9, 0, v246
	v_max_f32_e32 v200, 0, v247
	v_max_f32_e32 v201, 0, v248
	v_max_f32_e32 v216, 0, v249
	v_mfma_f32_16x16x32_bf16 v[210:213], v[34:37], v[238:241], 0
	v_fmac_f32_e32 v94, v217, v9
	v_fmac_f32_e32 v93, v217, v200
	v_fmac_f32_e32 v96, v217, v201
	v_fmac_f32_e32 v95, v217, v216
	v_mfma_f32_16x16x32_bf16 v[206:209], v[30:33], v[242:245], v[206:209]
	v_max_f32_e32 v9, 0, v250
	v_max_f32_e32 v200, 0, v251
	v_max_f32_e32 v201, 0, v252
	v_max_f32_e32 v216, 0, v253
	v_mfma_f32_16x16x32_bf16 v[210:213], v[38:41], v[242:245], v[210:213]
	v_fmac_f32_e32 v98, v217, v9
	v_fmac_f32_e32 v97, v217, v200
	v_fmac_f32_e32 v100, v217, v201
	v_fmac_f32_e32 v99, v217, v216
	ds_read_b128 v[238:241], v156
	ds_read_b128 v[242:245], v155
	ds_read_b32 v217, v137 offset:640
	s_waitcnt lgkmcnt(4)
; #define LAS __attribute__((address_space(3)))
; #define SEL_HADD(idx_) __hip_atomic_fetch_add(&hist[(idx_)], 1u, __ATOMIC_RELAXED, __HIP_MEMORY_SCOPE_WORKGROUP)
; __device__ __forceinline__ unsigned fkey(float f) { const unsigned u = __float_as_uint(f); return (u & 0x80000000u) ? ~u : (u | 0x80000000u); }
; __device__ __forceinline__ void sel_unit(LAS char* lds, int b, int u, const bf16_t* QI, const bf16_t* KIDX, const float* WIDX, unsigned long long* MASK) {
;     ...
;     for (int j = 0; j < 8; ++j) {
;         if (j < nj) {
;             int t = wid + 8 * j; asm volatile("" : "+s"(t));
; #pragma unroll
;             for (int kh = 0; kh < 2; ++kh) {
;             bf16x8 kf[2][2];
; #pragma unroll
;             for (int kb = 0; kb < 2; ++kb)
; #pragma unroll
;                 for (int ks = 0; ks < 2; ++ks) kf[kb][ks] = *(const bf16x8*)(KIDX + (rowbase + 64 * t + 32 * kh + 16 * kb + q16) * 64 + 32 * ks + 8 * kg);
; #pragma unroll
;             for (int kb = 0; kb < 2; ++kb) {
;                 f32x4 s = (f32x4){0.f, 0.f, 0.f, 0.f};
; #pragma unroll
;                 for (int hh = 0; hh < 8; ++hh) {
;                     f32x4 a = (f32x4){0.f, 0.f, 0.f, 0.f};
; #pragma unroll
;                     for (int ks = 0; ks < 2; ++ks) {
;                         const bf16x8 qv = *(const LAS bf16x8*)(lds + L_QI + q16 * 1024 + (((hh * 8 + 4 * ks + kg) ^ q16) << 4));
;                         a = __builtin_amdgcn_mfma_f32_16x16x32_bf16(kf[kb][ks], qv, a, 0, 0, 0);
;                     }
;                     const float wh = wl[hh * 16];
; #pragma unroll
;                     for (int i = 0; i < 4; ++i) s[i] += wh * fmaxf(a[i], 0.f);
;                 }
;                 u32x4 kk; kk.x = fkey(s[0]); kk.y = fkey(s[1]); kk.z = fkey(s[2]); kk.w = fkey(s[3]);
;                 sc[j][2 * kh + kb] = kk;
; #pragma unroll
;                 for (int i = 0; i < 4; ++i) SEL_HADD((kk[i] >> 24) * 16 + q16);
	v_mfma_f32_16x16x32_bf16 v[246:249], v[26:29], v[230:233], 0
	v_max_f32_e32 v9, 0, v206
	v_max_f32_e32 v200, 0, v207
	v_max_f32_e32 v201, 0, v208
	v_max_f32_e32 v216, 0, v209
	v_mfma_f32_16x16x32_bf16 v[250:253], v[34:37], v[230:233], 0
	v_fmac_f32_e32 v94, v6, v9
	v_fmac_f32_e32 v93, v6, v200
	v_fmac_f32_e32 v96, v6, v201
	v_fmac_f32_e32 v95, v6, v216
	v_mfma_f32_16x16x32_bf16 v[246:249], v[30:33], v[234:237], v[246:249]
	v_max_f32_e32 v9, 0, v210
	v_max_f32_e32 v200, 0, v211
	v_max_f32_e32 v201, 0, v212
	v_max_f32_e32 v216, 0, v213
	v_mfma_f32_16x16x32_bf16 v[250:253], v[38:41], v[234:237], v[250:253]
	v_fmac_f32_e32 v98, v6, v9
	v_fmac_f32_e32 v97, v6, v200
	v_fmac_f32_e32 v100, v6, v201
	v_fmac_f32_e32 v99, v6, v216
	ds_read_b128 v[230:233], v154
	ds_read_b128 v[234:237], v153
	ds_read_b32 v6, v137 offset:704
	s_waitcnt lgkmcnt(4)
	v_mfma_f32_16x16x32_bf16 v[206:209], v[26:29], v[238:241], 0
	v_max_f32_e32 v9, 0, v246
	v_max_f32_e32 v200, 0, v247
	v_max_f32_e32 v201, 0, v248
	v_max_f32_e32 v216, 0, v249
	v_mfma_f32_16x16x32_bf16 v[210:213], v[34:37], v[238:241], 0
	v_fmac_f32_e32 v94, v7, v9
	v_fmac_f32_e32 v93, v7, v200
	v_fmac_f32_e32 v96, v7, v201
	v_fmac_f32_e32 v95, v7, v216
	v_mfma_f32_16x16x32_bf16 v[206:209], v[30:33], v[242:245], v[206:209]
	v_max_f32_e32 v9, 0, v250
	v_max_f32_e32 v200, 0, v251
	v_max_f32_e32 v201, 0, v252
	v_max_f32_e32 v216, 0, v253
	v_mfma_f32_16x16x32_bf16 v[210:213], v[38:41], v[242:245], v[210:213]
	v_fmac_f32_e32 v98, v7, v9
	v_fmac_f32_e32 v97, v7, v200
	v_fmac_f32_e32 v100, v7, v201
	v_fmac_f32_e32 v99, v7, v216
	ds_read_b128 v[238:241], v152
	ds_read_b128 v[242:245], v151
	ds_read_b32 v7, v137 offset:768
	s_waitcnt lgkmcnt(4)
	v_mfma_f32_16x16x32_bf16 v[246:249], v[26:29], v[230:233], 0
	v_max_f32_e32 v9, 0, v206
	v_max_f32_e32 v200, 0, v207
	v_max_f32_e32 v201, 0, v208
	v_max_f32_e32 v216, 0, v209
	v_mfma_f32_16x16x32_bf16 v[250:253], v[34:37], v[230:233], 0
	v_fmac_f32_e32 v94, v217, v9
	v_fmac_f32_e32 v93, v217, v200
	v_fmac_f32_e32 v96, v217, v201
	v_fmac_f32_e32 v95, v217, v216
	v_mfma_f32_16x16x32_bf16 v[246:249], v[30:33], v[234:237], v[246:249]
	v_max_f32_e32 v9, 0, v210
	v_max_f32_e32 v200, 0, v211
	v_max_f32_e32 v201, 0, v212
	v_max_f32_e32 v216, 0, v213
	v_mfma_f32_16x16x32_bf16 v[250:253], v[38:41], v[234:237], v[250:253]
	v_fmac_f32_e32 v98, v217, v9
	v_fmac_f32_e32 v97, v217, v200
	v_fmac_f32_e32 v100, v217, v201
	v_fmac_f32_e32 v99, v217, v216
	ds_read_b128 v[230:233], v182
	ds_read_b128 v[234:237], v183
	ds_read_b32 v217, v137 offset:320
	s_waitcnt lgkmcnt(4)
	v_mfma_f32_16x16x32_bf16 v[206:209], v[26:29], v[238:241], 0
	v_max_f32_e32 v9, 0, v246
	v_max_f32_e32 v200, 0, v247
	v_max_f32_e32 v201, 0, v248
	v_max_f32_e32 v216, 0, v249
	v_mfma_f32_16x16x32_bf16 v[210:213], v[34:37], v[238:241], 0
	v_fmac_f32_e32 v94, v6, v9
	v_fmac_f32_e32 v93, v6, v200
	v_fmac_f32_e32 v96, v6, v201
	v_fmac_f32_e32 v95, v6, v216
	v_mfma_f32_16x16x32_bf16 v[206:209], v[30:33], v[242:245], v[206:209]
	v_max_f32_e32 v9, 0, v250
	v_max_f32_e32 v200, 0, v251
	v_max_f32_e32 v201, 0, v252
	v_max_f32_e32 v216, 0, v253
	v_mfma_f32_16x16x32_bf16 v[210:213], v[38:41], v[242:245], v[210:213]
	v_fmac_f32_e32 v98, v6, v9
	v_fmac_f32_e32 v97, v6, v200
	v_fmac_f32_e32 v100, v6, v201
	v_fmac_f32_e32 v99, v6, v216
	ds_read_b128 v[238:241], v184
	ds_read_b128 v[242:245], v185
	ds_read_b32 v6, v137 offset:384
	s_waitcnt vmcnt(0)
	s_cmp_lt_i32 s4, 4
	s_cbranch_scc1 .Lp0_nopf_2
	v_add_co_u32_e32 v22, vcc, 0xf000, v22
	s_nop 1
	v_addc_co_u32_e32 v23, vcc, 0, v23, vcc
	global_load_dwordx4 v[26:29], v[22:23], off
	global_load_dwordx4 v[30:33], v[22:23], off offset:64
	global_load_dwordx4 v[34:37], v[22:23], off offset:2048
	global_load_dwordx4 v[38:41], v[22:23], off offset:2112
.Lp0_nopf_2:
	s_waitcnt lgkmcnt(4)
	v_mfma_f32_16x16x32_bf16 v[246:249], v[42:45], v[230:233], 0
	v_max_f32_e32 v9, 0, v206
	v_max_f32_e32 v200, 0, v207
	v_max_f32_e32 v201, 0, v208
	v_max_f32_e32 v216, 0, v209
	v_fmac_f32_e32 v94, v7, v9
	v_fmac_f32_e32 v93, v7, v200
	v_fmac_f32_e32 v96, v7, v201
	v_fmac_f32_e32 v95, v7, v216
	v_max_f32_e32 v9, 0, v210
	v_max_f32_e32 v200, 0, v211
	v_max_f32_e32 v201, 0, v212
	v_max_f32_e32 v216, 0, v213
	v_fmac_f32_e32 v98, v7, v9
	v_fmac_f32_e32 v97, v7, v200
	v_mfma_f32_16x16x32_bf16 v[250:253], v[50:53], v[230:233], 0
	v_fmac_f32_e32 v100, v7, v201
	v_fmac_f32_e32 v99, v7, v216
	v_ashrrev_i32_e32 v9, 31, v94
	v_bitop3_b32 v94, v9, v94, v8 bitop3:0x36
	v_ashrrev_i32_e32 v200, 31, v93
	v_bitop3_b32 v93, v200, v93, v8 bitop3:0x36
	v_ashrrev_i32_e32 v201, 31, v96
	v_bitop3_b32 v96, v201, v96, v8 bitop3:0x36
	v_ashrrev_i32_e32 v216, 31, v95
	v_bitop3_b32 v95, v216, v95, v8 bitop3:0x36
	v_ashrrev_i32_e32 v9, 31, v98
	v_bitop3_b32 v98, v9, v98, v8 bitop3:0x36
	v_ashrrev_i32_e32 v200, 31, v97
	v_bitop3_b32 v97, v200, v97, v8 bitop3:0x36
	v_mfma_f32_16x16x32_bf16 v[246:249], v[46:49], v[234:237], v[246:249]
	v_ashrrev_i32_e32 v201, 31, v100
	v_bitop3_b32 v100, v201, v100, v8 bitop3:0x36
	v_ashrrev_i32_e32 v216, 31, v99
	v_bitop3_b32 v99, v216, v99, v8 bitop3:0x36
	v_lshrrev_b32_e32 v9, 24, v94
	v_lshl_add_u32 v9, v9, 6, v0
	ds_add_u32 v9, v205 offset:16384
	v_lshrrev_b32_e32 v200, 24, v93
	v_lshl_add_u32 v200, v200, 6, v0
	ds_add_u32 v200, v205 offset:16384
	v_lshrrev_b32_e32 v201, 24, v96
	v_lshl_add_u32 v201, v201, 6, v0
	ds_add_u32 v201, v205 offset:16384
	v_lshrrev_b32_e32 v216, 24, v95
	v_mfma_f32_16x16x32_bf16 v[250:253], v[2:5], v[234:237], v[250:253]
	v_lshl_add_u32 v216, v216, 6, v0
	ds_add_u32 v216, v205 offset:16384
	v_lshrrev_b32_e32 v9, 24, v98
	v_lshl_add_u32 v9, v9, 6, v0
	ds_add_u32 v9, v205 offset:16384
	v_lshrrev_b32_e32 v200, 24, v97
	v_lshl_add_u32 v200, v200, 6, v0
	ds_add_u32 v200, v205 offset:16384
	v_lshrrev_b32_e32 v201, 24, v100
	v_lshl_add_u32 v201, v201, 6, v0
	ds_add_u32 v201, v205 offset:16384
	v_lshrrev_b32_e32 v216, 24, v99
	v_lshl_add_u32 v216, v216, 6, v0
	ds_add_u32 v216, v205 offset:16384
	ds_read_b128 v[230:233], v179
	ds_read_b128 v[234:237], v180
	ds_read_b32 v7, v137 offset:448
	s_waitcnt lgkmcnt(12)
; #define LAS __attribute__((address_space(3)))
; __device__ __forceinline__ void sel_unit(LAS char* lds, int b, int u, const bf16_t* QI, const bf16_t* KIDX, const float* WIDX, unsigned long long* MASK) {
;     ...
;     for (int j = 0; j < 8; ++j) {
;         if (j < nj) {
;             int t = wid + 8 * j; asm volatile("" : "+s"(t));
; #pragma unroll
;             for (int kh = 0; kh < 2; ++kh) {
;             bf16x8 kf[2][2];
; #pragma unroll
;             for (int kb = 0; kb < 2; ++kb)
; #pragma unroll
;                 for (int ks = 0; ks < 2; ++ks) kf[kb][ks] = *(const bf16x8*)(KIDX + (rowbase + 64 * t + 32 * kh + 16 * kb + q16) * 64 + 32 * ks + 8 * kg);
; #pragma unroll
;             for (int kb = 0; kb < 2; ++kb) {
;                 f32x4 s = (f32x4){0.f, 0.f, 0.f, 0.f};
; #pragma unroll
;                 for (int hh = 0; hh < 8; ++hh) {
;                     f32x4 a = (f32x4){0.f, 0.f, 0.f, 0.f};
; #pragma unroll
;                     for (int ks = 0; ks < 2; ++ks) {
;                         const bf16x8 qv = *(const LAS bf16x8*)(lds + L_QI + q16 * 1024 + (((hh * 8 + 4 * ks + kg) ^ q16) << 4));
;                         a = __builtin_amdgcn_mfma_f32_16x16x32_bf16(kf[kb][ks], qv, a, 0, 0, 0);
;                     }
;                     const float wh = wl[hh * 16];
; #pragma unroll
;                     for (int i = 0; i < 4; ++i) s[i] += wh * fmaxf(a[i], 0.f);
;                 }
	v_mfma_f32_16x16x32_bf16 v[206:209], v[42:45], v[238:241], 0
	v_max_f32_e32 v9, 0, v246
	v_max_f32_e32 v200, 0, v247
	v_max_f32_e32 v201, 0, v248
	v_max_f32_e32 v216, 0, v249
	v_mfma_f32_16x16x32_bf16 v[210:213], v[50:53], v[238:241], 0
	v_mul_f32_e32 v102, v217, v9
	v_mul_f32_e32 v101, v217, v200
	v_mul_f32_e32 v104, v217, v201
	v_mul_f32_e32 v103, v217, v216
	v_mfma_f32_16x16x32_bf16 v[206:209], v[46:49], v[242:245], v[206:209]
	v_max_f32_e32 v9, 0, v250
	v_max_f32_e32 v200, 0, v251
	v_max_f32_e32 v201, 0, v252
	v_max_f32_e32 v216, 0, v253
	v_mfma_f32_16x16x32_bf16 v[210:213], v[2:5], v[242:245], v[210:213]
	v_mul_f32_e32 v106, v217, v9
	v_mul_f32_e32 v105, v217, v200
	v_mul_f32_e32 v108, v217, v201
	v_mul_f32_e32 v107, v217, v216
	ds_read_b128 v[238:241], v176
	ds_read_b128 v[242:245], v159
	ds_read_b32 v217, v137 offset:512
	s_waitcnt lgkmcnt(4)
	v_mfma_f32_16x16x32_bf16 v[246:249], v[42:45], v[230:233], 0
	v_max_f32_e32 v9, 0, v206
	v_max_f32_e32 v200, 0, v207
	v_max_f32_e32 v201, 0, v208
	v_max_f32_e32 v216, 0, v209
	v_mfma_f32_16x16x32_bf16 v[250:253], v[50:53], v[230:233], 0
	v_fmac_f32_e32 v102, v6, v9
	v_fmac_f32_e32 v101, v6, v200
	v_fmac_f32_e32 v104, v6, v201
	v_fmac_f32_e32 v103, v6, v216
	v_mfma_f32_16x16x32_bf16 v[246:249], v[46:49], v[234:237], v[246:249]
	v_max_f32_e32 v9, 0, v210
	v_max_f32_e32 v200, 0, v211
	v_max_f32_e32 v201, 0, v212
	v_max_f32_e32 v216, 0, v213
	v_mfma_f32_16x16x32_bf16 v[250:253], v[2:5], v[234:237], v[250:253]
	v_fmac_f32_e32 v106, v6, v9
	v_fmac_f32_e32 v105, v6, v200
	v_fmac_f32_e32 v108, v6, v201
	v_fmac_f32_e32 v107, v6, v216
	ds_read_b128 v[230:233], v158
	ds_read_b128 v[234:237], v157
	ds_read_b32 v6, v137 offset:576
	s_waitcnt lgkmcnt(4)
	v_mfma_f32_16x16x32_bf16 v[206:209], v[42:45], v[238:241], 0
	v_max_f32_e32 v9, 0, v246
	v_max_f32_e32 v200, 0, v247
	v_max_f32_e32 v201, 0, v248
	v_max_f32_e32 v216, 0, v249
	v_mfma_f32_16x16x32_bf16 v[210:213], v[50:53], v[238:241], 0
	v_fmac_f32_e32 v102, v7, v9
	v_fmac_f32_e32 v101, v7, v200
	v_fmac_f32_e32 v104, v7, v201
	v_fmac_f32_e32 v103, v7, v216
	v_mfma_f32_16x16x32_bf16 v[206:209], v[46:49], v[242:245], v[206:209]
	v_max_f32_e32 v9, 0, v250
	v_max_f32_e32 v200, 0, v251
	v_max_f32_e32 v201, 0, v252
	v_max_f32_e32 v216, 0, v253
	v_mfma_f32_16x16x32_bf16 v[210:213], v[2:5], v[242:245], v[210:213]
	v_fmac_f32_e32 v106, v7, v9
	v_fmac_f32_e32 v105, v7, v200
	v_fmac_f32_e32 v108, v7, v201
	v_fmac_f32_e32 v107, v7, v216
	ds_read_b128 v[238:241], v156
	ds_read_b128 v[242:245], v155
	ds_read_b32 v7, v137 offset:640
	s_waitcnt lgkmcnt(4)
	v_mfma_f32_16x16x32_bf16 v[246:249], v[42:45], v[230:233], 0
	v_max_f32_e32 v9, 0, v206
	v_max_f32_e32 v200, 0, v207
	v_max_f32_e32 v201, 0, v208
	v_max_f32_e32 v216, 0, v209
	v_mfma_f32_16x16x32_bf16 v[250:253], v[50:53], v[230:233], 0
	v_fmac_f32_e32 v102, v217, v9
	v_fmac_f32_e32 v101, v217, v200
	v_fmac_f32_e32 v104, v217, v201
	v_fmac_f32_e32 v103, v217, v216
	v_mfma_f32_16x16x32_bf16 v[246:249], v[46:49], v[234:237], v[246:249]
	v_max_f32_e32 v9, 0, v210
	v_max_f32_e32 v200, 0, v211
	v_max_f32_e32 v201, 0, v212
	v_max_f32_e32 v216, 0, v213
	v_mfma_f32_16x16x32_bf16 v[250:253], v[2:5], v[234:237], v[250:253]
	v_fmac_f32_e32 v106, v217, v9
	v_fmac_f32_e32 v105, v217, v200
	v_fmac_f32_e32 v108, v217, v201
	v_fmac_f32_e32 v107, v217, v216
	ds_read_b128 v[230:233], v154
	ds_read_b128 v[234:237], v153
	ds_read_b32 v217, v137 offset:704
	s_waitcnt lgkmcnt(4)
	v_mfma_f32_16x16x32_bf16 v[206:209], v[42:45], v[238:241], 0
	v_max_f32_e32 v9, 0, v246
	v_max_f32_e32 v200, 0, v247
	v_max_f32_e32 v201, 0, v248
	v_max_f32_e32 v216, 0, v249
	v_mfma_f32_16x16x32_bf16 v[210:213], v[50:53], v[238:241], 0
	v_fmac_f32_e32 v102, v6, v9
	v_fmac_f32_e32 v101, v6, v200
	v_fmac_f32_e32 v104, v6, v201
	v_fmac_f32_e32 v103, v6, v216
	v_mfma_f32_16x16x32_bf16 v[206:209], v[46:49], v[242:245], v[206:209]
	v_max_f32_e32 v9, 0, v250
	v_max_f32_e32 v200, 0, v251
	v_max_f32_e32 v201, 0, v252
	v_max_f32_e32 v216, 0, v253
	v_mfma_f32_16x16x32_bf16 v[210:213], v[2:5], v[242:245], v[210:213]
	v_fmac_f32_e32 v106, v6, v9
	v_fmac_f32_e32 v105, v6, v200
	v_fmac_f32_e32 v108, v6, v201
	v_fmac_f32_e32 v107, v6, v216
	ds_read_b128 v[238:241], v152
	ds_read_b128 v[242:245], v151
	ds_read_b32 v6, v137 offset:768
	s_waitcnt lgkmcnt(4)
	v_mfma_f32_16x16x32_bf16 v[246:249], v[42:45], v[230:233], 0
	v_max_f32_e32 v9, 0, v206
	v_max_f32_e32 v200, 0, v207
	v_max_f32_e32 v201, 0, v208
	v_max_f32_e32 v216, 0, v209
	v_mfma_f32_16x16x32_bf16 v[250:253], v[50:53], v[230:233], 0
	v_fmac_f32_e32 v102, v7, v9
	v_fmac_f32_e32 v101, v7, v200
	v_fmac_f32_e32 v104, v7, v201
	v_fmac_f32_e32 v103, v7, v216
	v_mfma_f32_16x16x32_bf16 v[246:249], v[46:49], v[234:237], v[246:249]
	v_max_f32_e32 v9, 0, v210
	v_max_f32_e32 v200, 0, v211
	v_max_f32_e32 v201, 0, v212
	v_max_f32_e32 v216, 0, v213
	v_mfma_f32_16x16x32_bf16 v[250:253], v[2:5], v[234:237], v[250:253]
	v_fmac_f32_e32 v106, v7, v9
	v_fmac_f32_e32 v105, v7, v200
	v_fmac_f32_e32 v108, v7, v201
	v_fmac_f32_e32 v107, v7, v216
	s_waitcnt lgkmcnt(1)
	v_mfma_f32_16x16x32_bf16 v[206:209], v[42:45], v[238:241], 0
	v_max_f32_e32 v9, 0, v246
	v_max_f32_e32 v200, 0, v247
	v_max_f32_e32 v201, 0, v248
	v_max_f32_e32 v216, 0, v249
	v_mfma_f32_16x16x32_bf16 v[210:213], v[50:53], v[238:241], 0
	v_fmac_f32_e32 v102, v217, v9
	v_fmac_f32_e32 v101, v217, v200
	v_fmac_f32_e32 v104, v217, v201
	v_fmac_f32_e32 v103, v217, v216
	v_mfma_f32_16x16x32_bf16 v[206:209], v[46:49], v[242:245], v[206:209]
	v_max_f32_e32 v9, 0, v250
	v_max_f32_e32 v200, 0, v251
	v_max_f32_e32 v201, 0, v252
	v_max_f32_e32 v216, 0, v253
	v_mfma_f32_16x16x32_bf16 v[210:213], v[2:5], v[242:245], v[210:213]
	v_fmac_f32_e32 v106, v217, v9
	v_fmac_f32_e32 v105, v217, v200
	v_fmac_f32_e32 v108, v217, v201
	v_fmac_f32_e32 v107, v217, v216
	s_waitcnt lgkmcnt(0)
; #define LAS __attribute__((address_space(3)))
; #define SEL_HADD(idx_) __hip_atomic_fetch_add(&hist[(idx_)], 1u, __ATOMIC_RELAXED, __HIP_MEMORY_SCOPE_WORKGROUP)
; __device__ __forceinline__ unsigned fkey(float f) { const unsigned u = __float_as_uint(f); return (u & 0x80000000u) ? ~u : (u | 0x80000000u); }
; __device__ __forceinline__ void sel_unit(LAS char* lds, int b, int u, const bf16_t* QI, const bf16_t* KIDX, const float* WIDX, unsigned long long* MASK) {
;     ...
;     for (int j = 0; j < 8; ++j) {
;         if (j < nj) {
;             int t = wid + 8 * j; asm volatile("" : "+s"(t));
; #pragma unroll
;             for (int kh = 0; kh < 2; ++kh) {
;             bf16x8 kf[2][2];
; #pragma unroll
;             for (int kb = 0; kb < 2; ++kb)
; #pragma unroll
;                 for (int ks = 0; ks < 2; ++ks) kf[kb][ks] = *(const bf16x8*)(KIDX + (rowbase + 64 * t + 32 * kh + 16 * kb + q16) * 64 + 32 * ks + 8 * kg);
; #pragma unroll
;             for (int kb = 0; kb < 2; ++kb) {
;                 f32x4 s = (f32x4){0.f, 0.f, 0.f, 0.f};
; #pragma unroll
;                 for (int hh = 0; hh < 8; ++hh) {
;                     f32x4 a = (f32x4){0.f, 0.f, 0.f, 0.f};
; #pragma unroll
;                     for (int ks = 0; ks < 2; ++ks) {
;                         const bf16x8 qv = *(const LAS bf16x8*)(lds + L_QI + q16 * 1024 + (((hh * 8 + 4 * ks + kg) ^ q16) << 4));
;                         a = __builtin_amdgcn_mfma_f32_16x16x32_bf16(kf[kb][ks], qv, a, 0, 0, 0);
;                     }
;                     const float wh = wl[hh * 16];
; #pragma unroll
;                     for (int i = 0; i < 4; ++i) s[i] += wh * fmaxf(a[i], 0.f);
;                 }
;                 u32x4 kk; kk.x = fkey(s[0]); kk.y = fkey(s[1]); kk.z = fkey(s[2]); kk.w = fkey(s[3]);
;                 sc[j][2 * kh + kb] = kk;
; #pragma unroll
;                 for (int i = 0; i < 4; ++i) SEL_HADD((kk[i] >> 24) * 16 + q16);
	v_max_f32_e32 v9, 0, v206
	v_max_f32_e32 v200, 0, v207
	v_max_f32_e32 v201, 0, v208
	v_max_f32_e32 v216, 0, v209
	v_fmac_f32_e32 v102, v6, v9
	v_fmac_f32_e32 v101, v6, v200
	v_fmac_f32_e32 v104, v6, v201
	v_fmac_f32_e32 v103, v6, v216
	v_max_f32_e32 v9, 0, v210
	v_max_f32_e32 v200, 0, v211
	v_max_f32_e32 v201, 0, v212
	v_max_f32_e32 v216, 0, v213
	v_fmac_f32_e32 v106, v6, v9
	v_fmac_f32_e32 v105, v6, v200
	v_fmac_f32_e32 v108, v6, v201
	v_fmac_f32_e32 v107, v6, v216
	v_ashrrev_i32_e32 v9, 31, v102
	v_bitop3_b32 v102, v9, v102, v8 bitop3:0x36
	v_ashrrev_i32_e32 v200, 31, v101
	v_bitop3_b32 v101, v200, v101, v8 bitop3:0x36
	v_ashrrev_i32_e32 v201, 31, v104
	v_bitop3_b32 v104, v201, v104, v8 bitop3:0x36
	v_ashrrev_i32_e32 v216, 31, v103
	v_bitop3_b32 v103, v216, v103, v8 bitop3:0x36
	v_ashrrev_i32_e32 v9, 31, v106
	v_bitop3_b32 v106, v9, v106, v8 bitop3:0x36
	v_ashrrev_i32_e32 v200, 31, v105
	v_bitop3_b32 v105, v200, v105, v8 bitop3:0x36
	v_ashrrev_i32_e32 v201, 31, v108
	v_bitop3_b32 v108, v201, v108, v8 bitop3:0x36
	v_ashrrev_i32_e32 v216, 31, v107
	v_bitop3_b32 v107, v216, v107, v8 bitop3:0x36
	v_lshrrev_b32_e32 v9, 24, v102
	v_lshl_add_u32 v9, v9, 6, v0
	ds_add_u32 v9, v205 offset:16384
	v_lshrrev_b32_e32 v200, 24, v101
	v_lshl_add_u32 v200, v200, 6, v0
	ds_add_u32 v200, v205 offset:16384
	v_lshrrev_b32_e32 v201, 24, v104
	v_lshl_add_u32 v201, v201, 6, v0
	ds_add_u32 v201, v205 offset:16384
	v_lshrrev_b32_e32 v216, 24, v103
	v_lshl_add_u32 v216, v216, 6, v0
	ds_add_u32 v216, v205 offset:16384
	v_lshrrev_b32_e32 v9, 24, v106
	v_lshl_add_u32 v9, v9, 6, v0
	ds_add_u32 v9, v205 offset:16384
	v_lshrrev_b32_e32 v200, 24, v105
	v_lshl_add_u32 v200, v200, 6, v0
	ds_add_u32 v200, v205 offset:16384
	v_lshrrev_b32_e32 v201, 24, v108
	v_lshl_add_u32 v201, v201, 6, v0
	ds_add_u32 v201, v205 offset:16384
	v_lshrrev_b32_e32 v216, 24, v107
	v_lshl_add_u32 v216, v216, 6, v0
	ds_add_u32 v216, v205 offset:16384
.LBB0_662:
	s_cmp_gt_i32 s4, 3
	s_cselect_b64 s[56:57], -1, 0
	s_cmp_lt_i32 s4, 4
	s_cbranch_scc1 .LBB0_664
	ds_read_b128 v[230:233], v182
	ds_read_b128 v[234:237], v183
	ds_read_b32 v6, v137 offset:320
	ds_read_b128 v[238:241], v184
	ds_read_b128 v[242:245], v185
	ds_read_b32 v7, v137 offset:384
	s_waitcnt vmcnt(0)
	v_add_co_u32_e32 v22, vcc, s96, v22
	s_nop 1
	v_addc_co_u32_e32 v23, vcc, 0, v23, vcc
	global_load_dwordx4 v[42:45], v[22:23], off
	global_load_dwordx4 v[46:49], v[22:23], off offset:64
	global_load_dwordx4 v[50:53], v[22:23], off offset:2048
	global_load_dwordx4 v[2:5], v[22:23], off offset:2112
	s_waitcnt lgkmcnt(4)
	v_mfma_f32_16x16x32_bf16 v[246:249], v[26:29], v[230:233], 0
	v_mfma_f32_16x16x32_bf16 v[250:253], v[34:37], v[230:233], 0
	v_mfma_f32_16x16x32_bf16 v[246:249], v[30:33], v[234:237], v[246:249]
	v_mfma_f32_16x16x32_bf16 v[250:253], v[38:41], v[234:237], v[250:253]
	ds_read_b128 v[230:233], v179
	ds_read_b128 v[234:237], v180
	ds_read_b32 v217, v137 offset:448
	s_waitcnt lgkmcnt(4)
	s_nop 1
	v_mfma_f32_16x16x32_bf16 v[206:209], v[26:29], v[238:241], 0
	v_max_f32_e32 v9, 0, v246
	v_max_f32_e32 v200, 0, v247
	v_max_f32_e32 v201, 0, v248
	v_max_f32_e32 v216, 0, v249
	v_mfma_f32_16x16x32_bf16 v[210:213], v[34:37], v[238:241], 0
	v_mul_f32_e32 v110, v6, v9
	v_mul_f32_e32 v109, v6, v200
	v_mul_f32_e32 v112, v6, v201
	v_mul_f32_e32 v111, v6, v216
	v_mfma_f32_16x16x32_bf16 v[206:209], v[30:33], v[242:245], v[206:209]
	v_max_f32_e32 v9, 0, v250
	v_max_f32_e32 v200, 0, v251
	v_max_f32_e32 v201, 0, v252
	v_max_f32_e32 v216, 0, v253
	v_mfma_f32_16x16x32_bf16 v[210:213], v[38:41], v[242:245], v[210:213]
	v_mul_f32_e32 v114, v6, v9
	v_mul_f32_e32 v113, v6, v200
	v_mul_f32_e32 v116, v6, v201
	v_mul_f32_e32 v115, v6, v216
	ds_read_b128 v[238:241], v176
	ds_read_b128 v[242:245], v159
	ds_read_b32 v6, v137 offset:512
	s_waitcnt lgkmcnt(4)
	v_mfma_f32_16x16x32_bf16 v[246:249], v[26:29], v[230:233], 0
	v_max_f32_e32 v9, 0, v206
	v_max_f32_e32 v200, 0, v207
	v_max_f32_e32 v201, 0, v208
	v_max_f32_e32 v216, 0, v209
	v_mfma_f32_16x16x32_bf16 v[250:253], v[34:37], v[230:233], 0
	v_fmac_f32_e32 v110, v7, v9
	v_fmac_f32_e32 v109, v7, v200
	v_fmac_f32_e32 v112, v7, v201
	v_fmac_f32_e32 v111, v7, v216
	v_mfma_f32_16x16x32_bf16 v[246:249], v[30:33], v[234:237], v[246:249]
	v_max_f32_e32 v9, 0, v210
	v_max_f32_e32 v200, 0, v211
	v_max_f32_e32 v201, 0, v212
	v_max_f32_e32 v216, 0, v213
	v_mfma_f32_16x16x32_bf16 v[250:253], v[38:41], v[234:237], v[250:253]
	v_fmac_f32_e32 v114, v7, v9
	v_fmac_f32_e32 v113, v7, v200
	v_fmac_f32_e32 v116, v7, v201
	v_fmac_f32_e32 v115, v7, v216
	ds_read_b128 v[230:233], v158
	ds_read_b128 v[234:237], v157
	ds_read_b32 v7, v137 offset:576
	s_waitcnt lgkmcnt(4)
	v_mfma_f32_16x16x32_bf16 v[206:209], v[26:29], v[238:241], 0
	v_max_f32_e32 v9, 0, v246
	v_max_f32_e32 v200, 0, v247
	v_max_f32_e32 v201, 0, v248
	v_max_f32_e32 v216, 0, v249
	v_mfma_f32_16x16x32_bf16 v[210:213], v[34:37], v[238:241], 0
	v_fmac_f32_e32 v110, v217, v9
	v_fmac_f32_e32 v109, v217, v200
	v_fmac_f32_e32 v112, v217, v201
	v_fmac_f32_e32 v111, v217, v216
	v_mfma_f32_16x16x32_bf16 v[206:209], v[30:33], v[242:245], v[206:209]
	v_max_f32_e32 v9, 0, v250
	v_max_f32_e32 v200, 0, v251
	v_max_f32_e32 v201, 0, v252
	v_max_f32_e32 v216, 0, v253
	v_mfma_f32_16x16x32_bf16 v[210:213], v[38:41], v[242:245], v[210:213]
	v_fmac_f32_e32 v114, v217, v9
	v_fmac_f32_e32 v113, v217, v200
	v_fmac_f32_e32 v116, v217, v201
	v_fmac_f32_e32 v115, v217, v216
	ds_read_b128 v[238:241], v156
	ds_read_b128 v[242:245], v155
	ds_read_b32 v217, v137 offset:640
	s_waitcnt lgkmcnt(4)
; #define LAS __attribute__((address_space(3)))
; #define SEL_HADD(idx_) __hip_atomic_fetch_add(&hist[(idx_)], 1u, __ATOMIC_RELAXED, __HIP_MEMORY_SCOPE_WORKGROUP)
; __device__ __forceinline__ unsigned fkey(float f) { const unsigned u = __float_as_uint(f); return (u & 0x80000000u) ? ~u : (u | 0x80000000u); }
; __device__ __forceinline__ void sel_unit(LAS char* lds, int b, int u, const bf16_t* QI, const bf16_t* KIDX, const float* WIDX, unsigned long long* MASK) {
;     ...
;     for (int j = 0; j < 8; ++j) {
;         if (j < nj) {
;             int t = wid + 8 * j; asm volatile("" : "+s"(t));
; #pragma unroll
;             for (int kh = 0; kh < 2; ++kh) {
;             bf16x8 kf[2][2];
; #pragma unroll
;             for (int kb = 0; kb < 2; ++kb)
; #pragma unroll
;                 for (int ks = 0; ks < 2; ++ks) kf[kb][ks] = *(const bf16x8*)(KIDX + (rowbase + 64 * t + 32 * kh + 16 * kb + q16) * 64 + 32 * ks + 8 * kg);
; #pragma unroll
;             for (int kb = 0; kb < 2; ++kb) {
;                 f32x4 s = (f32x4){0.f, 0.f, 0.f, 0.f};
; #pragma unroll
;                 for (int hh = 0; hh < 8; ++hh) {
;                     f32x4 a = (f32x4){0.f, 0.f, 0.f, 0.f};
; #pragma unroll
;                     for (int ks = 0; ks < 2; ++ks) {
;                         const bf16x8 qv = *(const LAS bf16x8*)(lds + L_QI + q16 * 1024 + (((hh * 8 + 4 * ks + kg) ^ q16) << 4));
;                         a = __builtin_amdgcn_mfma_f32_16x16x32_bf16(kf[kb][ks], qv, a, 0, 0, 0);
;                     }
;                     const float wh = wl[hh * 16];
; #pragma unroll
;                     for (int i = 0; i < 4; ++i) s[i] += wh * fmaxf(a[i], 0.f);
;                 }
;                 u32x4 kk; kk.x = fkey(s[0]); kk.y = fkey(s[1]); kk.z = fkey(s[2]); kk.w = fkey(s[3]);
;                 sc[j][2 * kh + kb] = kk;
; #pragma unroll
;                 for (int i = 0; i < 4; ++i) SEL_HADD((kk[i] >> 24) * 16 + q16);
	v_mfma_f32_16x16x32_bf16 v[246:249], v[26:29], v[230:233], 0
	v_max_f32_e32 v9, 0, v206
	v_max_f32_e32 v200, 0, v207
	v_max_f32_e32 v201, 0, v208
	v_max_f32_e32 v216, 0, v209
	v_mfma_f32_16x16x32_bf16 v[250:253], v[34:37], v[230:233], 0
	v_fmac_f32_e32 v110, v6, v9
	v_fmac_f32_e32 v109, v6, v200
	v_fmac_f32_e32 v112, v6, v201
	v_fmac_f32_e32 v111, v6, v216
	v_mfma_f32_16x16x32_bf16 v[246:249], v[30:33], v[234:237], v[246:249]
	v_max_f32_e32 v9, 0, v210
	v_max_f32_e32 v200, 0, v211
	v_max_f32_e32 v201, 0, v212
	v_max_f32_e32 v216, 0, v213
	v_mfma_f32_16x16x32_bf16 v[250:253], v[38:41], v[234:237], v[250:253]
	v_fmac_f32_e32 v114, v6, v9
	v_fmac_f32_e32 v113, v6, v200
	v_fmac_f32_e32 v116, v6, v201
	v_fmac_f32_e32 v115, v6, v216
	ds_read_b128 v[230:233], v154
	ds_read_b128 v[234:237], v153
	ds_read_b32 v6, v137 offset:704
	s_waitcnt lgkmcnt(4)
	v_mfma_f32_16x16x32_bf16 v[206:209], v[26:29], v[238:241], 0
	v_max_f32_e32 v9, 0, v246
	v_max_f32_e32 v200, 0, v247
	v_max_f32_e32 v201, 0, v248
	v_max_f32_e32 v216, 0, v249
	v_mfma_f32_16x16x32_bf16 v[210:213], v[34:37], v[238:241], 0
	v_fmac_f32_e32 v110, v7, v9
	v_fmac_f32_e32 v109, v7, v200
	v_fmac_f32_e32 v112, v7, v201
	v_fmac_f32_e32 v111, v7, v216
	v_mfma_f32_16x16x32_bf16 v[206:209], v[30:33], v[242:245], v[206:209]
	v_max_f32_e32 v9, 0, v250
	v_max_f32_e32 v200, 0, v251
	v_max_f32_e32 v201, 0, v252
	v_max_f32_e32 v216, 0, v253
	v_mfma_f32_16x16x32_bf16 v[210:213], v[38:41], v[242:245], v[210:213]
	v_fmac_f32_e32 v114, v7, v9
	v_fmac_f32_e32 v113, v7, v200
	v_fmac_f32_e32 v116, v7, v201
	v_fmac_f32_e32 v115, v7, v216
	ds_read_b128 v[238:241], v152
	ds_read_b128 v[242:245], v151
	ds_read_b32 v7, v137 offset:768
	s_waitcnt lgkmcnt(4)
	v_mfma_f32_16x16x32_bf16 v[246:249], v[26:29], v[230:233], 0
	v_max_f32_e32 v9, 0, v206
	v_max_f32_e32 v200, 0, v207
	v_max_f32_e32 v201, 0, v208
	v_max_f32_e32 v216, 0, v209
	v_mfma_f32_16x16x32_bf16 v[250:253], v[34:37], v[230:233], 0
	v_fmac_f32_e32 v110, v217, v9
	v_fmac_f32_e32 v109, v217, v200
	v_fmac_f32_e32 v112, v217, v201
	v_fmac_f32_e32 v111, v217, v216
	v_mfma_f32_16x16x32_bf16 v[246:249], v[30:33], v[234:237], v[246:249]
	v_max_f32_e32 v9, 0, v210
	v_max_f32_e32 v200, 0, v211
	v_max_f32_e32 v201, 0, v212
	v_max_f32_e32 v216, 0, v213
	v_mfma_f32_16x16x32_bf16 v[250:253], v[38:41], v[234:237], v[250:253]
	v_fmac_f32_e32 v114, v217, v9
	v_fmac_f32_e32 v113, v217, v200
	v_fmac_f32_e32 v116, v217, v201
	v_fmac_f32_e32 v115, v217, v216
	ds_read_b128 v[230:233], v182
	ds_read_b128 v[234:237], v183
	ds_read_b32 v217, v137 offset:320
	s_waitcnt lgkmcnt(4)
	v_mfma_f32_16x16x32_bf16 v[206:209], v[26:29], v[238:241], 0
	v_max_f32_e32 v9, 0, v246
	v_max_f32_e32 v200, 0, v247
	v_max_f32_e32 v201, 0, v248
	v_max_f32_e32 v216, 0, v249
	v_mfma_f32_16x16x32_bf16 v[210:213], v[34:37], v[238:241], 0
	v_fmac_f32_e32 v110, v6, v9
	v_fmac_f32_e32 v109, v6, v200
	v_fmac_f32_e32 v112, v6, v201
	v_fmac_f32_e32 v111, v6, v216
	v_mfma_f32_16x16x32_bf16 v[206:209], v[30:33], v[242:245], v[206:209]
	v_max_f32_e32 v9, 0, v250
	v_max_f32_e32 v200, 0, v251
	v_max_f32_e32 v201, 0, v252
	v_max_f32_e32 v216, 0, v253
	v_mfma_f32_16x16x32_bf16 v[210:213], v[38:41], v[242:245], v[210:213]
	v_fmac_f32_e32 v114, v6, v9
	v_fmac_f32_e32 v113, v6, v200
	v_fmac_f32_e32 v116, v6, v201
	v_fmac_f32_e32 v115, v6, v216
	ds_read_b128 v[238:241], v184
	ds_read_b128 v[242:245], v185
	ds_read_b32 v6, v137 offset:384
	s_waitcnt vmcnt(0)
	s_cmp_lt_i32 s4, 5
	s_cbranch_scc1 .Lp0_nopf_3
	v_add_co_u32_e32 v22, vcc, 0xf000, v22
	s_nop 1
	v_addc_co_u32_e32 v23, vcc, 0, v23, vcc
	global_load_dwordx4 v[26:29], v[22:23], off
	global_load_dwordx4 v[30:33], v[22:23], off offset:64
	global_load_dwordx4 v[34:37], v[22:23], off offset:2048
	global_load_dwordx4 v[38:41], v[22:23], off offset:2112
.Lp0_nopf_3:
	s_waitcnt lgkmcnt(4)
	v_mfma_f32_16x16x32_bf16 v[246:249], v[42:45], v[230:233], 0
	v_max_f32_e32 v9, 0, v206
	v_max_f32_e32 v200, 0, v207
	v_max_f32_e32 v201, 0, v208
	v_max_f32_e32 v216, 0, v209
	v_fmac_f32_e32 v110, v7, v9
	v_fmac_f32_e32 v109, v7, v200
	v_fmac_f32_e32 v112, v7, v201
	v_fmac_f32_e32 v111, v7, v216
	v_max_f32_e32 v9, 0, v210
	v_max_f32_e32 v200, 0, v211
	v_max_f32_e32 v201, 0, v212
	v_max_f32_e32 v216, 0, v213
	v_fmac_f32_e32 v114, v7, v9
	v_fmac_f32_e32 v113, v7, v200
	v_mfma_f32_16x16x32_bf16 v[250:253], v[50:53], v[230:233], 0
	v_fmac_f32_e32 v116, v7, v201
	v_fmac_f32_e32 v115, v7, v216
	v_ashrrev_i32_e32 v9, 31, v110
	v_bitop3_b32 v110, v9, v110, v8 bitop3:0x36
	v_ashrrev_i32_e32 v200, 31, v109
	v_bitop3_b32 v109, v200, v109, v8 bitop3:0x36
	v_ashrrev_i32_e32 v201, 31, v112
	v_bitop3_b32 v112, v201, v112, v8 bitop3:0x36
	v_ashrrev_i32_e32 v216, 31, v111
	v_bitop3_b32 v111, v216, v111, v8 bitop3:0x36
	v_ashrrev_i32_e32 v9, 31, v114
	v_bitop3_b32 v114, v9, v114, v8 bitop3:0x36
	v_ashrrev_i32_e32 v200, 31, v113
	v_bitop3_b32 v113, v200, v113, v8 bitop3:0x36
	v_mfma_f32_16x16x32_bf16 v[246:249], v[46:49], v[234:237], v[246:249]
	v_ashrrev_i32_e32 v201, 31, v116
	v_bitop3_b32 v116, v201, v116, v8 bitop3:0x36
	v_ashrrev_i32_e32 v216, 31, v115
	v_bitop3_b32 v115, v216, v115, v8 bitop3:0x36
	v_lshrrev_b32_e32 v9, 24, v110
	v_lshl_add_u32 v9, v9, 6, v0
	ds_add_u32 v9, v205 offset:16384
	v_lshrrev_b32_e32 v200, 24, v109
	v_lshl_add_u32 v200, v200, 6, v0
	ds_add_u32 v200, v205 offset:16384
	v_lshrrev_b32_e32 v201, 24, v112
	v_lshl_add_u32 v201, v201, 6, v0
	ds_add_u32 v201, v205 offset:16384
	v_lshrrev_b32_e32 v216, 24, v111
	v_mfma_f32_16x16x32_bf16 v[250:253], v[2:5], v[234:237], v[250:253]
	v_lshl_add_u32 v216, v216, 6, v0
	ds_add_u32 v216, v205 offset:16384
	v_lshrrev_b32_e32 v9, 24, v114
	v_lshl_add_u32 v9, v9, 6, v0
	ds_add_u32 v9, v205 offset:16384
	v_lshrrev_b32_e32 v200, 24, v113
	v_lshl_add_u32 v200, v200, 6, v0
	ds_add_u32 v200, v205 offset:16384
	v_lshrrev_b32_e32 v201, 24, v116
	v_lshl_add_u32 v201, v201, 6, v0
	ds_add_u32 v201, v205 offset:16384
	v_lshrrev_b32_e32 v216, 24, v115
	v_lshl_add_u32 v216, v216, 6, v0
	ds_add_u32 v216, v205 offset:16384
	ds_read_b128 v[230:233], v179
	ds_read_b128 v[234:237], v180
	ds_read_b32 v7, v137 offset:448
	s_waitcnt lgkmcnt(12)
; #define LAS __attribute__((address_space(3)))
; __device__ __forceinline__ void sel_unit(LAS char* lds, int b, int u, const bf16_t* QI, const bf16_t* KIDX, const float* WIDX, unsigned long long* MASK) {
;     ...
;     for (int j = 0; j < 8; ++j) {
;         if (j < nj) {
;             int t = wid + 8 * j; asm volatile("" : "+s"(t));
; #pragma unroll
;             for (int kh = 0; kh < 2; ++kh) {
;             bf16x8 kf[2][2];
; #pragma unroll
;             for (int kb = 0; kb < 2; ++kb)
; #pragma unroll
;                 for (int ks = 0; ks < 2; ++ks) kf[kb][ks] = *(const bf16x8*)(KIDX + (rowbase + 64 * t + 32 * kh + 16 * kb + q16) * 64 + 32 * ks + 8 * kg);
; #pragma unroll
;             for (int kb = 0; kb < 2; ++kb) {
;                 f32x4 s = (f32x4){0.f, 0.f, 0.f, 0.f};
; #pragma unroll
;                 for (int hh = 0; hh < 8; ++hh) {
;                     f32x4 a = (f32x4){0.f, 0.f, 0.f, 0.f};
; #pragma unroll
;                     for (int ks = 0; ks < 2; ++ks) {
;                         const bf16x8 qv = *(const LAS bf16x8*)(lds + L_QI + q16 * 1024 + (((hh * 8 + 4 * ks + kg) ^ q16) << 4));
;                         a = __builtin_amdgcn_mfma_f32_16x16x32_bf16(kf[kb][ks], qv, a, 0, 0, 0);
;                     }
;                     const float wh = wl[hh * 16];
; #pragma unroll
;                     for (int i = 0; i < 4; ++i) s[i] += wh * fmaxf(a[i], 0.f);
;                 }
	v_mfma_f32_16x16x32_bf16 v[206:209], v[42:45], v[238:241], 0
	v_max_f32_e32 v9, 0, v246
	v_max_f32_e32 v200, 0, v247
	v_max_f32_e32 v201, 0, v248
	v_max_f32_e32 v216, 0, v249
	v_mfma_f32_16x16x32_bf16 v[210:213], v[50:53], v[238:241], 0
	v_mul_f32_e32 v118, v217, v9
	v_mul_f32_e32 v117, v217, v200
	v_mul_f32_e32 v120, v217, v201
	v_mul_f32_e32 v119, v217, v216
	v_mfma_f32_16x16x32_bf16 v[206:209], v[46:49], v[242:245], v[206:209]
	v_max_f32_e32 v9, 0, v250
	v_max_f32_e32 v200, 0, v251
	v_max_f32_e32 v201, 0, v252
	v_max_f32_e32 v216, 0, v253
	v_mfma_f32_16x16x32_bf16 v[210:213], v[2:5], v[242:245], v[210:213]
	v_mul_f32_e32 v122, v217, v9
	v_mul_f32_e32 v121, v217, v200
	v_mul_f32_e32 v124, v217, v201
	v_mul_f32_e32 v123, v217, v216
	ds_read_b128 v[238:241], v176
	ds_read_b128 v[242:245], v159
	ds_read_b32 v217, v137 offset:512
	s_waitcnt lgkmcnt(4)
	v_mfma_f32_16x16x32_bf16 v[246:249], v[42:45], v[230:233], 0
	v_max_f32_e32 v9, 0, v206
	v_max_f32_e32 v200, 0, v207
	v_max_f32_e32 v201, 0, v208
	v_max_f32_e32 v216, 0, v209
	v_mfma_f32_16x16x32_bf16 v[250:253], v[50:53], v[230:233], 0
	v_fmac_f32_e32 v118, v6, v9
	v_fmac_f32_e32 v117, v6, v200
	v_fmac_f32_e32 v120, v6, v201
	v_fmac_f32_e32 v119, v6, v216
	v_mfma_f32_16x16x32_bf16 v[246:249], v[46:49], v[234:237], v[246:249]
	v_max_f32_e32 v9, 0, v210
	v_max_f32_e32 v200, 0, v211
	v_max_f32_e32 v201, 0, v212
	v_max_f32_e32 v216, 0, v213
	v_mfma_f32_16x16x32_bf16 v[250:253], v[2:5], v[234:237], v[250:253]
	v_fmac_f32_e32 v122, v6, v9
	v_fmac_f32_e32 v121, v6, v200
	v_fmac_f32_e32 v124, v6, v201
	v_fmac_f32_e32 v123, v6, v216
	ds_read_b128 v[230:233], v158
	ds_read_b128 v[234:237], v157
	ds_read_b32 v6, v137 offset:576
	s_waitcnt lgkmcnt(4)
	v_mfma_f32_16x16x32_bf16 v[206:209], v[42:45], v[238:241], 0
	v_max_f32_e32 v9, 0, v246
	v_max_f32_e32 v200, 0, v247
	v_max_f32_e32 v201, 0, v248
	v_max_f32_e32 v216, 0, v249
	v_mfma_f32_16x16x32_bf16 v[210:213], v[50:53], v[238:241], 0
	v_fmac_f32_e32 v118, v7, v9
	v_fmac_f32_e32 v117, v7, v200
	v_fmac_f32_e32 v120, v7, v201
	v_fmac_f32_e32 v119, v7, v216
	v_mfma_f32_16x16x32_bf16 v[206:209], v[46:49], v[242:245], v[206:209]
	v_max_f32_e32 v9, 0, v250
	v_max_f32_e32 v200, 0, v251
	v_max_f32_e32 v201, 0, v252
	v_max_f32_e32 v216, 0, v253
	v_mfma_f32_16x16x32_bf16 v[210:213], v[2:5], v[242:245], v[210:213]
	v_fmac_f32_e32 v122, v7, v9
	v_fmac_f32_e32 v121, v7, v200
	v_fmac_f32_e32 v124, v7, v201
	v_fmac_f32_e32 v123, v7, v216
	ds_read_b128 v[238:241], v156
	ds_read_b128 v[242:245], v155
	ds_read_b32 v7, v137 offset:640
	s_waitcnt lgkmcnt(4)
	v_mfma_f32_16x16x32_bf16 v[246:249], v[42:45], v[230:233], 0
	v_max_f32_e32 v9, 0, v206
	v_max_f32_e32 v200, 0, v207
	v_max_f32_e32 v201, 0, v208
	v_max_f32_e32 v216, 0, v209
	v_mfma_f32_16x16x32_bf16 v[250:253], v[50:53], v[230:233], 0
	v_fmac_f32_e32 v118, v217, v9
	v_fmac_f32_e32 v117, v217, v200
	v_fmac_f32_e32 v120, v217, v201
	v_fmac_f32_e32 v119, v217, v216
	v_mfma_f32_16x16x32_bf16 v[246:249], v[46:49], v[234:237], v[246:249]
	v_max_f32_e32 v9, 0, v210
	v_max_f32_e32 v200, 0, v211
	v_max_f32_e32 v201, 0, v212
	v_max_f32_e32 v216, 0, v213
	v_mfma_f32_16x16x32_bf16 v[250:253], v[2:5], v[234:237], v[250:253]
	v_fmac_f32_e32 v122, v217, v9
	v_fmac_f32_e32 v121, v217, v200
	v_fmac_f32_e32 v124, v217, v201
	v_fmac_f32_e32 v123, v217, v216
	ds_read_b128 v[230:233], v154
	ds_read_b128 v[234:237], v153
	ds_read_b32 v217, v137 offset:704
	s_waitcnt lgkmcnt(4)
	v_mfma_f32_16x16x32_bf16 v[206:209], v[42:45], v[238:241], 0
	v_max_f32_e32 v9, 0, v246
	v_max_f32_e32 v200, 0, v247
	v_max_f32_e32 v201, 0, v248
	v_max_f32_e32 v216, 0, v249
	v_mfma_f32_16x16x32_bf16 v[210:213], v[50:53], v[238:241], 0
	v_fmac_f32_e32 v118, v6, v9
	v_fmac_f32_e32 v117, v6, v200
	v_fmac_f32_e32 v120, v6, v201
	v_fmac_f32_e32 v119, v6, v216
	v_mfma_f32_16x16x32_bf16 v[206:209], v[46:49], v[242:245], v[206:209]
	v_max_f32_e32 v9, 0, v250
	v_max_f32_e32 v200, 0, v251
	v_max_f32_e32 v201, 0, v252
	v_max_f32_e32 v216, 0, v253
	v_mfma_f32_16x16x32_bf16 v[210:213], v[2:5], v[242:245], v[210:213]
	v_fmac_f32_e32 v122, v6, v9
	v_fmac_f32_e32 v121, v6, v200
	v_fmac_f32_e32 v124, v6, v201
	v_fmac_f32_e32 v123, v6, v216
	ds_read_b128 v[238:241], v152
	ds_read_b128 v[242:245], v151
	ds_read_b32 v6, v137 offset:768
	s_waitcnt lgkmcnt(4)
	v_mfma_f32_16x16x32_bf16 v[246:249], v[42:45], v[230:233], 0
	v_max_f32_e32 v9, 0, v206
	v_max_f32_e32 v200, 0, v207
	v_max_f32_e32 v201, 0, v208
	v_max_f32_e32 v216, 0, v209
	v_mfma_f32_16x16x32_bf16 v[250:253], v[50:53], v[230:233], 0
	v_fmac_f32_e32 v118, v7, v9
	v_fmac_f32_e32 v117, v7, v200
	v_fmac_f32_e32 v120, v7, v201
	v_fmac_f32_e32 v119, v7, v216
	v_mfma_f32_16x16x32_bf16 v[246:249], v[46:49], v[234:237], v[246:249]
	v_max_f32_e32 v9, 0, v210
	v_max_f32_e32 v200, 0, v211
	v_max_f32_e32 v201, 0, v212
	v_max_f32_e32 v216, 0, v213
	v_mfma_f32_16x16x32_bf16 v[250:253], v[2:5], v[234:237], v[250:253]
	v_fmac_f32_e32 v122, v7, v9
	v_fmac_f32_e32 v121, v7, v200
	v_fmac_f32_e32 v124, v7, v201
	v_fmac_f32_e32 v123, v7, v216
	s_waitcnt lgkmcnt(1)
	v_mfma_f32_16x16x32_bf16 v[206:209], v[42:45], v[238:241], 0
	v_max_f32_e32 v9, 0, v246
	v_max_f32_e32 v200, 0, v247
	v_max_f32_e32 v201, 0, v248
	v_max_f32_e32 v216, 0, v249
	v_mfma_f32_16x16x32_bf16 v[210:213], v[50:53], v[238:241], 0
	v_fmac_f32_e32 v118, v217, v9
	v_fmac_f32_e32 v117, v217, v200
	v_fmac_f32_e32 v120, v217, v201
	v_fmac_f32_e32 v119, v217, v216
	v_mfma_f32_16x16x32_bf16 v[206:209], v[46:49], v[242:245], v[206:209]
	v_max_f32_e32 v9, 0, v250
	v_max_f32_e32 v200, 0, v251
	v_max_f32_e32 v201, 0, v252
	v_max_f32_e32 v216, 0, v253
	v_mfma_f32_16x16x32_bf16 v[210:213], v[2:5], v[242:245], v[210:213]
	v_fmac_f32_e32 v122, v217, v9
	v_fmac_f32_e32 v121, v217, v200
	v_fmac_f32_e32 v124, v217, v201
	v_fmac_f32_e32 v123, v217, v216
	s_waitcnt lgkmcnt(0)
; #define LAS __attribute__((address_space(3)))
; #define SEL_HADD(idx_) __hip_atomic_fetch_add(&hist[(idx_)], 1u, __ATOMIC_RELAXED, __HIP_MEMORY_SCOPE_WORKGROUP)
; __device__ __forceinline__ unsigned fkey(float f) { const unsigned u = __float_as_uint(f); return (u & 0x80000000u) ? ~u : (u | 0x80000000u); }
; __device__ __forceinline__ void sel_unit(LAS char* lds, int b, int u, const bf16_t* QI, const bf16_t* KIDX, const float* WIDX, unsigned long long* MASK) {
;     ...
;     for (int j = 0; j < 8; ++j) {
;         if (j < nj) {
;             int t = wid + 8 * j; asm volatile("" : "+s"(t));
; #pragma unroll
;             for (int kh = 0; kh < 2; ++kh) {
;             bf16x8 kf[2][2];
; #pragma unroll
;             for (int kb = 0; kb < 2; ++kb)
; #pragma unroll
;                 for (int ks = 0; ks < 2; ++ks) kf[kb][ks] = *(const bf16x8*)(KIDX + (rowbase + 64 * t + 32 * kh + 16 * kb + q16) * 64 + 32 * ks + 8 * kg);
; #pragma unroll
;             for (int kb = 0; kb < 2; ++kb) {
;                 f32x4 s = (f32x4){0.f, 0.f, 0.f, 0.f};
; #pragma unroll
;                 for (int hh = 0; hh < 8; ++hh) {
;                     f32x4 a = (f32x4){0.f, 0.f, 0.f, 0.f};
; #pragma unroll
;                     for (int ks = 0; ks < 2; ++ks) {
;                         const bf16x8 qv = *(const LAS bf16x8*)(lds + L_QI + q16 * 1024 + (((hh * 8 + 4 * ks + kg) ^ q16) << 4));
;                         a = __builtin_amdgcn_mfma_f32_16x16x32_bf16(kf[kb][ks], qv, a, 0, 0, 0);
;                     }
;                     const float wh = wl[hh * 16];
; #pragma unroll
;                     for (int i = 0; i < 4; ++i) s[i] += wh * fmaxf(a[i], 0.f);
;                 }
;                 u32x4 kk; kk.x = fkey(s[0]); kk.y = fkey(s[1]); kk.z = fkey(s[2]); kk.w = fkey(s[3]);
;                 sc[j][2 * kh + kb] = kk;
; #pragma unroll
;                 for (int i = 0; i < 4; ++i) SEL_HADD((kk[i] >> 24) * 16 + q16);
	v_max_f32_e32 v9, 0, v206
	v_max_f32_e32 v200, 0, v207
	v_max_f32_e32 v201, 0, v208
	v_max_f32_e32 v216, 0, v209
	v_fmac_f32_e32 v118, v6, v9
	v_fmac_f32_e32 v117, v6, v200
	v_fmac_f32_e32 v120, v6, v201
	v_fmac_f32_e32 v119, v6, v216
	v_max_f32_e32 v9, 0, v210
	v_max_f32_e32 v200, 0, v211
	v_max_f32_e32 v201, 0, v212
	v_max_f32_e32 v216, 0, v213
	v_fmac_f32_e32 v122, v6, v9
	v_fmac_f32_e32 v121, v6, v200
	v_fmac_f32_e32 v124, v6, v201
	v_fmac_f32_e32 v123, v6, v216
	v_ashrrev_i32_e32 v9, 31, v118
	v_bitop3_b32 v118, v9, v118, v8 bitop3:0x36
	v_ashrrev_i32_e32 v200, 31, v117
	v_bitop3_b32 v117, v200, v117, v8 bitop3:0x36
	v_ashrrev_i32_e32 v201, 31, v120
	v_bitop3_b32 v120, v201, v120, v8 bitop3:0x36
	v_ashrrev_i32_e32 v216, 31, v119
	v_bitop3_b32 v119, v216, v119, v8 bitop3:0x36
	v_ashrrev_i32_e32 v9, 31, v122
	v_bitop3_b32 v122, v9, v122, v8 bitop3:0x36
	v_ashrrev_i32_e32 v200, 31, v121
	v_bitop3_b32 v121, v200, v121, v8 bitop3:0x36
	v_ashrrev_i32_e32 v201, 31, v124
	v_bitop3_b32 v124, v201, v124, v8 bitop3:0x36
	v_ashrrev_i32_e32 v216, 31, v123
	v_bitop3_b32 v123, v216, v123, v8 bitop3:0x36
	v_lshrrev_b32_e32 v9, 24, v118
	v_lshl_add_u32 v9, v9, 6, v0
	ds_add_u32 v9, v205 offset:16384
	v_lshrrev_b32_e32 v200, 24, v117
	v_lshl_add_u32 v200, v200, 6, v0
	ds_add_u32 v200, v205 offset:16384
	v_lshrrev_b32_e32 v201, 24, v120
	v_lshl_add_u32 v201, v201, 6, v0
	ds_add_u32 v201, v205 offset:16384
	v_lshrrev_b32_e32 v216, 24, v119
	v_lshl_add_u32 v216, v216, 6, v0
	ds_add_u32 v216, v205 offset:16384
	v_lshrrev_b32_e32 v9, 24, v122
	v_lshl_add_u32 v9, v9, 6, v0
	ds_add_u32 v9, v205 offset:16384
	v_lshrrev_b32_e32 v200, 24, v121
	v_lshl_add_u32 v200, v200, 6, v0
	ds_add_u32 v200, v205 offset:16384
	v_lshrrev_b32_e32 v201, 24, v124
	v_lshl_add_u32 v201, v201, 6, v0
	ds_add_u32 v201, v205 offset:16384
	v_lshrrev_b32_e32 v216, 24, v123
	v_lshl_add_u32 v216, v216, 6, v0
	ds_add_u32 v216, v205 offset:16384
.LBB0_664:
	s_cmp_gt_i32 s4, 4
	s_cselect_b64 s[24:25], -1, 0
	s_cmp_lt_i32 s4, 5
	s_cbranch_scc1 .LBB0_666
	ds_read_b128 v[230:233], v182
	ds_read_b128 v[234:237], v183
	ds_read_b32 v6, v137 offset:320
	ds_read_b128 v[238:241], v184
	ds_read_b128 v[242:245], v185
	ds_read_b32 v7, v137 offset:384
	s_waitcnt vmcnt(0)
	v_add_co_u32_e32 v22, vcc, s96, v22
	s_nop 1
	v_addc_co_u32_e32 v23, vcc, 0, v23, vcc
	global_load_dwordx4 v[42:45], v[22:23], off
	global_load_dwordx4 v[46:49], v[22:23], off offset:64
	global_load_dwordx4 v[50:53], v[22:23], off offset:2048
	global_load_dwordx4 v[2:5], v[22:23], off offset:2112
	s_waitcnt lgkmcnt(4)
	v_mfma_f32_16x16x32_bf16 v[246:249], v[26:29], v[230:233], 0
	v_mfma_f32_16x16x32_bf16 v[250:253], v[34:37], v[230:233], 0
	v_mfma_f32_16x16x32_bf16 v[246:249], v[30:33], v[234:237], v[246:249]
	v_mfma_f32_16x16x32_bf16 v[250:253], v[38:41], v[234:237], v[250:253]
	ds_read_b128 v[230:233], v179
	ds_read_b128 v[234:237], v180
	ds_read_b32 v217, v137 offset:448
	s_waitcnt lgkmcnt(4)
	s_nop 1
	v_mfma_f32_16x16x32_bf16 v[206:209], v[26:29], v[238:241], 0
	v_max_f32_e32 v9, 0, v246
	v_max_f32_e32 v200, 0, v247
	v_max_f32_e32 v201, 0, v248
	v_max_f32_e32 v216, 0, v249
	v_mfma_f32_16x16x32_bf16 v[210:213], v[34:37], v[238:241], 0
	v_mul_f32_e32 v126, v6, v9
	v_mul_f32_e32 v125, v6, v200
	v_mul_f32_e32 v128, v6, v201
	v_mul_f32_e32 v127, v6, v216
	v_mfma_f32_16x16x32_bf16 v[206:209], v[30:33], v[242:245], v[206:209]
	v_max_f32_e32 v9, 0, v250
	v_max_f32_e32 v200, 0, v251
	v_max_f32_e32 v201, 0, v252
	v_max_f32_e32 v216, 0, v253
	v_mfma_f32_16x16x32_bf16 v[210:213], v[38:41], v[242:245], v[210:213]
	v_mul_f32_e32 v130, v6, v9
	v_mul_f32_e32 v129, v6, v200
	v_mul_f32_e32 v132, v6, v201
	v_mul_f32_e32 v131, v6, v216
	ds_read_b128 v[238:241], v176
	ds_read_b128 v[242:245], v159
	ds_read_b32 v6, v137 offset:512
	s_waitcnt lgkmcnt(4)
	v_mfma_f32_16x16x32_bf16 v[246:249], v[26:29], v[230:233], 0
	v_max_f32_e32 v9, 0, v206
	v_max_f32_e32 v200, 0, v207
	v_max_f32_e32 v201, 0, v208
	v_max_f32_e32 v216, 0, v209
	v_mfma_f32_16x16x32_bf16 v[250:253], v[34:37], v[230:233], 0
	v_fmac_f32_e32 v126, v7, v9
	v_fmac_f32_e32 v125, v7, v200
	v_fmac_f32_e32 v128, v7, v201
	v_fmac_f32_e32 v127, v7, v216
	v_mfma_f32_16x16x32_bf16 v[246:249], v[30:33], v[234:237], v[246:249]
	v_max_f32_e32 v9, 0, v210
	v_max_f32_e32 v200, 0, v211
	v_max_f32_e32 v201, 0, v212
	v_max_f32_e32 v216, 0, v213
	v_mfma_f32_16x16x32_bf16 v[250:253], v[38:41], v[234:237], v[250:253]
	v_fmac_f32_e32 v130, v7, v9
	v_fmac_f32_e32 v129, v7, v200
	v_fmac_f32_e32 v132, v7, v201
	v_fmac_f32_e32 v131, v7, v216
	ds_read_b128 v[230:233], v158
	ds_read_b128 v[234:237], v157
	ds_read_b32 v7, v137 offset:576
	s_waitcnt lgkmcnt(4)
	v_mfma_f32_16x16x32_bf16 v[206:209], v[26:29], v[238:241], 0
	v_max_f32_e32 v9, 0, v246
	v_max_f32_e32 v200, 0, v247
	v_max_f32_e32 v201, 0, v248
	v_max_f32_e32 v216, 0, v249
	v_mfma_f32_16x16x32_bf16 v[210:213], v[34:37], v[238:241], 0
	v_fmac_f32_e32 v126, v217, v9
	v_fmac_f32_e32 v125, v217, v200
	v_fmac_f32_e32 v128, v217, v201
	v_fmac_f32_e32 v127, v217, v216
	v_mfma_f32_16x16x32_bf16 v[206:209], v[30:33], v[242:245], v[206:209]
	v_max_f32_e32 v9, 0, v250
	v_max_f32_e32 v200, 0, v251
	v_max_f32_e32 v201, 0, v252
	v_max_f32_e32 v216, 0, v253
	v_mfma_f32_16x16x32_bf16 v[210:213], v[38:41], v[242:245], v[210:213]
	v_fmac_f32_e32 v130, v217, v9
	v_fmac_f32_e32 v129, v217, v200
	v_fmac_f32_e32 v132, v217, v201
	v_fmac_f32_e32 v131, v217, v216
	ds_read_b128 v[238:241], v156
	ds_read_b128 v[242:245], v155
	ds_read_b32 v217, v137 offset:640
	s_waitcnt lgkmcnt(4)
; #define LAS __attribute__((address_space(3)))
; #define SEL_HADD(idx_) __hip_atomic_fetch_add(&hist[(idx_)], 1u, __ATOMIC_RELAXED, __HIP_MEMORY_SCOPE_WORKGROUP)
; __device__ __forceinline__ unsigned fkey(float f) { const unsigned u = __float_as_uint(f); return (u & 0x80000000u) ? ~u : (u | 0x80000000u); }
; __device__ __forceinline__ void sel_unit(LAS char* lds, int b, int u, const bf16_t* QI, const bf16_t* KIDX, const float* WIDX, unsigned long long* MASK) {
;     ...
;     for (int j = 0; j < 8; ++j) {
;         if (j < nj) {
;             int t = wid + 8 * j; asm volatile("" : "+s"(t));
; #pragma unroll
;             for (int kh = 0; kh < 2; ++kh) {
;             bf16x8 kf[2][2];
; #pragma unroll
;             for (int kb = 0; kb < 2; ++kb)
; #pragma unroll
;                 for (int ks = 0; ks < 2; ++ks) kf[kb][ks] = *(const bf16x8*)(KIDX + (rowbase + 64 * t + 32 * kh + 16 * kb + q16) * 64 + 32 * ks + 8 * kg);
; #pragma unroll
;             for (int kb = 0; kb < 2; ++kb) {
;                 f32x4 s = (f32x4){0.f, 0.f, 0.f, 0.f};
; #pragma unroll
;                 for (int hh = 0; hh < 8; ++hh) {
;                     f32x4 a = (f32x4){0.f, 0.f, 0.f, 0.f};
; #pragma unroll
;                     for (int ks = 0; ks < 2; ++ks) {
;                         const bf16x8 qv = *(const LAS bf16x8*)(lds + L_QI + q16 * 1024 + (((hh * 8 + 4 * ks + kg) ^ q16) << 4));
;                         a = __builtin_amdgcn_mfma_f32_16x16x32_bf16(kf[kb][ks], qv, a, 0, 0, 0);
;                     }
;                     const float wh = wl[hh * 16];
; #pragma unroll
;                     for (int i = 0; i < 4; ++i) s[i] += wh * fmaxf(a[i], 0.f);
;                 }
;                 u32x4 kk; kk.x = fkey(s[0]); kk.y = fkey(s[1]); kk.z = fkey(s[2]); kk.w = fkey(s[3]);
;                 sc[j][2 * kh + kb] = kk;
; #pragma unroll
;                 for (int i = 0; i < 4; ++i) SEL_HADD((kk[i] >> 24) * 16 + q16);
	v_mfma_f32_16x16x32_bf16 v[246:249], v[26:29], v[230:233], 0
	v_max_f32_e32 v9, 0, v206
	v_max_f32_e32 v200, 0, v207
	v_max_f32_e32 v201, 0, v208
	v_max_f32_e32 v216, 0, v209
	v_mfma_f32_16x16x32_bf16 v[250:253], v[34:37], v[230:233], 0
	v_fmac_f32_e32 v126, v6, v9
	v_fmac_f32_e32 v125, v6, v200
	v_fmac_f32_e32 v128, v6, v201
	v_fmac_f32_e32 v127, v6, v216
	v_mfma_f32_16x16x32_bf16 v[246:249], v[30:33], v[234:237], v[246:249]
	v_max_f32_e32 v9, 0, v210
	v_max_f32_e32 v200, 0, v211
	v_max_f32_e32 v201, 0, v212
	v_max_f32_e32 v216, 0, v213
	v_mfma_f32_16x16x32_bf16 v[250:253], v[38:41], v[234:237], v[250:253]
	v_fmac_f32_e32 v130, v6, v9
	v_fmac_f32_e32 v129, v6, v200
	v_fmac_f32_e32 v132, v6, v201
	v_fmac_f32_e32 v131, v6, v216
	ds_read_b128 v[230:233], v154
	ds_read_b128 v[234:237], v153
	ds_read_b32 v6, v137 offset:704
	s_waitcnt lgkmcnt(4)
	v_mfma_f32_16x16x32_bf16 v[206:209], v[26:29], v[238:241], 0
	v_max_f32_e32 v9, 0, v246
	v_max_f32_e32 v200, 0, v247
	v_max_f32_e32 v201, 0, v248
	v_max_f32_e32 v216, 0, v249
	v_mfma_f32_16x16x32_bf16 v[210:213], v[34:37], v[238:241], 0
	v_fmac_f32_e32 v126, v7, v9
	v_fmac_f32_e32 v125, v7, v200
	v_fmac_f32_e32 v128, v7, v201
	v_fmac_f32_e32 v127, v7, v216
	v_mfma_f32_16x16x32_bf16 v[206:209], v[30:33], v[242:245], v[206:209]
	v_max_f32_e32 v9, 0, v250
	v_max_f32_e32 v200, 0, v251
	v_max_f32_e32 v201, 0, v252
	v_max_f32_e32 v216, 0, v253
	v_mfma_f32_16x16x32_bf16 v[210:213], v[38:41], v[242:245], v[210:213]
	v_fmac_f32_e32 v130, v7, v9
	v_fmac_f32_e32 v129, v7, v200
	v_fmac_f32_e32 v132, v7, v201
	v_fmac_f32_e32 v131, v7, v216
	ds_read_b128 v[238:241], v152
	ds_read_b128 v[242:245], v151
	ds_read_b32 v7, v137 offset:768
	s_waitcnt lgkmcnt(4)
	v_mfma_f32_16x16x32_bf16 v[246:249], v[26:29], v[230:233], 0
	v_max_f32_e32 v9, 0, v206
	v_max_f32_e32 v200, 0, v207
	v_max_f32_e32 v201, 0, v208
	v_max_f32_e32 v216, 0, v209
	v_mfma_f32_16x16x32_bf16 v[250:253], v[34:37], v[230:233], 0
	v_fmac_f32_e32 v126, v217, v9
	v_fmac_f32_e32 v125, v217, v200
	v_fmac_f32_e32 v128, v217, v201
	v_fmac_f32_e32 v127, v217, v216
	v_mfma_f32_16x16x32_bf16 v[246:249], v[30:33], v[234:237], v[246:249]
	v_max_f32_e32 v9, 0, v210
	v_max_f32_e32 v200, 0, v211
	v_max_f32_e32 v201, 0, v212
	v_max_f32_e32 v216, 0, v213
	v_mfma_f32_16x16x32_bf16 v[250:253], v[38:41], v[234:237], v[250:253]
	v_fmac_f32_e32 v130, v217, v9
	v_fmac_f32_e32 v129, v217, v200
	v_fmac_f32_e32 v132, v217, v201
	v_fmac_f32_e32 v131, v217, v216
	ds_read_b128 v[230:233], v182
	ds_read_b128 v[234:237], v183
	ds_read_b32 v217, v137 offset:320
	s_waitcnt lgkmcnt(4)
	v_mfma_f32_16x16x32_bf16 v[206:209], v[26:29], v[238:241], 0
	v_max_f32_e32 v9, 0, v246
	v_max_f32_e32 v200, 0, v247
	v_max_f32_e32 v201, 0, v248
	v_max_f32_e32 v216, 0, v249
	v_mfma_f32_16x16x32_bf16 v[210:213], v[34:37], v[238:241], 0
	v_fmac_f32_e32 v126, v6, v9
	v_fmac_f32_e32 v125, v6, v200
	v_fmac_f32_e32 v128, v6, v201
	v_fmac_f32_e32 v127, v6, v216
	v_mfma_f32_16x16x32_bf16 v[206:209], v[30:33], v[242:245], v[206:209]
	v_max_f32_e32 v9, 0, v250
	v_max_f32_e32 v200, 0, v251
	v_max_f32_e32 v201, 0, v252
	v_max_f32_e32 v216, 0, v253
	v_mfma_f32_16x16x32_bf16 v[210:213], v[38:41], v[242:245], v[210:213]
	v_fmac_f32_e32 v130, v6, v9
	v_fmac_f32_e32 v129, v6, v200
	v_fmac_f32_e32 v132, v6, v201
	v_fmac_f32_e32 v131, v6, v216
	ds_read_b128 v[238:241], v184
	ds_read_b128 v[242:245], v185
	ds_read_b32 v6, v137 offset:384
	s_waitcnt vmcnt(0)
	s_cmp_lt_i32 s4, 6
	s_cbranch_scc1 .Lp0_nopf_4
	v_add_co_u32_e32 v22, vcc, 0xf000, v22
	s_nop 1
	v_addc_co_u32_e32 v23, vcc, 0, v23, vcc
	global_load_dwordx4 v[26:29], v[22:23], off
	global_load_dwordx4 v[30:33], v[22:23], off offset:64
	global_load_dwordx4 v[34:37], v[22:23], off offset:2048
	global_load_dwordx4 v[38:41], v[22:23], off offset:2112
.Lp0_nopf_4:
	s_waitcnt lgkmcnt(4)
	v_mfma_f32_16x16x32_bf16 v[246:249], v[42:45], v[230:233], 0
	v_max_f32_e32 v9, 0, v206
	v_max_f32_e32 v200, 0, v207
	v_max_f32_e32 v201, 0, v208
	v_max_f32_e32 v216, 0, v209
	v_fmac_f32_e32 v126, v7, v9
	v_fmac_f32_e32 v125, v7, v200
	v_fmac_f32_e32 v128, v7, v201
	v_fmac_f32_e32 v127, v7, v216
	v_max_f32_e32 v9, 0, v210
	v_max_f32_e32 v200, 0, v211
	v_max_f32_e32 v201, 0, v212
	v_max_f32_e32 v216, 0, v213
	v_fmac_f32_e32 v130, v7, v9
	v_fmac_f32_e32 v129, v7, v200
	v_mfma_f32_16x16x32_bf16 v[250:253], v[50:53], v[230:233], 0
	v_fmac_f32_e32 v132, v7, v201
	v_fmac_f32_e32 v131, v7, v216
	v_ashrrev_i32_e32 v9, 31, v126
	v_bitop3_b32 v126, v9, v126, v8 bitop3:0x36
	v_ashrrev_i32_e32 v200, 31, v125
	v_bitop3_b32 v125, v200, v125, v8 bitop3:0x36
	v_ashrrev_i32_e32 v201, 31, v128
	v_bitop3_b32 v128, v201, v128, v8 bitop3:0x36
	v_ashrrev_i32_e32 v216, 31, v127
	v_bitop3_b32 v127, v216, v127, v8 bitop3:0x36
	v_ashrrev_i32_e32 v9, 31, v130
	v_bitop3_b32 v130, v9, v130, v8 bitop3:0x36
	v_ashrrev_i32_e32 v200, 31, v129
	v_bitop3_b32 v129, v200, v129, v8 bitop3:0x36
	v_mfma_f32_16x16x32_bf16 v[246:249], v[46:49], v[234:237], v[246:249]
	v_ashrrev_i32_e32 v201, 31, v132
	v_bitop3_b32 v132, v201, v132, v8 bitop3:0x36
	v_ashrrev_i32_e32 v216, 31, v131
	v_bitop3_b32 v131, v216, v131, v8 bitop3:0x36
	v_lshrrev_b32_e32 v9, 24, v126
	v_lshl_add_u32 v9, v9, 6, v0
	ds_add_u32 v9, v205 offset:16384
	v_lshrrev_b32_e32 v200, 24, v125
	v_lshl_add_u32 v200, v200, 6, v0
	ds_add_u32 v200, v205 offset:16384
	v_lshrrev_b32_e32 v201, 24, v128
	v_lshl_add_u32 v201, v201, 6, v0
	ds_add_u32 v201, v205 offset:16384
	v_lshrrev_b32_e32 v216, 24, v127
	v_mfma_f32_16x16x32_bf16 v[250:253], v[2:5], v[234:237], v[250:253]
	v_lshl_add_u32 v216, v216, 6, v0
	ds_add_u32 v216, v205 offset:16384
	v_lshrrev_b32_e32 v9, 24, v130
	v_lshl_add_u32 v9, v9, 6, v0
	ds_add_u32 v9, v205 offset:16384
	v_lshrrev_b32_e32 v200, 24, v129
	v_lshl_add_u32 v200, v200, 6, v0
	ds_add_u32 v200, v205 offset:16384
	v_lshrrev_b32_e32 v201, 24, v132
	v_lshl_add_u32 v201, v201, 6, v0
	ds_add_u32 v201, v205 offset:16384
	v_lshrrev_b32_e32 v216, 24, v131
	v_lshl_add_u32 v216, v216, 6, v0
	ds_add_u32 v216, v205 offset:16384
	ds_read_b128 v[230:233], v179
	ds_read_b128 v[234:237], v180
	ds_read_b32 v7, v137 offset:448
	s_waitcnt lgkmcnt(12)
; #define LAS __attribute__((address_space(3)))
; __device__ __forceinline__ void sel_unit(LAS char* lds, int b, int u, const bf16_t* QI, const bf16_t* KIDX, const float* WIDX, unsigned long long* MASK) {
;     ...
;     for (int j = 0; j < 8; ++j) {
;         if (j < nj) {
;             int t = wid + 8 * j; asm volatile("" : "+s"(t));
; #pragma unroll
;             for (int kh = 0; kh < 2; ++kh) {
;             bf16x8 kf[2][2];
; #pragma unroll
;             for (int kb = 0; kb < 2; ++kb)
; #pragma unroll
;                 for (int ks = 0; ks < 2; ++ks) kf[kb][ks] = *(const bf16x8*)(KIDX + (rowbase + 64 * t + 32 * kh + 16 * kb + q16) * 64 + 32 * ks + 8 * kg);
; #pragma unroll
;             for (int kb = 0; kb < 2; ++kb) {
;                 f32x4 s = (f32x4){0.f, 0.f, 0.f, 0.f};
; #pragma unroll
;                 for (int hh = 0; hh < 8; ++hh) {
;                     f32x4 a = (f32x4){0.f, 0.f, 0.f, 0.f};
; #pragma unroll
;                     for (int ks = 0; ks < 2; ++ks) {
;                         const bf16x8 qv = *(const LAS bf16x8*)(lds + L_QI + q16 * 1024 + (((hh * 8 + 4 * ks + kg) ^ q16) << 4));
;                         a = __builtin_amdgcn_mfma_f32_16x16x32_bf16(kf[kb][ks], qv, a, 0, 0, 0);
;                     }
;                     const float wh = wl[hh * 16];
; #pragma unroll
;                     for (int i = 0; i < 4; ++i) s[i] += wh * fmaxf(a[i], 0.f);
;                 }
	v_mfma_f32_16x16x32_bf16 v[206:209], v[42:45], v[238:241], 0
	v_max_f32_e32 v9, 0, v246
	v_max_f32_e32 v200, 0, v247
	v_max_f32_e32 v201, 0, v248
	v_max_f32_e32 v216, 0, v249
	v_mfma_f32_16x16x32_bf16 v[210:213], v[50:53], v[238:241], 0
	v_mul_f32_e32 v134, v217, v9
	v_mul_f32_e32 v133, v217, v200
	v_mul_f32_e32 v136, v217, v201
	v_mul_f32_e32 v135, v217, v216
	v_mfma_f32_16x16x32_bf16 v[206:209], v[46:49], v[242:245], v[206:209]
	v_max_f32_e32 v9, 0, v250
	v_max_f32_e32 v200, 0, v251
	v_max_f32_e32 v201, 0, v252
	v_max_f32_e32 v216, 0, v253
	v_mfma_f32_16x16x32_bf16 v[210:213], v[2:5], v[242:245], v[210:213]
	v_mul_f32_e32 v139, v217, v9
	v_mul_f32_e32 v138, v217, v200
	v_mul_f32_e32 v141, v217, v201
	v_mul_f32_e32 v140, v217, v216
	ds_read_b128 v[238:241], v176
	ds_read_b128 v[242:245], v159
	ds_read_b32 v217, v137 offset:512
	s_waitcnt lgkmcnt(4)
	v_mfma_f32_16x16x32_bf16 v[246:249], v[42:45], v[230:233], 0
	v_max_f32_e32 v9, 0, v206
	v_max_f32_e32 v200, 0, v207
	v_max_f32_e32 v201, 0, v208
	v_max_f32_e32 v216, 0, v209
	v_mfma_f32_16x16x32_bf16 v[250:253], v[50:53], v[230:233], 0
	v_fmac_f32_e32 v134, v6, v9
	v_fmac_f32_e32 v133, v6, v200
	v_fmac_f32_e32 v136, v6, v201
	v_fmac_f32_e32 v135, v6, v216
	v_mfma_f32_16x16x32_bf16 v[246:249], v[46:49], v[234:237], v[246:249]
	v_max_f32_e32 v9, 0, v210
	v_max_f32_e32 v200, 0, v211
	v_max_f32_e32 v201, 0, v212
	v_max_f32_e32 v216, 0, v213
	v_mfma_f32_16x16x32_bf16 v[250:253], v[2:5], v[234:237], v[250:253]
	v_fmac_f32_e32 v139, v6, v9
	v_fmac_f32_e32 v138, v6, v200
	v_fmac_f32_e32 v141, v6, v201
	v_fmac_f32_e32 v140, v6, v216
	ds_read_b128 v[230:233], v158
	ds_read_b128 v[234:237], v157
	ds_read_b32 v6, v137 offset:576
	s_waitcnt lgkmcnt(4)
	v_mfma_f32_16x16x32_bf16 v[206:209], v[42:45], v[238:241], 0
	v_max_f32_e32 v9, 0, v246
	v_max_f32_e32 v200, 0, v247
	v_max_f32_e32 v201, 0, v248
	v_max_f32_e32 v216, 0, v249
	v_mfma_f32_16x16x32_bf16 v[210:213], v[50:53], v[238:241], 0
	v_fmac_f32_e32 v134, v7, v9
	v_fmac_f32_e32 v133, v7, v200
	v_fmac_f32_e32 v136, v7, v201
	v_fmac_f32_e32 v135, v7, v216
	v_mfma_f32_16x16x32_bf16 v[206:209], v[46:49], v[242:245], v[206:209]
	v_max_f32_e32 v9, 0, v250
	v_max_f32_e32 v200, 0, v251
	v_max_f32_e32 v201, 0, v252
	v_max_f32_e32 v216, 0, v253
	v_mfma_f32_16x16x32_bf16 v[210:213], v[2:5], v[242:245], v[210:213]
	v_fmac_f32_e32 v139, v7, v9
	v_fmac_f32_e32 v138, v7, v200
	v_fmac_f32_e32 v141, v7, v201
	v_fmac_f32_e32 v140, v7, v216
	ds_read_b128 v[238:241], v156
	ds_read_b128 v[242:245], v155
	ds_read_b32 v7, v137 offset:640
	s_waitcnt lgkmcnt(4)
	v_mfma_f32_16x16x32_bf16 v[246:249], v[42:45], v[230:233], 0
	v_max_f32_e32 v9, 0, v206
	v_max_f32_e32 v200, 0, v207
	v_max_f32_e32 v201, 0, v208
	v_max_f32_e32 v216, 0, v209
	v_mfma_f32_16x16x32_bf16 v[250:253], v[50:53], v[230:233], 0
	v_fmac_f32_e32 v134, v217, v9
	v_fmac_f32_e32 v133, v217, v200
	v_fmac_f32_e32 v136, v217, v201
	v_fmac_f32_e32 v135, v217, v216
	v_mfma_f32_16x16x32_bf16 v[246:249], v[46:49], v[234:237], v[246:249]
	v_max_f32_e32 v9, 0, v210
	v_max_f32_e32 v200, 0, v211
	v_max_f32_e32 v201, 0, v212
	v_max_f32_e32 v216, 0, v213
	v_mfma_f32_16x16x32_bf16 v[250:253], v[2:5], v[234:237], v[250:253]
	v_fmac_f32_e32 v139, v217, v9
	v_fmac_f32_e32 v138, v217, v200
	v_fmac_f32_e32 v141, v217, v201
	v_fmac_f32_e32 v140, v217, v216
	ds_read_b128 v[230:233], v154
	ds_read_b128 v[234:237], v153
	ds_read_b32 v217, v137 offset:704
	s_waitcnt lgkmcnt(4)
	v_mfma_f32_16x16x32_bf16 v[206:209], v[42:45], v[238:241], 0
	v_max_f32_e32 v9, 0, v246
	v_max_f32_e32 v200, 0, v247
	v_max_f32_e32 v201, 0, v248
	v_max_f32_e32 v216, 0, v249
	v_mfma_f32_16x16x32_bf16 v[210:213], v[50:53], v[238:241], 0
	v_fmac_f32_e32 v134, v6, v9
	v_fmac_f32_e32 v133, v6, v200
	v_fmac_f32_e32 v136, v6, v201
	v_fmac_f32_e32 v135, v6, v216
	v_mfma_f32_16x16x32_bf16 v[206:209], v[46:49], v[242:245], v[206:209]
	v_max_f32_e32 v9, 0, v250
	v_max_f32_e32 v200, 0, v251
	v_max_f32_e32 v201, 0, v252
	v_max_f32_e32 v216, 0, v253
	v_mfma_f32_16x16x32_bf16 v[210:213], v[2:5], v[242:245], v[210:213]
	v_fmac_f32_e32 v139, v6, v9
	v_fmac_f32_e32 v138, v6, v200
	v_fmac_f32_e32 v141, v6, v201
	v_fmac_f32_e32 v140, v6, v216
	ds_read_b128 v[238:241], v152
	ds_read_b128 v[242:245], v151
	ds_read_b32 v6, v137 offset:768
	s_waitcnt lgkmcnt(4)
	v_mfma_f32_16x16x32_bf16 v[246:249], v[42:45], v[230:233], 0
	v_max_f32_e32 v9, 0, v206
	v_max_f32_e32 v200, 0, v207
	v_max_f32_e32 v201, 0, v208
	v_max_f32_e32 v216, 0, v209
	v_mfma_f32_16x16x32_bf16 v[250:253], v[50:53], v[230:233], 0
	v_fmac_f32_e32 v134, v7, v9
	v_fmac_f32_e32 v133, v7, v200
	v_fmac_f32_e32 v136, v7, v201
	v_fmac_f32_e32 v135, v7, v216
	v_mfma_f32_16x16x32_bf16 v[246:249], v[46:49], v[234:237], v[246:249]
	v_max_f32_e32 v9, 0, v210
	v_max_f32_e32 v200, 0, v211
	v_max_f32_e32 v201, 0, v212
	v_max_f32_e32 v216, 0, v213
	v_mfma_f32_16x16x32_bf16 v[250:253], v[2:5], v[234:237], v[250:253]
	v_fmac_f32_e32 v139, v7, v9
	v_fmac_f32_e32 v138, v7, v200
	v_fmac_f32_e32 v141, v7, v201
	v_fmac_f32_e32 v140, v7, v216
	s_waitcnt lgkmcnt(1)
	v_mfma_f32_16x16x32_bf16 v[206:209], v[42:45], v[238:241], 0
	v_max_f32_e32 v9, 0, v246
	v_max_f32_e32 v200, 0, v247
	v_max_f32_e32 v201, 0, v248
	v_max_f32_e32 v216, 0, v249
	v_mfma_f32_16x16x32_bf16 v[210:213], v[50:53], v[238:241], 0
	v_fmac_f32_e32 v134, v217, v9
	v_fmac_f32_e32 v133, v217, v200
	v_fmac_f32_e32 v136, v217, v201
	v_fmac_f32_e32 v135, v217, v216
	v_mfma_f32_16x16x32_bf16 v[206:209], v[46:49], v[242:245], v[206:209]
	v_max_f32_e32 v9, 0, v250
	v_max_f32_e32 v200, 0, v251
	v_max_f32_e32 v201, 0, v252
	v_max_f32_e32 v216, 0, v253
	v_mfma_f32_16x16x32_bf16 v[210:213], v[2:5], v[242:245], v[210:213]
	v_fmac_f32_e32 v139, v217, v9
	v_fmac_f32_e32 v138, v217, v200
	v_fmac_f32_e32 v141, v217, v201
	v_fmac_f32_e32 v140, v217, v216
	s_waitcnt lgkmcnt(0)
; #define LAS __attribute__((address_space(3)))
; #define SEL_HADD(idx_) __hip_atomic_fetch_add(&hist[(idx_)], 1u, __ATOMIC_RELAXED, __HIP_MEMORY_SCOPE_WORKGROUP)
; __device__ __forceinline__ unsigned fkey(float f) { const unsigned u = __float_as_uint(f); return (u & 0x80000000u) ? ~u : (u | 0x80000000u); }
; __device__ __forceinline__ void sel_unit(LAS char* lds, int b, int u, const bf16_t* QI, const bf16_t* KIDX, const float* WIDX, unsigned long long* MASK) {
;     ...
;     for (int j = 0; j < 8; ++j) {
;         if (j < nj) {
;             int t = wid + 8 * j; asm volatile("" : "+s"(t));
; #pragma unroll
;             for (int kh = 0; kh < 2; ++kh) {
;             bf16x8 kf[2][2];
; #pragma unroll
;             for (int kb = 0; kb < 2; ++kb)
; #pragma unroll
;                 for (int ks = 0; ks < 2; ++ks) kf[kb][ks] = *(const bf16x8*)(KIDX + (rowbase + 64 * t + 32 * kh + 16 * kb + q16) * 64 + 32 * ks + 8 * kg);
; #pragma unroll
;             for (int kb = 0; kb < 2; ++kb) {
;                 f32x4 s = (f32x4){0.f, 0.f, 0.f, 0.f};
; #pragma unroll
;                 for (int hh = 0; hh < 8; ++hh) {
;                     f32x4 a = (f32x4){0.f, 0.f, 0.f, 0.f};
; #pragma unroll
;                     for (int ks = 0; ks < 2; ++ks) {
;                         const bf16x8 qv = *(const LAS bf16x8*)(lds + L_QI + q16 * 1024 + (((hh * 8 + 4 * ks + kg) ^ q16) << 4));
;                         a = __builtin_amdgcn_mfma_f32_16x16x32_bf16(kf[kb][ks], qv, a, 0, 0, 0);
;                     }
;                     const float wh = wl[hh * 16];
; #pragma unroll
;                     for (int i = 0; i < 4; ++i) s[i] += wh * fmaxf(a[i], 0.f);
;                 }
;                 u32x4 kk; kk.x = fkey(s[0]); kk.y = fkey(s[1]); kk.z = fkey(s[2]); kk.w = fkey(s[3]);
;                 sc[j][2 * kh + kb] = kk;
; #pragma unroll
;                 for (int i = 0; i < 4; ++i) SEL_HADD((kk[i] >> 24) * 16 + q16);
	v_max_f32_e32 v9, 0, v206
	v_max_f32_e32 v200, 0, v207
	v_max_f32_e32 v201, 0, v208
	v_max_f32_e32 v216, 0, v209
	v_fmac_f32_e32 v134, v6, v9
	v_fmac_f32_e32 v133, v6, v200
	v_fmac_f32_e32 v136, v6, v201
	v_fmac_f32_e32 v135, v6, v216
	v_max_f32_e32 v9, 0, v210
	v_max_f32_e32 v200, 0, v211
	v_max_f32_e32 v201, 0, v212
	v_max_f32_e32 v216, 0, v213
	v_fmac_f32_e32 v139, v6, v9
	v_fmac_f32_e32 v138, v6, v200
	v_fmac_f32_e32 v141, v6, v201
	v_fmac_f32_e32 v140, v6, v216
	v_ashrrev_i32_e32 v9, 31, v134
	v_bitop3_b32 v134, v9, v134, v8 bitop3:0x36
	v_ashrrev_i32_e32 v200, 31, v133
	v_bitop3_b32 v133, v200, v133, v8 bitop3:0x36
	v_ashrrev_i32_e32 v201, 31, v136
	v_bitop3_b32 v136, v201, v136, v8 bitop3:0x36
	v_ashrrev_i32_e32 v216, 31, v135
	v_bitop3_b32 v135, v216, v135, v8 bitop3:0x36
	v_ashrrev_i32_e32 v9, 31, v139
	v_bitop3_b32 v139, v9, v139, v8 bitop3:0x36
	v_ashrrev_i32_e32 v200, 31, v138
	v_bitop3_b32 v138, v200, v138, v8 bitop3:0x36
	v_ashrrev_i32_e32 v201, 31, v141
	v_bitop3_b32 v141, v201, v141, v8 bitop3:0x36
	v_ashrrev_i32_e32 v216, 31, v140
	v_bitop3_b32 v140, v216, v140, v8 bitop3:0x36
	v_lshrrev_b32_e32 v9, 24, v134
	v_lshl_add_u32 v9, v9, 6, v0
	ds_add_u32 v9, v205 offset:16384
	v_lshrrev_b32_e32 v200, 24, v133
	v_lshl_add_u32 v200, v200, 6, v0
	ds_add_u32 v200, v205 offset:16384
	v_lshrrev_b32_e32 v201, 24, v136
	v_lshl_add_u32 v201, v201, 6, v0
	ds_add_u32 v201, v205 offset:16384
	v_lshrrev_b32_e32 v216, 24, v135
	v_lshl_add_u32 v216, v216, 6, v0
	ds_add_u32 v216, v205 offset:16384
	v_lshrrev_b32_e32 v9, 24, v139
	v_lshl_add_u32 v9, v9, 6, v0
	ds_add_u32 v9, v205 offset:16384
	v_lshrrev_b32_e32 v200, 24, v138
	v_lshl_add_u32 v200, v200, 6, v0
	ds_add_u32 v200, v205 offset:16384
	v_lshrrev_b32_e32 v201, 24, v141
	v_lshl_add_u32 v201, v201, 6, v0
	ds_add_u32 v201, v205 offset:16384
	v_lshrrev_b32_e32 v216, 24, v140
	v_lshl_add_u32 v216, v216, 6, v0
	ds_add_u32 v216, v205 offset:16384
.LBB0_666:
	s_cmp_gt_i32 s4, 5
	s_cselect_b64 s[48:49], -1, 0
	s_cmp_lt_i32 s4, 6
	s_cbranch_scc1 .LBB0_668
	ds_read_b128 v[230:233], v182
	ds_read_b128 v[234:237], v183
	ds_read_b32 v6, v137 offset:320
	ds_read_b128 v[238:241], v184
	ds_read_b128 v[242:245], v185
	ds_read_b32 v7, v137 offset:384
	s_waitcnt vmcnt(0)
	v_add_co_u32_e32 v22, vcc, s96, v22
	s_nop 1
	v_addc_co_u32_e32 v23, vcc, 0, v23, vcc
	global_load_dwordx4 v[42:45], v[22:23], off
	global_load_dwordx4 v[46:49], v[22:23], off offset:64
	global_load_dwordx4 v[50:53], v[22:23], off offset:2048
	global_load_dwordx4 v[2:5], v[22:23], off offset:2112
	s_waitcnt lgkmcnt(4)
	v_mfma_f32_16x16x32_bf16 v[246:249], v[26:29], v[230:233], 0
	v_mfma_f32_16x16x32_bf16 v[250:253], v[34:37], v[230:233], 0
	v_mfma_f32_16x16x32_bf16 v[246:249], v[30:33], v[234:237], v[246:249]
	v_mfma_f32_16x16x32_bf16 v[250:253], v[38:41], v[234:237], v[250:253]
	ds_read_b128 v[230:233], v179
	ds_read_b128 v[234:237], v180
	ds_read_b32 v217, v137 offset:448
	s_waitcnt lgkmcnt(4)
	s_nop 1
	v_mfma_f32_16x16x32_bf16 v[206:209], v[26:29], v[238:241], 0
	v_max_f32_e32 v9, 0, v246
	v_max_f32_e32 v200, 0, v247
	v_max_f32_e32 v201, 0, v248
	v_max_f32_e32 v216, 0, v249
	v_mfma_f32_16x16x32_bf16 v[210:213], v[34:37], v[238:241], 0
	v_mul_f32_e32 v143, v6, v9
	v_mul_f32_e32 v142, v6, v200
	v_mul_f32_e32 v145, v6, v201
	v_mul_f32_e32 v144, v6, v216
	v_mfma_f32_16x16x32_bf16 v[206:209], v[30:33], v[242:245], v[206:209]
	v_max_f32_e32 v9, 0, v250
	v_max_f32_e32 v200, 0, v251
	v_max_f32_e32 v201, 0, v252
	v_max_f32_e32 v216, 0, v253
	v_mfma_f32_16x16x32_bf16 v[210:213], v[38:41], v[242:245], v[210:213]
	v_mul_f32_e32 v147, v6, v9
	v_mul_f32_e32 v146, v6, v200
	v_mul_f32_e32 v149, v6, v201
	v_mul_f32_e32 v148, v6, v216
	ds_read_b128 v[238:241], v176
	ds_read_b128 v[242:245], v159
	ds_read_b32 v6, v137 offset:512
	s_waitcnt lgkmcnt(4)
	v_mfma_f32_16x16x32_bf16 v[246:249], v[26:29], v[230:233], 0
	v_max_f32_e32 v9, 0, v206
	v_max_f32_e32 v200, 0, v207
	v_max_f32_e32 v201, 0, v208
	v_max_f32_e32 v216, 0, v209
	v_mfma_f32_16x16x32_bf16 v[250:253], v[34:37], v[230:233], 0
	v_fmac_f32_e32 v143, v7, v9
	v_fmac_f32_e32 v142, v7, v200
	v_fmac_f32_e32 v145, v7, v201
	v_fmac_f32_e32 v144, v7, v216
	v_mfma_f32_16x16x32_bf16 v[246:249], v[30:33], v[234:237], v[246:249]
	v_max_f32_e32 v9, 0, v210
	v_max_f32_e32 v200, 0, v211
	v_max_f32_e32 v201, 0, v212
	v_max_f32_e32 v216, 0, v213
	v_mfma_f32_16x16x32_bf16 v[250:253], v[38:41], v[234:237], v[250:253]
	v_fmac_f32_e32 v147, v7, v9
	v_fmac_f32_e32 v146, v7, v200
	v_fmac_f32_e32 v149, v7, v201
	v_fmac_f32_e32 v148, v7, v216
	ds_read_b128 v[230:233], v158
	ds_read_b128 v[234:237], v157
	ds_read_b32 v7, v137 offset:576
	s_waitcnt lgkmcnt(4)
	v_mfma_f32_16x16x32_bf16 v[206:209], v[26:29], v[238:241], 0
	v_max_f32_e32 v9, 0, v246
	v_max_f32_e32 v200, 0, v247
	v_max_f32_e32 v201, 0, v248
	v_max_f32_e32 v216, 0, v249
	v_mfma_f32_16x16x32_bf16 v[210:213], v[34:37], v[238:241], 0
	v_fmac_f32_e32 v143, v217, v9
	v_fmac_f32_e32 v142, v217, v200
	v_fmac_f32_e32 v145, v217, v201
	v_fmac_f32_e32 v144, v217, v216
	v_mfma_f32_16x16x32_bf16 v[206:209], v[30:33], v[242:245], v[206:209]
	v_max_f32_e32 v9, 0, v250
	v_max_f32_e32 v200, 0, v251
	v_max_f32_e32 v201, 0, v252
	v_max_f32_e32 v216, 0, v253
	v_mfma_f32_16x16x32_bf16 v[210:213], v[38:41], v[242:245], v[210:213]
	v_fmac_f32_e32 v147, v217, v9
	v_fmac_f32_e32 v146, v217, v200
	v_fmac_f32_e32 v149, v217, v201
	v_fmac_f32_e32 v148, v217, v216
	ds_read_b128 v[238:241], v156
	ds_read_b128 v[242:245], v155
	ds_read_b32 v217, v137 offset:640
	s_waitcnt lgkmcnt(4)
; #define LAS __attribute__((address_space(3)))
; #define SEL_HADD(idx_) __hip_atomic_fetch_add(&hist[(idx_)], 1u, __ATOMIC_RELAXED, __HIP_MEMORY_SCOPE_WORKGROUP)
; __device__ __forceinline__ unsigned fkey(float f) { const unsigned u = __float_as_uint(f); return (u & 0x80000000u) ? ~u : (u | 0x80000000u); }
; __device__ __forceinline__ void sel_unit(LAS char* lds, int b, int u, const bf16_t* QI, const bf16_t* KIDX, const float* WIDX, unsigned long long* MASK) {
;     ...
;     for (int j = 0; j < 8; ++j) {
;         if (j < nj) {
;             int t = wid + 8 * j; asm volatile("" : "+s"(t));
; #pragma unroll
;             for (int kh = 0; kh < 2; ++kh) {
;             bf16x8 kf[2][2];
; #pragma unroll
;             for (int kb = 0; kb < 2; ++kb)
; #pragma unroll
;                 for (int ks = 0; ks < 2; ++ks) kf[kb][ks] = *(const bf16x8*)(KIDX + (rowbase + 64 * t + 32 * kh + 16 * kb + q16) * 64 + 32 * ks + 8 * kg);
; #pragma unroll
;             for (int kb = 0; kb < 2; ++kb) {
;                 f32x4 s = (f32x4){0.f, 0.f, 0.f, 0.f};
; #pragma unroll
;                 for (int hh = 0; hh < 8; ++hh) {
;                     f32x4 a = (f32x4){0.f, 0.f, 0.f, 0.f};
; #pragma unroll
;                     for (int ks = 0; ks < 2; ++ks) {
;                         const bf16x8 qv = *(const LAS bf16x8*)(lds + L_QI + q16 * 1024 + (((hh * 8 + 4 * ks + kg) ^ q16) << 4));
;                         a = __builtin_amdgcn_mfma_f32_16x16x32_bf16(kf[kb][ks], qv, a, 0, 0, 0);
;                     }
;                     const float wh = wl[hh * 16];
; #pragma unroll
;                     for (int i = 0; i < 4; ++i) s[i] += wh * fmaxf(a[i], 0.f);
;                 }
;                 u32x4 kk; kk.x = fkey(s[0]); kk.y = fkey(s[1]); kk.z = fkey(s[2]); kk.w = fkey(s[3]);
;                 sc[j][2 * kh + kb] = kk;
; #pragma unroll
;                 for (int i = 0; i < 4; ++i) SEL_HADD((kk[i] >> 24) * 16 + q16);
	v_mfma_f32_16x16x32_bf16 v[246:249], v[26:29], v[230:233], 0
	v_max_f32_e32 v9, 0, v206
	v_max_f32_e32 v200, 0, v207
	v_max_f32_e32 v201, 0, v208
	v_max_f32_e32 v216, 0, v209
	v_mfma_f32_16x16x32_bf16 v[250:253], v[34:37], v[230:233], 0
	v_fmac_f32_e32 v143, v6, v9
	v_fmac_f32_e32 v142, v6, v200
	v_fmac_f32_e32 v145, v6, v201
	v_fmac_f32_e32 v144, v6, v216
	v_mfma_f32_16x16x32_bf16 v[246:249], v[30:33], v[234:237], v[246:249]
	v_max_f32_e32 v9, 0, v210
	v_max_f32_e32 v200, 0, v211
	v_max_f32_e32 v201, 0, v212
	v_max_f32_e32 v216, 0, v213
	v_mfma_f32_16x16x32_bf16 v[250:253], v[38:41], v[234:237], v[250:253]
	v_fmac_f32_e32 v147, v6, v9
	v_fmac_f32_e32 v146, v6, v200
	v_fmac_f32_e32 v149, v6, v201
	v_fmac_f32_e32 v148, v6, v216
	ds_read_b128 v[230:233], v154
	ds_read_b128 v[234:237], v153
	ds_read_b32 v6, v137 offset:704
	s_waitcnt lgkmcnt(4)
	v_mfma_f32_16x16x32_bf16 v[206:209], v[26:29], v[238:241], 0
	v_max_f32_e32 v9, 0, v246
	v_max_f32_e32 v200, 0, v247
	v_max_f32_e32 v201, 0, v248
	v_max_f32_e32 v216, 0, v249
	v_mfma_f32_16x16x32_bf16 v[210:213], v[34:37], v[238:241], 0
	v_fmac_f32_e32 v143, v7, v9
	v_fmac_f32_e32 v142, v7, v200
	v_fmac_f32_e32 v145, v7, v201
	v_fmac_f32_e32 v144, v7, v216
	v_mfma_f32_16x16x32_bf16 v[206:209], v[30:33], v[242:245], v[206:209]
	v_max_f32_e32 v9, 0, v250
	v_max_f32_e32 v200, 0, v251
	v_max_f32_e32 v201, 0, v252
	v_max_f32_e32 v216, 0, v253
	v_mfma_f32_16x16x32_bf16 v[210:213], v[38:41], v[242:245], v[210:213]
	v_fmac_f32_e32 v147, v7, v9
	v_fmac_f32_e32 v146, v7, v200
	v_fmac_f32_e32 v149, v7, v201
	v_fmac_f32_e32 v148, v7, v216
	ds_read_b128 v[238:241], v152
	ds_read_b128 v[242:245], v151
	ds_read_b32 v7, v137 offset:768
	s_waitcnt lgkmcnt(4)
	v_mfma_f32_16x16x32_bf16 v[246:249], v[26:29], v[230:233], 0
	v_max_f32_e32 v9, 0, v206
	v_max_f32_e32 v200, 0, v207
	v_max_f32_e32 v201, 0, v208
	v_max_f32_e32 v216, 0, v209
	v_mfma_f32_16x16x32_bf16 v[250:253], v[34:37], v[230:233], 0
	v_fmac_f32_e32 v143, v217, v9
	v_fmac_f32_e32 v142, v217, v200
	v_fmac_f32_e32 v145, v217, v201
	v_fmac_f32_e32 v144, v217, v216
	v_mfma_f32_16x16x32_bf16 v[246:249], v[30:33], v[234:237], v[246:249]
	v_max_f32_e32 v9, 0, v210
	v_max_f32_e32 v200, 0, v211
	v_max_f32_e32 v201, 0, v212
	v_max_f32_e32 v216, 0, v213
	v_mfma_f32_16x16x32_bf16 v[250:253], v[38:41], v[234:237], v[250:253]
	v_fmac_f32_e32 v147, v217, v9
	v_fmac_f32_e32 v146, v217, v200
	v_fmac_f32_e32 v149, v217, v201
	v_fmac_f32_e32 v148, v217, v216
	ds_read_b128 v[230:233], v182
	ds_read_b128 v[234:237], v183
	ds_read_b32 v217, v137 offset:320
	s_waitcnt lgkmcnt(4)
	v_mfma_f32_16x16x32_bf16 v[206:209], v[26:29], v[238:241], 0
	v_max_f32_e32 v9, 0, v246
	v_max_f32_e32 v200, 0, v247
	v_max_f32_e32 v201, 0, v248
	v_max_f32_e32 v216, 0, v249
	v_mfma_f32_16x16x32_bf16 v[210:213], v[34:37], v[238:241], 0
	v_fmac_f32_e32 v143, v6, v9
	v_fmac_f32_e32 v142, v6, v200
	v_fmac_f32_e32 v145, v6, v201
	v_fmac_f32_e32 v144, v6, v216
	v_mfma_f32_16x16x32_bf16 v[206:209], v[30:33], v[242:245], v[206:209]
	v_max_f32_e32 v9, 0, v250
	v_max_f32_e32 v200, 0, v251
	v_max_f32_e32 v201, 0, v252
	v_max_f32_e32 v216, 0, v253
	v_mfma_f32_16x16x32_bf16 v[210:213], v[38:41], v[242:245], v[210:213]
	v_fmac_f32_e32 v147, v6, v9
	v_fmac_f32_e32 v146, v6, v200
	v_fmac_f32_e32 v149, v6, v201
	v_fmac_f32_e32 v148, v6, v216
	ds_read_b128 v[238:241], v184
	ds_read_b128 v[242:245], v185
	ds_read_b32 v6, v137 offset:384
	s_waitcnt vmcnt(0)
	s_cmp_lt_i32 s4, 7
	s_cbranch_scc1 .Lp0_nopf_5
	v_add_co_u32_e32 v22, vcc, 0xf000, v22
	s_nop 1
	v_addc_co_u32_e32 v23, vcc, 0, v23, vcc
	global_load_dwordx4 v[26:29], v[22:23], off
	global_load_dwordx4 v[30:33], v[22:23], off offset:64
	global_load_dwordx4 v[34:37], v[22:23], off offset:2048
	global_load_dwordx4 v[38:41], v[22:23], off offset:2112
.Lp0_nopf_5:
	s_waitcnt lgkmcnt(4)
	v_mfma_f32_16x16x32_bf16 v[246:249], v[42:45], v[230:233], 0
	v_max_f32_e32 v9, 0, v206
	v_max_f32_e32 v200, 0, v207
	v_max_f32_e32 v201, 0, v208
	v_max_f32_e32 v216, 0, v209
	v_fmac_f32_e32 v143, v7, v9
	v_fmac_f32_e32 v142, v7, v200
	v_fmac_f32_e32 v145, v7, v201
	v_fmac_f32_e32 v144, v7, v216
	v_max_f32_e32 v9, 0, v210
	v_max_f32_e32 v200, 0, v211
	v_max_f32_e32 v201, 0, v212
	v_max_f32_e32 v216, 0, v213
	v_fmac_f32_e32 v147, v7, v9
	v_fmac_f32_e32 v146, v7, v200
	v_mfma_f32_16x16x32_bf16 v[250:253], v[50:53], v[230:233], 0
	v_fmac_f32_e32 v149, v7, v201
	v_fmac_f32_e32 v148, v7, v216
	v_ashrrev_i32_e32 v9, 31, v143
	v_bitop3_b32 v143, v9, v143, v8 bitop3:0x36
	v_ashrrev_i32_e32 v200, 31, v142
	v_bitop3_b32 v142, v200, v142, v8 bitop3:0x36
	v_ashrrev_i32_e32 v201, 31, v145
	v_bitop3_b32 v145, v201, v145, v8 bitop3:0x36
	v_ashrrev_i32_e32 v216, 31, v144
	v_bitop3_b32 v144, v216, v144, v8 bitop3:0x36
	v_ashrrev_i32_e32 v9, 31, v147
	v_bitop3_b32 v147, v9, v147, v8 bitop3:0x36
	v_ashrrev_i32_e32 v200, 31, v146
	v_bitop3_b32 v146, v200, v146, v8 bitop3:0x36
	v_mfma_f32_16x16x32_bf16 v[246:249], v[46:49], v[234:237], v[246:249]
	v_ashrrev_i32_e32 v201, 31, v149
	v_bitop3_b32 v149, v201, v149, v8 bitop3:0x36
	v_ashrrev_i32_e32 v216, 31, v148
	v_bitop3_b32 v148, v216, v148, v8 bitop3:0x36
	v_lshrrev_b32_e32 v9, 24, v143
	v_lshl_add_u32 v9, v9, 6, v0
	ds_add_u32 v9, v205 offset:16384
	v_lshrrev_b32_e32 v200, 24, v142
	v_lshl_add_u32 v200, v200, 6, v0
	ds_add_u32 v200, v205 offset:16384
	v_lshrrev_b32_e32 v201, 24, v145
	v_lshl_add_u32 v201, v201, 6, v0
	ds_add_u32 v201, v205 offset:16384
	v_lshrrev_b32_e32 v216, 24, v144
	v_mfma_f32_16x16x32_bf16 v[250:253], v[2:5], v[234:237], v[250:253]
	v_lshl_add_u32 v216, v216, 6, v0
	ds_add_u32 v216, v205 offset:16384
	v_lshrrev_b32_e32 v9, 24, v147
	v_lshl_add_u32 v9, v9, 6, v0
	ds_add_u32 v9, v205 offset:16384
	v_lshrrev_b32_e32 v200, 24, v146
	v_lshl_add_u32 v200, v200, 6, v0
	ds_add_u32 v200, v205 offset:16384
	v_lshrrev_b32_e32 v201, 24, v149
	v_lshl_add_u32 v201, v201, 6, v0
	ds_add_u32 v201, v205 offset:16384
	v_lshrrev_b32_e32 v216, 24, v148
	v_lshl_add_u32 v216, v216, 6, v0
	ds_add_u32 v216, v205 offset:16384
	ds_read_b128 v[230:233], v179
	ds_read_b128 v[234:237], v180
	ds_read_b32 v7, v137 offset:448
	s_waitcnt lgkmcnt(12)
; #define LAS __attribute__((address_space(3)))
; __device__ __forceinline__ void sel_unit(LAS char* lds, int b, int u, const bf16_t* QI, const bf16_t* KIDX, const float* WIDX, unsigned long long* MASK) {
;     ...
;     for (int j = 0; j < 8; ++j) {
;         if (j < nj) {
;             int t = wid + 8 * j; asm volatile("" : "+s"(t));
; #pragma unroll
;             for (int kh = 0; kh < 2; ++kh) {
;             bf16x8 kf[2][2];
; #pragma unroll
;             for (int kb = 0; kb < 2; ++kb)
; #pragma unroll
;                 for (int ks = 0; ks < 2; ++ks) kf[kb][ks] = *(const bf16x8*)(KIDX + (rowbase + 64 * t + 32 * kh + 16 * kb + q16) * 64 + 32 * ks + 8 * kg);
; #pragma unroll
;             for (int kb = 0; kb < 2; ++kb) {
;                 f32x4 s = (f32x4){0.f, 0.f, 0.f, 0.f};
; #pragma unroll
;                 for (int hh = 0; hh < 8; ++hh) {
;                     f32x4 a = (f32x4){0.f, 0.f, 0.f, 0.f};
; #pragma unroll
;                     for (int ks = 0; ks < 2; ++ks) {
;                         const bf16x8 qv = *(const LAS bf16x8*)(lds + L_QI + q16 * 1024 + (((hh * 8 + 4 * ks + kg) ^ q16) << 4));
;                         a = __builtin_amdgcn_mfma_f32_16x16x32_bf16(kf[kb][ks], qv, a, 0, 0, 0);
;                     }
;                     const float wh = wl[hh * 16];
; #pragma unroll
;                     for (int i = 0; i < 4; ++i) s[i] += wh * fmaxf(a[i], 0.f);
;                 }
	v_mfma_f32_16x16x32_bf16 v[206:209], v[42:45], v[238:241], 0
	v_max_f32_e32 v9, 0, v246
	v_max_f32_e32 v200, 0, v247
	v_max_f32_e32 v201, 0, v248
	v_max_f32_e32 v216, 0, v249
	v_mfma_f32_16x16x32_bf16 v[210:213], v[50:53], v[238:241], 0
	v_mul_f32_e32 v178, v217, v9
	v_mul_f32_e32 v177, v217, v200
	v_mul_f32_e32 v186, v217, v201
	v_mul_f32_e32 v181, v217, v216
	v_mfma_f32_16x16x32_bf16 v[206:209], v[46:49], v[242:245], v[206:209]
	v_max_f32_e32 v9, 0, v250
	v_max_f32_e32 v200, 0, v251
	v_max_f32_e32 v201, 0, v252
	v_max_f32_e32 v216, 0, v253
	v_mfma_f32_16x16x32_bf16 v[210:213], v[2:5], v[242:245], v[210:213]
	v_mul_f32_e32 v188, v217, v9
	v_mul_f32_e32 v187, v217, v200
	v_mul_f32_e32 v190, v217, v201
	v_mul_f32_e32 v189, v217, v216
	ds_read_b128 v[238:241], v176
	ds_read_b128 v[242:245], v159
	ds_read_b32 v217, v137 offset:512
	s_waitcnt lgkmcnt(4)
	v_mfma_f32_16x16x32_bf16 v[246:249], v[42:45], v[230:233], 0
	v_max_f32_e32 v9, 0, v206
	v_max_f32_e32 v200, 0, v207
	v_max_f32_e32 v201, 0, v208
	v_max_f32_e32 v216, 0, v209
	v_mfma_f32_16x16x32_bf16 v[250:253], v[50:53], v[230:233], 0
	v_fmac_f32_e32 v178, v6, v9
	v_fmac_f32_e32 v177, v6, v200
	v_fmac_f32_e32 v186, v6, v201
	v_fmac_f32_e32 v181, v6, v216
	v_mfma_f32_16x16x32_bf16 v[246:249], v[46:49], v[234:237], v[246:249]
	v_max_f32_e32 v9, 0, v210
	v_max_f32_e32 v200, 0, v211
	v_max_f32_e32 v201, 0, v212
	v_max_f32_e32 v216, 0, v213
	v_mfma_f32_16x16x32_bf16 v[250:253], v[2:5], v[234:237], v[250:253]
	v_fmac_f32_e32 v188, v6, v9
	v_fmac_f32_e32 v187, v6, v200
	v_fmac_f32_e32 v190, v6, v201
	v_fmac_f32_e32 v189, v6, v216
	ds_read_b128 v[230:233], v158
	ds_read_b128 v[234:237], v157
	ds_read_b32 v6, v137 offset:576
	s_waitcnt lgkmcnt(4)
	v_mfma_f32_16x16x32_bf16 v[206:209], v[42:45], v[238:241], 0
	v_max_f32_e32 v9, 0, v246
	v_max_f32_e32 v200, 0, v247
	v_max_f32_e32 v201, 0, v248
	v_max_f32_e32 v216, 0, v249
	v_mfma_f32_16x16x32_bf16 v[210:213], v[50:53], v[238:241], 0
	v_fmac_f32_e32 v178, v7, v9
	v_fmac_f32_e32 v177, v7, v200
	v_fmac_f32_e32 v186, v7, v201
	v_fmac_f32_e32 v181, v7, v216
	v_mfma_f32_16x16x32_bf16 v[206:209], v[46:49], v[242:245], v[206:209]
	v_max_f32_e32 v9, 0, v250
	v_max_f32_e32 v200, 0, v251
	v_max_f32_e32 v201, 0, v252
	v_max_f32_e32 v216, 0, v253
	v_mfma_f32_16x16x32_bf16 v[210:213], v[2:5], v[242:245], v[210:213]
	v_fmac_f32_e32 v188, v7, v9
	v_fmac_f32_e32 v187, v7, v200
	v_fmac_f32_e32 v190, v7, v201
	v_fmac_f32_e32 v189, v7, v216
	ds_read_b128 v[238:241], v156
	ds_read_b128 v[242:245], v155
	ds_read_b32 v7, v137 offset:640
	s_waitcnt lgkmcnt(4)
	v_mfma_f32_16x16x32_bf16 v[246:249], v[42:45], v[230:233], 0
	v_max_f32_e32 v9, 0, v206
	v_max_f32_e32 v200, 0, v207
	v_max_f32_e32 v201, 0, v208
	v_max_f32_e32 v216, 0, v209
	v_mfma_f32_16x16x32_bf16 v[250:253], v[50:53], v[230:233], 0
	v_fmac_f32_e32 v178, v217, v9
	v_fmac_f32_e32 v177, v217, v200
	v_fmac_f32_e32 v186, v217, v201
	v_fmac_f32_e32 v181, v217, v216
	v_mfma_f32_16x16x32_bf16 v[246:249], v[46:49], v[234:237], v[246:249]
	v_max_f32_e32 v9, 0, v210
	v_max_f32_e32 v200, 0, v211
	v_max_f32_e32 v201, 0, v212
	v_max_f32_e32 v216, 0, v213
	v_mfma_f32_16x16x32_bf16 v[250:253], v[2:5], v[234:237], v[250:253]
	v_fmac_f32_e32 v188, v217, v9
	v_fmac_f32_e32 v187, v217, v200
	v_fmac_f32_e32 v190, v217, v201
	v_fmac_f32_e32 v189, v217, v216
	ds_read_b128 v[230:233], v154
	ds_read_b128 v[234:237], v153
	ds_read_b32 v217, v137 offset:704
	s_waitcnt lgkmcnt(4)
	v_mfma_f32_16x16x32_bf16 v[206:209], v[42:45], v[238:241], 0
	v_max_f32_e32 v9, 0, v246
	v_max_f32_e32 v200, 0, v247
	v_max_f32_e32 v201, 0, v248
	v_max_f32_e32 v216, 0, v249
	v_mfma_f32_16x16x32_bf16 v[210:213], v[50:53], v[238:241], 0
	v_fmac_f32_e32 v178, v6, v9
	v_fmac_f32_e32 v177, v6, v200
	v_fmac_f32_e32 v186, v6, v201
	v_fmac_f32_e32 v181, v6, v216
	v_mfma_f32_16x16x32_bf16 v[206:209], v[46:49], v[242:245], v[206:209]
	v_max_f32_e32 v9, 0, v250
	v_max_f32_e32 v200, 0, v251
	v_max_f32_e32 v201, 0, v252
	v_max_f32_e32 v216, 0, v253
	v_mfma_f32_16x16x32_bf16 v[210:213], v[2:5], v[242:245], v[210:213]
	v_fmac_f32_e32 v188, v6, v9
	v_fmac_f32_e32 v187, v6, v200
	v_fmac_f32_e32 v190, v6, v201
	v_fmac_f32_e32 v189, v6, v216
	ds_read_b128 v[238:241], v152
	ds_read_b128 v[242:245], v151
	ds_read_b32 v6, v137 offset:768
	s_waitcnt lgkmcnt(4)
	v_mfma_f32_16x16x32_bf16 v[246:249], v[42:45], v[230:233], 0
	v_max_f32_e32 v9, 0, v206
	v_max_f32_e32 v200, 0, v207
	v_max_f32_e32 v201, 0, v208
	v_max_f32_e32 v216, 0, v209
	v_mfma_f32_16x16x32_bf16 v[250:253], v[50:53], v[230:233], 0
	v_fmac_f32_e32 v178, v7, v9
	v_fmac_f32_e32 v177, v7, v200
	v_fmac_f32_e32 v186, v7, v201
	v_fmac_f32_e32 v181, v7, v216
	v_mfma_f32_16x16x32_bf16 v[246:249], v[46:49], v[234:237], v[246:249]
	v_max_f32_e32 v9, 0, v210
	v_max_f32_e32 v200, 0, v211
	v_max_f32_e32 v201, 0, v212
	v_max_f32_e32 v216, 0, v213
	v_mfma_f32_16x16x32_bf16 v[250:253], v[2:5], v[234:237], v[250:253]
	v_fmac_f32_e32 v188, v7, v9
	v_fmac_f32_e32 v187, v7, v200
	v_fmac_f32_e32 v190, v7, v201
	v_fmac_f32_e32 v189, v7, v216
	s_waitcnt lgkmcnt(1)
	v_mfma_f32_16x16x32_bf16 v[206:209], v[42:45], v[238:241], 0
	v_max_f32_e32 v9, 0, v246
	v_max_f32_e32 v200, 0, v247
	v_max_f32_e32 v201, 0, v248
	v_max_f32_e32 v216, 0, v249
	v_mfma_f32_16x16x32_bf16 v[210:213], v[50:53], v[238:241], 0
	v_fmac_f32_e32 v178, v217, v9
	v_fmac_f32_e32 v177, v217, v200
	v_fmac_f32_e32 v186, v217, v201
	v_fmac_f32_e32 v181, v217, v216
	v_mfma_f32_16x16x32_bf16 v[206:209], v[46:49], v[242:245], v[206:209]
	v_max_f32_e32 v9, 0, v250
	v_max_f32_e32 v200, 0, v251
	v_max_f32_e32 v201, 0, v252
	v_max_f32_e32 v216, 0, v253
	v_mfma_f32_16x16x32_bf16 v[210:213], v[2:5], v[242:245], v[210:213]
	v_fmac_f32_e32 v188, v217, v9
	v_fmac_f32_e32 v187, v217, v200
	v_fmac_f32_e32 v190, v217, v201
	v_fmac_f32_e32 v189, v217, v216
	s_waitcnt lgkmcnt(0)
; #define LAS __attribute__((address_space(3)))
; #define SEL_HADD(idx_) __hip_atomic_fetch_add(&hist[(idx_)], 1u, __ATOMIC_RELAXED, __HIP_MEMORY_SCOPE_WORKGROUP)
; __device__ __forceinline__ unsigned fkey(float f) { const unsigned u = __float_as_uint(f); return (u & 0x80000000u) ? ~u : (u | 0x80000000u); }
; __device__ __forceinline__ void sel_unit(LAS char* lds, int b, int u, const bf16_t* QI, const bf16_t* KIDX, const float* WIDX, unsigned long long* MASK) {
;     ...
;     for (int j = 0; j < 8; ++j) {
;         if (j < nj) {
;             int t = wid + 8 * j; asm volatile("" : "+s"(t));
; #pragma unroll
;             for (int kh = 0; kh < 2; ++kh) {
;             bf16x8 kf[2][2];
; #pragma unroll
;             for (int kb = 0; kb < 2; ++kb)
; #pragma unroll
;                 for (int ks = 0; ks < 2; ++ks) kf[kb][ks] = *(const bf16x8*)(KIDX + (rowbase + 64 * t + 32 * kh + 16 * kb + q16) * 64 + 32 * ks + 8 * kg);
; #pragma unroll
;             for (int kb = 0; kb < 2; ++kb) {
;                 f32x4 s = (f32x4){0.f, 0.f, 0.f, 0.f};
; #pragma unroll
;                 for (int hh = 0; hh < 8; ++hh) {
;                     f32x4 a = (f32x4){0.f, 0.f, 0.f, 0.f};
; #pragma unroll
;                     for (int ks = 0; ks < 2; ++ks) {
;                         const bf16x8 qv = *(const LAS bf16x8*)(lds + L_QI + q16 * 1024 + (((hh * 8 + 4 * ks + kg) ^ q16) << 4));
;                         a = __builtin_amdgcn_mfma_f32_16x16x32_bf16(kf[kb][ks], qv, a, 0, 0, 0);
;                     }
;                     const float wh = wl[hh * 16];
; #pragma unroll
;                     for (int i = 0; i < 4; ++i) s[i] += wh * fmaxf(a[i], 0.f);
;                 }
;                 u32x4 kk; kk.x = fkey(s[0]); kk.y = fkey(s[1]); kk.z = fkey(s[2]); kk.w = fkey(s[3]);
;                 sc[j][2 * kh + kb] = kk;
; #pragma unroll
;                 for (int i = 0; i < 4; ++i) SEL_HADD((kk[i] >> 24) * 16 + q16);
	v_max_f32_e32 v9, 0, v206
	v_max_f32_e32 v200, 0, v207
	v_max_f32_e32 v201, 0, v208
	v_max_f32_e32 v216, 0, v209
	v_fmac_f32_e32 v178, v6, v9
	v_fmac_f32_e32 v177, v6, v200
	v_fmac_f32_e32 v186, v6, v201
	v_fmac_f32_e32 v181, v6, v216
	v_max_f32_e32 v9, 0, v210
	v_max_f32_e32 v200, 0, v211
	v_max_f32_e32 v201, 0, v212
	v_max_f32_e32 v216, 0, v213
	v_fmac_f32_e32 v188, v6, v9
	v_fmac_f32_e32 v187, v6, v200
	v_fmac_f32_e32 v190, v6, v201
	v_fmac_f32_e32 v189, v6, v216
	v_ashrrev_i32_e32 v9, 31, v178
	v_bitop3_b32 v178, v9, v178, v8 bitop3:0x36
	v_ashrrev_i32_e32 v200, 31, v177
	v_bitop3_b32 v177, v200, v177, v8 bitop3:0x36
	v_ashrrev_i32_e32 v201, 31, v186
	v_bitop3_b32 v186, v201, v186, v8 bitop3:0x36
	v_ashrrev_i32_e32 v216, 31, v181
	v_bitop3_b32 v181, v216, v181, v8 bitop3:0x36
	v_ashrrev_i32_e32 v9, 31, v188
	v_bitop3_b32 v188, v9, v188, v8 bitop3:0x36
	v_ashrrev_i32_e32 v200, 31, v187
	v_bitop3_b32 v187, v200, v187, v8 bitop3:0x36
	v_ashrrev_i32_e32 v201, 31, v190
	v_bitop3_b32 v190, v201, v190, v8 bitop3:0x36
	v_ashrrev_i32_e32 v216, 31, v189
	v_bitop3_b32 v189, v216, v189, v8 bitop3:0x36
	v_lshrrev_b32_e32 v9, 24, v178
	v_lshl_add_u32 v9, v9, 6, v0
	ds_add_u32 v9, v205 offset:16384
	v_lshrrev_b32_e32 v200, 24, v177
	v_lshl_add_u32 v200, v200, 6, v0
	ds_add_u32 v200, v205 offset:16384
	v_lshrrev_b32_e32 v201, 24, v186
	v_lshl_add_u32 v201, v201, 6, v0
	ds_add_u32 v201, v205 offset:16384
	v_lshrrev_b32_e32 v216, 24, v181
	v_lshl_add_u32 v216, v216, 6, v0
	ds_add_u32 v216, v205 offset:16384
	v_lshrrev_b32_e32 v9, 24, v188
	v_lshl_add_u32 v9, v9, 6, v0
	ds_add_u32 v9, v205 offset:16384
	v_lshrrev_b32_e32 v200, 24, v187
	v_lshl_add_u32 v200, v200, 6, v0
	ds_add_u32 v200, v205 offset:16384
	v_lshrrev_b32_e32 v201, 24, v190
	v_lshl_add_u32 v201, v201, 6, v0
	ds_add_u32 v201, v205 offset:16384
	v_lshrrev_b32_e32 v216, 24, v189
	v_lshl_add_u32 v216, v216, 6, v0
	ds_add_u32 v216, v205 offset:16384
.LBB0_668:
	s_cmp_gt_i32 s4, 6
	s_cselect_b64 s[0:1], -1, 0
	s_cmp_lt_i32 s4, 7
	s_cbranch_scc1 .LBB0_670
	ds_read_b128 v[230:233], v182
	ds_read_b128 v[234:237], v183
	ds_read_b32 v6, v137 offset:320
	ds_read_b128 v[238:241], v184
	ds_read_b128 v[242:245], v185
	ds_read_b32 v7, v137 offset:384
	s_waitcnt vmcnt(0)
	v_add_co_u32_e32 v22, vcc, s96, v22
	s_nop 1
	v_addc_co_u32_e32 v23, vcc, 0, v23, vcc
	global_load_dwordx4 v[42:45], v[22:23], off
	global_load_dwordx4 v[46:49], v[22:23], off offset:64
	global_load_dwordx4 v[50:53], v[22:23], off offset:2048
	global_load_dwordx4 v[2:5], v[22:23], off offset:2112
	s_waitcnt lgkmcnt(4)
	v_mfma_f32_16x16x32_bf16 v[246:249], v[26:29], v[230:233], 0
	v_mfma_f32_16x16x32_bf16 v[250:253], v[34:37], v[230:233], 0
	v_mfma_f32_16x16x32_bf16 v[246:249], v[30:33], v[234:237], v[246:249]
	v_mfma_f32_16x16x32_bf16 v[250:253], v[38:41], v[234:237], v[250:253]
	ds_read_b128 v[230:233], v179
	ds_read_b128 v[234:237], v180
	ds_read_b32 v217, v137 offset:448
	s_waitcnt lgkmcnt(4)
	s_nop 1
	v_mfma_f32_16x16x32_bf16 v[206:209], v[26:29], v[238:241], 0
	v_max_f32_e32 v9, 0, v246
	v_max_f32_e32 v200, 0, v247
	v_max_f32_e32 v201, 0, v248
	v_max_f32_e32 v216, 0, v249
	v_mfma_f32_16x16x32_bf16 v[210:213], v[34:37], v[238:241], 0
	v_mul_f32_e32 v192, v6, v9
	v_mul_f32_e32 v191, v6, v200
	v_mul_f32_e32 v194, v6, v201
	v_mul_f32_e32 v193, v6, v216
	v_mfma_f32_16x16x32_bf16 v[206:209], v[30:33], v[242:245], v[206:209]
	v_max_f32_e32 v9, 0, v250
	v_max_f32_e32 v200, 0, v251
	v_max_f32_e32 v201, 0, v252
	v_max_f32_e32 v216, 0, v253
	v_mfma_f32_16x16x32_bf16 v[210:213], v[38:41], v[242:245], v[210:213]
	v_mul_f32_e32 v196, v6, v9
	v_mul_f32_e32 v195, v6, v200
	v_mul_f32_e32 v198, v6, v201
	v_mul_f32_e32 v197, v6, v216
	ds_read_b128 v[238:241], v176
	ds_read_b128 v[242:245], v159
	ds_read_b32 v6, v137 offset:512
	s_waitcnt lgkmcnt(4)
	v_mfma_f32_16x16x32_bf16 v[246:249], v[26:29], v[230:233], 0
	v_max_f32_e32 v9, 0, v206
	v_max_f32_e32 v200, 0, v207
	v_max_f32_e32 v201, 0, v208
	v_max_f32_e32 v216, 0, v209
	v_mfma_f32_16x16x32_bf16 v[250:253], v[34:37], v[230:233], 0
	v_fmac_f32_e32 v192, v7, v9
	v_fmac_f32_e32 v191, v7, v200
	v_fmac_f32_e32 v194, v7, v201
	v_fmac_f32_e32 v193, v7, v216
	v_mfma_f32_16x16x32_bf16 v[246:249], v[30:33], v[234:237], v[246:249]
	v_max_f32_e32 v9, 0, v210
	v_max_f32_e32 v200, 0, v211
	v_max_f32_e32 v201, 0, v212
	v_max_f32_e32 v216, 0, v213
	v_mfma_f32_16x16x32_bf16 v[250:253], v[38:41], v[234:237], v[250:253]
	v_fmac_f32_e32 v196, v7, v9
	v_fmac_f32_e32 v195, v7, v200
	v_fmac_f32_e32 v198, v7, v201
	v_fmac_f32_e32 v197, v7, v216
	ds_read_b128 v[230:233], v158
	ds_read_b128 v[234:237], v157
	ds_read_b32 v7, v137 offset:576
	s_waitcnt lgkmcnt(4)
	v_mfma_f32_16x16x32_bf16 v[206:209], v[26:29], v[238:241], 0
	v_max_f32_e32 v9, 0, v246
	v_max_f32_e32 v200, 0, v247
	v_max_f32_e32 v201, 0, v248
	v_max_f32_e32 v216, 0, v249
	v_mfma_f32_16x16x32_bf16 v[210:213], v[34:37], v[238:241], 0
	v_fmac_f32_e32 v192, v217, v9
	v_fmac_f32_e32 v191, v217, v200
	v_fmac_f32_e32 v194, v217, v201
	v_fmac_f32_e32 v193, v217, v216
	v_mfma_f32_16x16x32_bf16 v[206:209], v[30:33], v[242:245], v[206:209]
	v_max_f32_e32 v9, 0, v250
	v_max_f32_e32 v200, 0, v251
	v_max_f32_e32 v201, 0, v252
	v_max_f32_e32 v216, 0, v253
	v_mfma_f32_16x16x32_bf16 v[210:213], v[38:41], v[242:245], v[210:213]
	v_fmac_f32_e32 v196, v217, v9
	v_fmac_f32_e32 v195, v217, v200
	v_fmac_f32_e32 v198, v217, v201
	v_fmac_f32_e32 v197, v217, v216
	ds_read_b128 v[238:241], v156
	ds_read_b128 v[242:245], v155
	ds_read_b32 v217, v137 offset:640
	s_waitcnt lgkmcnt(4)
; #define LAS __attribute__((address_space(3)))
; #define SEL_HADD(idx_) __hip_atomic_fetch_add(&hist[(idx_)], 1u, __ATOMIC_RELAXED, __HIP_MEMORY_SCOPE_WORKGROUP)
; __device__ __forceinline__ unsigned fkey(float f) { const unsigned u = __float_as_uint(f); return (u & 0x80000000u) ? ~u : (u | 0x80000000u); }
; __device__ __forceinline__ void sel_unit(LAS char* lds, int b, int u, const bf16_t* QI, const bf16_t* KIDX, const float* WIDX, unsigned long long* MASK) {
;     ...
;     for (int j = 0; j < 8; ++j) {
;         if (j < nj) {
;             int t = wid + 8 * j; asm volatile("" : "+s"(t));
; #pragma unroll
;             for (int kh = 0; kh < 2; ++kh) {
;             bf16x8 kf[2][2];
; #pragma unroll
;             for (int kb = 0; kb < 2; ++kb)
; #pragma unroll
;                 for (int ks = 0; ks < 2; ++ks) kf[kb][ks] = *(const bf16x8*)(KIDX + (rowbase + 64 * t + 32 * kh + 16 * kb + q16) * 64 + 32 * ks + 8 * kg);
; #pragma unroll
;             for (int kb = 0; kb < 2; ++kb) {
;                 f32x4 s = (f32x4){0.f, 0.f, 0.f, 0.f};
; #pragma unroll
;                 for (int hh = 0; hh < 8; ++hh) {
;                     f32x4 a = (f32x4){0.f, 0.f, 0.f, 0.f};
; #pragma unroll
;                     for (int ks = 0; ks < 2; ++ks) {
;                         const bf16x8 qv = *(const LAS bf16x8*)(lds + L_QI + q16 * 1024 + (((hh * 8 + 4 * ks + kg) ^ q16) << 4));
;                         a = __builtin_amdgcn_mfma_f32_16x16x32_bf16(kf[kb][ks], qv, a, 0, 0, 0);
;                     }
;                     const float wh = wl[hh * 16];
; #pragma unroll
;                     for (int i = 0; i < 4; ++i) s[i] += wh * fmaxf(a[i], 0.f);
;                 }
;                 u32x4 kk; kk.x = fkey(s[0]); kk.y = fkey(s[1]); kk.z = fkey(s[2]); kk.w = fkey(s[3]);
;                 sc[j][2 * kh + kb] = kk;
; #pragma unroll
;                 for (int i = 0; i < 4; ++i) SEL_HADD((kk[i] >> 24) * 16 + q16);
	v_mfma_f32_16x16x32_bf16 v[246:249], v[26:29], v[230:233], 0
	v_max_f32_e32 v9, 0, v206
	v_max_f32_e32 v200, 0, v207
	v_max_f32_e32 v201, 0, v208
	v_max_f32_e32 v216, 0, v209
	v_mfma_f32_16x16x32_bf16 v[250:253], v[34:37], v[230:233], 0
	v_fmac_f32_e32 v192, v6, v9
	v_fmac_f32_e32 v191, v6, v200
	v_fmac_f32_e32 v194, v6, v201
	v_fmac_f32_e32 v193, v6, v216
	v_mfma_f32_16x16x32_bf16 v[246:249], v[30:33], v[234:237], v[246:249]
	v_max_f32_e32 v9, 0, v210
	v_max_f32_e32 v200, 0, v211
	v_max_f32_e32 v201, 0, v212
	v_max_f32_e32 v216, 0, v213
	v_mfma_f32_16x16x32_bf16 v[250:253], v[38:41], v[234:237], v[250:253]
	v_fmac_f32_e32 v196, v6, v9
	v_fmac_f32_e32 v195, v6, v200
	v_fmac_f32_e32 v198, v6, v201
	v_fmac_f32_e32 v197, v6, v216
	ds_read_b128 v[230:233], v154
	ds_read_b128 v[234:237], v153
	ds_read_b32 v6, v137 offset:704
	s_waitcnt lgkmcnt(4)
	v_mfma_f32_16x16x32_bf16 v[206:209], v[26:29], v[238:241], 0
	v_max_f32_e32 v9, 0, v246
	v_max_f32_e32 v200, 0, v247
	v_max_f32_e32 v201, 0, v248
	v_max_f32_e32 v216, 0, v249
	v_mfma_f32_16x16x32_bf16 v[210:213], v[34:37], v[238:241], 0
	v_fmac_f32_e32 v192, v7, v9
	v_fmac_f32_e32 v191, v7, v200
	v_fmac_f32_e32 v194, v7, v201
	v_fmac_f32_e32 v193, v7, v216
	v_mfma_f32_16x16x32_bf16 v[206:209], v[30:33], v[242:245], v[206:209]
	v_max_f32_e32 v9, 0, v250
	v_max_f32_e32 v200, 0, v251
	v_max_f32_e32 v201, 0, v252
	v_max_f32_e32 v216, 0, v253
	v_mfma_f32_16x16x32_bf16 v[210:213], v[38:41], v[242:245], v[210:213]
	v_fmac_f32_e32 v196, v7, v9
	v_fmac_f32_e32 v195, v7, v200
	v_fmac_f32_e32 v198, v7, v201
	v_fmac_f32_e32 v197, v7, v216
	ds_read_b128 v[238:241], v152
	ds_read_b128 v[242:245], v151
	ds_read_b32 v7, v137 offset:768
	s_waitcnt lgkmcnt(4)
	v_mfma_f32_16x16x32_bf16 v[246:249], v[26:29], v[230:233], 0
	v_max_f32_e32 v9, 0, v206
	v_max_f32_e32 v200, 0, v207
	v_max_f32_e32 v201, 0, v208
	v_max_f32_e32 v216, 0, v209
	v_mfma_f32_16x16x32_bf16 v[250:253], v[34:37], v[230:233], 0
	v_fmac_f32_e32 v192, v217, v9
	v_fmac_f32_e32 v191, v217, v200
	v_fmac_f32_e32 v194, v217, v201
	v_fmac_f32_e32 v193, v217, v216
	v_mfma_f32_16x16x32_bf16 v[246:249], v[30:33], v[234:237], v[246:249]
	v_max_f32_e32 v9, 0, v210
	v_max_f32_e32 v200, 0, v211
	v_max_f32_e32 v201, 0, v212
	v_max_f32_e32 v216, 0, v213
	v_mfma_f32_16x16x32_bf16 v[250:253], v[38:41], v[234:237], v[250:253]
	v_fmac_f32_e32 v196, v217, v9
	v_fmac_f32_e32 v195, v217, v200
	v_fmac_f32_e32 v198, v217, v201
	v_fmac_f32_e32 v197, v217, v216
	ds_read_b128 v[230:233], v182
	ds_read_b128 v[234:237], v183
	ds_read_b32 v217, v137 offset:320
	s_waitcnt lgkmcnt(4)
	v_mfma_f32_16x16x32_bf16 v[206:209], v[26:29], v[238:241], 0
	v_max_f32_e32 v9, 0, v246
	v_max_f32_e32 v200, 0, v247
	v_max_f32_e32 v201, 0, v248
	v_max_f32_e32 v216, 0, v249
	v_mfma_f32_16x16x32_bf16 v[210:213], v[34:37], v[238:241], 0
	v_fmac_f32_e32 v192, v6, v9
	v_fmac_f32_e32 v191, v6, v200
	v_fmac_f32_e32 v194, v6, v201
	v_fmac_f32_e32 v193, v6, v216
	v_mfma_f32_16x16x32_bf16 v[206:209], v[30:33], v[242:245], v[206:209]
	v_max_f32_e32 v9, 0, v250
	v_max_f32_e32 v200, 0, v251
	v_max_f32_e32 v201, 0, v252
	v_max_f32_e32 v216, 0, v253
	v_mfma_f32_16x16x32_bf16 v[210:213], v[38:41], v[242:245], v[210:213]
	v_fmac_f32_e32 v196, v6, v9
	v_fmac_f32_e32 v195, v6, v200
	v_fmac_f32_e32 v198, v6, v201
	v_fmac_f32_e32 v197, v6, v216
	ds_read_b128 v[238:241], v184
	ds_read_b128 v[242:245], v185
	ds_read_b32 v6, v137 offset:384
	s_waitcnt vmcnt(0)
	s_cmp_lt_i32 s4, 8
	s_cbranch_scc1 .Lp0_nopf_6
	v_add_co_u32_e32 v22, vcc, 0xf000, v22
	s_nop 1
	v_addc_co_u32_e32 v23, vcc, 0, v23, vcc
	global_load_dwordx4 v[26:29], v[22:23], off
	global_load_dwordx4 v[30:33], v[22:23], off offset:64
	global_load_dwordx4 v[34:37], v[22:23], off offset:2048
	global_load_dwordx4 v[38:41], v[22:23], off offset:2112
.Lp0_nopf_6:
	s_waitcnt lgkmcnt(4)
	v_mfma_f32_16x16x32_bf16 v[246:249], v[42:45], v[230:233], 0
	v_max_f32_e32 v9, 0, v206
	v_max_f32_e32 v200, 0, v207
	v_max_f32_e32 v201, 0, v208
	v_max_f32_e32 v216, 0, v209
	v_fmac_f32_e32 v192, v7, v9
	v_fmac_f32_e32 v191, v7, v200
	v_fmac_f32_e32 v194, v7, v201
	v_fmac_f32_e32 v193, v7, v216
	v_max_f32_e32 v9, 0, v210
	v_max_f32_e32 v200, 0, v211
	v_max_f32_e32 v201, 0, v212
	v_max_f32_e32 v216, 0, v213
	v_fmac_f32_e32 v196, v7, v9
	v_fmac_f32_e32 v195, v7, v200
	v_mfma_f32_16x16x32_bf16 v[250:253], v[50:53], v[230:233], 0
	v_fmac_f32_e32 v198, v7, v201
	v_fmac_f32_e32 v197, v7, v216
	v_ashrrev_i32_e32 v9, 31, v192
	v_bitop3_b32 v192, v9, v192, v8 bitop3:0x36
	v_ashrrev_i32_e32 v200, 31, v191
	v_bitop3_b32 v191, v200, v191, v8 bitop3:0x36
	v_ashrrev_i32_e32 v201, 31, v194
	v_bitop3_b32 v194, v201, v194, v8 bitop3:0x36
	v_ashrrev_i32_e32 v216, 31, v193
	v_bitop3_b32 v193, v216, v193, v8 bitop3:0x36
	v_ashrrev_i32_e32 v9, 31, v196
	v_bitop3_b32 v196, v9, v196, v8 bitop3:0x36
	v_ashrrev_i32_e32 v200, 31, v195
	v_bitop3_b32 v195, v200, v195, v8 bitop3:0x36
	v_mfma_f32_16x16x32_bf16 v[246:249], v[46:49], v[234:237], v[246:249]
	v_ashrrev_i32_e32 v201, 31, v198
	v_bitop3_b32 v198, v201, v198, v8 bitop3:0x36
	v_ashrrev_i32_e32 v216, 31, v197
	v_bitop3_b32 v197, v216, v197, v8 bitop3:0x36
	v_lshrrev_b32_e32 v9, 24, v192
	v_lshl_add_u32 v9, v9, 6, v0
	ds_add_u32 v9, v205 offset:16384
	v_lshrrev_b32_e32 v200, 24, v191
	v_lshl_add_u32 v200, v200, 6, v0
	ds_add_u32 v200, v205 offset:16384
	v_lshrrev_b32_e32 v201, 24, v194
	v_lshl_add_u32 v201, v201, 6, v0
	ds_add_u32 v201, v205 offset:16384
	v_lshrrev_b32_e32 v216, 24, v193
	v_mfma_f32_16x16x32_bf16 v[250:253], v[2:5], v[234:237], v[250:253]
	v_lshl_add_u32 v216, v216, 6, v0
	ds_add_u32 v216, v205 offset:16384
	v_lshrrev_b32_e32 v9, 24, v196
	v_lshl_add_u32 v9, v9, 6, v0
	ds_add_u32 v9, v205 offset:16384
	v_lshrrev_b32_e32 v200, 24, v195
	v_lshl_add_u32 v200, v200, 6, v0
	ds_add_u32 v200, v205 offset:16384
	v_lshrrev_b32_e32 v201, 24, v198
	v_lshl_add_u32 v201, v201, 6, v0
	ds_add_u32 v201, v205 offset:16384
	v_lshrrev_b32_e32 v216, 24, v197
	v_lshl_add_u32 v216, v216, 6, v0
	ds_add_u32 v216, v205 offset:16384
	ds_read_b128 v[230:233], v179
	ds_read_b128 v[234:237], v180
	ds_read_b32 v7, v137 offset:448
	s_waitcnt lgkmcnt(12)
; #define LAS __attribute__((address_space(3)))
; __device__ __forceinline__ void sel_unit(LAS char* lds, int b, int u, const bf16_t* QI, const bf16_t* KIDX, const float* WIDX, unsigned long long* MASK) {
;     ...
;     for (int j = 0; j < 8; ++j) {
;         if (j < nj) {
;             int t = wid + 8 * j; asm volatile("" : "+s"(t));
; #pragma unroll
;             for (int kh = 0; kh < 2; ++kh) {
;             bf16x8 kf[2][2];
; #pragma unroll
;             for (int kb = 0; kb < 2; ++kb)
; #pragma unroll
;                 for (int ks = 0; ks < 2; ++ks) kf[kb][ks] = *(const bf16x8*)(KIDX + (rowbase + 64 * t + 32 * kh + 16 * kb + q16) * 64 + 32 * ks + 8 * kg);
; #pragma unroll
;             for (int kb = 0; kb < 2; ++kb) {
;                 f32x4 s = (f32x4){0.f, 0.f, 0.f, 0.f};
; #pragma unroll
;                 for (int hh = 0; hh < 8; ++hh) {
;                     f32x4 a = (f32x4){0.f, 0.f, 0.f, 0.f};
; #pragma unroll
;                     for (int ks = 0; ks < 2; ++ks) {
;                         const bf16x8 qv = *(const LAS bf16x8*)(lds + L_QI + q16 * 1024 + (((hh * 8 + 4 * ks + kg) ^ q16) << 4));
;                         a = __builtin_amdgcn_mfma_f32_16x16x32_bf16(kf[kb][ks], qv, a, 0, 0, 0);
;                     }
;                     const float wh = wl[hh * 16];
; #pragma unroll
;                     for (int i = 0; i < 4; ++i) s[i] += wh * fmaxf(a[i], 0.f);
;                 }
	v_mfma_f32_16x16x32_bf16 v[206:209], v[42:45], v[238:241], 0
	v_max_f32_e32 v9, 0, v246
	v_max_f32_e32 v200, 0, v247
	v_max_f32_e32 v201, 0, v248
	v_max_f32_e32 v216, 0, v249
	v_mfma_f32_16x16x32_bf16 v[210:213], v[50:53], v[238:241], 0
	v_mul_f32_e32 v57, v217, v9
	v_mul_f32_e32 v56, v217, v200
	v_mul_f32_e32 v55, v217, v201
	v_mul_f32_e32 v54, v217, v216
	v_mfma_f32_16x16x32_bf16 v[206:209], v[46:49], v[242:245], v[206:209]
	v_max_f32_e32 v9, 0, v250
	v_max_f32_e32 v200, 0, v251
	v_max_f32_e32 v201, 0, v252
	v_max_f32_e32 v216, 0, v253
	v_mfma_f32_16x16x32_bf16 v[210:213], v[2:5], v[242:245], v[210:213]
	v_mul_f32_e32 v218, v217, v9
	v_mul_f32_e32 v199, v217, v200
	v_mul_f32_e32 v220, v217, v201
	v_mul_f32_e32 v219, v217, v216
	ds_read_b128 v[238:241], v176
	ds_read_b128 v[242:245], v159
	ds_read_b32 v217, v137 offset:512
	s_waitcnt lgkmcnt(4)
	v_mfma_f32_16x16x32_bf16 v[246:249], v[42:45], v[230:233], 0
	v_max_f32_e32 v9, 0, v206
	v_max_f32_e32 v200, 0, v207
	v_max_f32_e32 v201, 0, v208
	v_max_f32_e32 v216, 0, v209
	v_mfma_f32_16x16x32_bf16 v[250:253], v[50:53], v[230:233], 0
	v_fmac_f32_e32 v57, v6, v9
	v_fmac_f32_e32 v56, v6, v200
	v_fmac_f32_e32 v55, v6, v201
	v_fmac_f32_e32 v54, v6, v216
	v_mfma_f32_16x16x32_bf16 v[246:249], v[46:49], v[234:237], v[246:249]
	v_max_f32_e32 v9, 0, v210
	v_max_f32_e32 v200, 0, v211
	v_max_f32_e32 v201, 0, v212
	v_max_f32_e32 v216, 0, v213
	v_mfma_f32_16x16x32_bf16 v[250:253], v[2:5], v[234:237], v[250:253]
	v_fmac_f32_e32 v218, v6, v9
	v_fmac_f32_e32 v199, v6, v200
	v_fmac_f32_e32 v220, v6, v201
	v_fmac_f32_e32 v219, v6, v216
	ds_read_b128 v[230:233], v158
	ds_read_b128 v[234:237], v157
	ds_read_b32 v6, v137 offset:576
	s_waitcnt lgkmcnt(4)
	v_mfma_f32_16x16x32_bf16 v[206:209], v[42:45], v[238:241], 0
	v_max_f32_e32 v9, 0, v246
	v_max_f32_e32 v200, 0, v247
	v_max_f32_e32 v201, 0, v248
	v_max_f32_e32 v216, 0, v249
	v_mfma_f32_16x16x32_bf16 v[210:213], v[50:53], v[238:241], 0
	v_fmac_f32_e32 v57, v7, v9
	v_fmac_f32_e32 v56, v7, v200
	v_fmac_f32_e32 v55, v7, v201
	v_fmac_f32_e32 v54, v7, v216
	v_mfma_f32_16x16x32_bf16 v[206:209], v[46:49], v[242:245], v[206:209]
	v_max_f32_e32 v9, 0, v250
	v_max_f32_e32 v200, 0, v251
	v_max_f32_e32 v201, 0, v252
	v_max_f32_e32 v216, 0, v253
	v_mfma_f32_16x16x32_bf16 v[210:213], v[2:5], v[242:245], v[210:213]
	v_fmac_f32_e32 v218, v7, v9
	v_fmac_f32_e32 v199, v7, v200
	v_fmac_f32_e32 v220, v7, v201
	v_fmac_f32_e32 v219, v7, v216
	ds_read_b128 v[238:241], v156
	ds_read_b128 v[242:245], v155
	ds_read_b32 v7, v137 offset:640
	s_waitcnt lgkmcnt(4)
	v_mfma_f32_16x16x32_bf16 v[246:249], v[42:45], v[230:233], 0
	v_max_f32_e32 v9, 0, v206
	v_max_f32_e32 v200, 0, v207
	v_max_f32_e32 v201, 0, v208
	v_max_f32_e32 v216, 0, v209
	v_mfma_f32_16x16x32_bf16 v[250:253], v[50:53], v[230:233], 0
	v_fmac_f32_e32 v57, v217, v9
	v_fmac_f32_e32 v56, v217, v200
	v_fmac_f32_e32 v55, v217, v201
	v_fmac_f32_e32 v54, v217, v216
	v_mfma_f32_16x16x32_bf16 v[246:249], v[46:49], v[234:237], v[246:249]
	v_max_f32_e32 v9, 0, v210
	v_max_f32_e32 v200, 0, v211
	v_max_f32_e32 v201, 0, v212
	v_max_f32_e32 v216, 0, v213
	v_mfma_f32_16x16x32_bf16 v[250:253], v[2:5], v[234:237], v[250:253]
	v_fmac_f32_e32 v218, v217, v9
	v_fmac_f32_e32 v199, v217, v200
	v_fmac_f32_e32 v220, v217, v201
	v_fmac_f32_e32 v219, v217, v216
	ds_read_b128 v[230:233], v154
	ds_read_b128 v[234:237], v153
	ds_read_b32 v217, v137 offset:704
	s_waitcnt lgkmcnt(4)
	v_mfma_f32_16x16x32_bf16 v[206:209], v[42:45], v[238:241], 0
	v_max_f32_e32 v9, 0, v246
	v_max_f32_e32 v200, 0, v247
	v_max_f32_e32 v201, 0, v248
	v_max_f32_e32 v216, 0, v249
	v_mfma_f32_16x16x32_bf16 v[210:213], v[50:53], v[238:241], 0
	v_fmac_f32_e32 v57, v6, v9
	v_fmac_f32_e32 v56, v6, v200
	v_fmac_f32_e32 v55, v6, v201
	v_fmac_f32_e32 v54, v6, v216
	v_mfma_f32_16x16x32_bf16 v[206:209], v[46:49], v[242:245], v[206:209]
	v_max_f32_e32 v9, 0, v250
	v_max_f32_e32 v200, 0, v251
	v_max_f32_e32 v201, 0, v252
	v_max_f32_e32 v216, 0, v253
	v_mfma_f32_16x16x32_bf16 v[210:213], v[2:5], v[242:245], v[210:213]
	v_fmac_f32_e32 v218, v6, v9
	v_fmac_f32_e32 v199, v6, v200
	v_fmac_f32_e32 v220, v6, v201
	v_fmac_f32_e32 v219, v6, v216
	ds_read_b128 v[238:241], v152
	ds_read_b128 v[242:245], v151
	ds_read_b32 v6, v137 offset:768
	s_waitcnt lgkmcnt(4)
	v_mfma_f32_16x16x32_bf16 v[246:249], v[42:45], v[230:233], 0
	v_max_f32_e32 v9, 0, v206
	v_max_f32_e32 v200, 0, v207
	v_max_f32_e32 v201, 0, v208
	v_max_f32_e32 v216, 0, v209
	v_mfma_f32_16x16x32_bf16 v[250:253], v[50:53], v[230:233], 0
	v_fmac_f32_e32 v57, v7, v9
	v_fmac_f32_e32 v56, v7, v200
	v_fmac_f32_e32 v55, v7, v201
	v_fmac_f32_e32 v54, v7, v216
	v_mfma_f32_16x16x32_bf16 v[246:249], v[46:49], v[234:237], v[246:249]
	v_max_f32_e32 v9, 0, v210
	v_max_f32_e32 v200, 0, v211
	v_max_f32_e32 v201, 0, v212
	v_max_f32_e32 v216, 0, v213
	v_mfma_f32_16x16x32_bf16 v[250:253], v[2:5], v[234:237], v[250:253]
	v_fmac_f32_e32 v218, v7, v9
	v_fmac_f32_e32 v199, v7, v200
	v_fmac_f32_e32 v220, v7, v201
	v_fmac_f32_e32 v219, v7, v216
	s_waitcnt lgkmcnt(1)
	v_mfma_f32_16x16x32_bf16 v[206:209], v[42:45], v[238:241], 0
	v_max_f32_e32 v9, 0, v246
	v_max_f32_e32 v200, 0, v247
	v_max_f32_e32 v201, 0, v248
	v_max_f32_e32 v216, 0, v249
	v_mfma_f32_16x16x32_bf16 v[210:213], v[50:53], v[238:241], 0
	v_fmac_f32_e32 v57, v217, v9
	v_fmac_f32_e32 v56, v217, v200
	v_fmac_f32_e32 v55, v217, v201
	v_fmac_f32_e32 v54, v217, v216
	v_mfma_f32_16x16x32_bf16 v[206:209], v[46:49], v[242:245], v[206:209]
	v_max_f32_e32 v9, 0, v250
	v_max_f32_e32 v200, 0, v251
	v_max_f32_e32 v201, 0, v252
	v_max_f32_e32 v216, 0, v253
	v_mfma_f32_16x16x32_bf16 v[210:213], v[2:5], v[242:245], v[210:213]
	v_fmac_f32_e32 v218, v217, v9
	v_fmac_f32_e32 v199, v217, v200
	v_fmac_f32_e32 v220, v217, v201
	v_fmac_f32_e32 v219, v217, v216
	s_waitcnt lgkmcnt(0)
; #define LAS __attribute__((address_space(3)))
; #define SEL_HADD(idx_) __hip_atomic_fetch_add(&hist[(idx_)], 1u, __ATOMIC_RELAXED, __HIP_MEMORY_SCOPE_WORKGROUP)
; __device__ __forceinline__ unsigned fkey(float f) { const unsigned u = __float_as_uint(f); return (u & 0x80000000u) ? ~u : (u | 0x80000000u); }
; __device__ __forceinline__ void sel_unit(LAS char* lds, int b, int u, const bf16_t* QI, const bf16_t* KIDX, const float* WIDX, unsigned long long* MASK) {
;     ...
;     for (int j = 0; j < 8; ++j) {
;         if (j < nj) {
;             int t = wid + 8 * j; asm volatile("" : "+s"(t));
; #pragma unroll
;             for (int kh = 0; kh < 2; ++kh) {
;             bf16x8 kf[2][2];
; #pragma unroll
;             for (int kb = 0; kb < 2; ++kb)
; #pragma unroll
;                 for (int ks = 0; ks < 2; ++ks) kf[kb][ks] = *(const bf16x8*)(KIDX + (rowbase + 64 * t + 32 * kh + 16 * kb + q16) * 64 + 32 * ks + 8 * kg);
; #pragma unroll
;             for (int kb = 0; kb < 2; ++kb) {
;                 f32x4 s = (f32x4){0.f, 0.f, 0.f, 0.f};
; #pragma unroll
;                 for (int hh = 0; hh < 8; ++hh) {
;                     f32x4 a = (f32x4){0.f, 0.f, 0.f, 0.f};
; #pragma unroll
;                     for (int ks = 0; ks < 2; ++ks) {
;                         const bf16x8 qv = *(const LAS bf16x8*)(lds + L_QI + q16 * 1024 + (((hh * 8 + 4 * ks + kg) ^ q16) << 4));
;                         a = __builtin_amdgcn_mfma_f32_16x16x32_bf16(kf[kb][ks], qv, a, 0, 0, 0);
;                     }
;                     const float wh = wl[hh * 16];
; #pragma unroll
;                     for (int i = 0; i < 4; ++i) s[i] += wh * fmaxf(a[i], 0.f);
;                 }
;                 u32x4 kk; kk.x = fkey(s[0]); kk.y = fkey(s[1]); kk.z = fkey(s[2]); kk.w = fkey(s[3]);
;                 sc[j][2 * kh + kb] = kk;
; #pragma unroll
;                 for (int i = 0; i < 4; ++i) SEL_HADD((kk[i] >> 24) * 16 + q16);
	v_max_f32_e32 v9, 0, v206
	v_max_f32_e32 v200, 0, v207
	v_max_f32_e32 v201, 0, v208
	v_max_f32_e32 v216, 0, v209
	v_fmac_f32_e32 v57, v6, v9
	v_fmac_f32_e32 v56, v6, v200
	v_fmac_f32_e32 v55, v6, v201
	v_fmac_f32_e32 v54, v6, v216
	v_max_f32_e32 v9, 0, v210
	v_max_f32_e32 v200, 0, v211
	v_max_f32_e32 v201, 0, v212
	v_max_f32_e32 v216, 0, v213
	v_fmac_f32_e32 v218, v6, v9
	v_fmac_f32_e32 v199, v6, v200
	v_fmac_f32_e32 v220, v6, v201
	v_fmac_f32_e32 v219, v6, v216
	v_ashrrev_i32_e32 v9, 31, v57
	v_bitop3_b32 v57, v9, v57, v8 bitop3:0x36
	v_ashrrev_i32_e32 v200, 31, v56
	v_bitop3_b32 v56, v200, v56, v8 bitop3:0x36
	v_ashrrev_i32_e32 v201, 31, v55
	v_bitop3_b32 v55, v201, v55, v8 bitop3:0x36
	v_ashrrev_i32_e32 v216, 31, v54
	v_bitop3_b32 v54, v216, v54, v8 bitop3:0x36
	v_ashrrev_i32_e32 v9, 31, v218
	v_bitop3_b32 v218, v9, v218, v8 bitop3:0x36
	v_ashrrev_i32_e32 v200, 31, v199
	v_bitop3_b32 v199, v200, v199, v8 bitop3:0x36
	v_ashrrev_i32_e32 v201, 31, v220
	v_bitop3_b32 v220, v201, v220, v8 bitop3:0x36
	v_ashrrev_i32_e32 v216, 31, v219
	v_bitop3_b32 v219, v216, v219, v8 bitop3:0x36
	v_lshrrev_b32_e32 v9, 24, v57
	v_lshl_add_u32 v9, v9, 6, v0
	ds_add_u32 v9, v205 offset:16384
	v_lshrrev_b32_e32 v200, 24, v56
	v_lshl_add_u32 v200, v200, 6, v0
	ds_add_u32 v200, v205 offset:16384
	v_lshrrev_b32_e32 v201, 24, v55
	v_lshl_add_u32 v201, v201, 6, v0
	ds_add_u32 v201, v205 offset:16384
	v_lshrrev_b32_e32 v216, 24, v54
	v_lshl_add_u32 v216, v216, 6, v0
	ds_add_u32 v216, v205 offset:16384
	v_lshrrev_b32_e32 v9, 24, v218
	v_lshl_add_u32 v9, v9, 6, v0
	ds_add_u32 v9, v205 offset:16384
	v_lshrrev_b32_e32 v200, 24, v199
	v_lshl_add_u32 v200, v200, 6, v0
	ds_add_u32 v200, v205 offset:16384
	v_lshrrev_b32_e32 v201, 24, v220
	v_lshl_add_u32 v201, v201, 6, v0
	ds_add_u32 v201, v205 offset:16384
	v_lshrrev_b32_e32 v216, 24, v219
	v_lshl_add_u32 v216, v216, 6, v0
	ds_add_u32 v216, v205 offset:16384
.LBB0_670:
	s_cmp_gt_i32 s4, 7
	s_cselect_b64 s[26:27], -1, 0
	s_cmp_lt_i32 s4, 8
	s_cbranch_scc1 .LBB0_672
	ds_read_b128 v[230:233], v182
	ds_read_b128 v[234:237], v183
	ds_read_b32 v6, v137 offset:320
	ds_read_b128 v[238:241], v184
	ds_read_b128 v[242:245], v185
	ds_read_b32 v7, v137 offset:384
	s_waitcnt vmcnt(0)
	v_add_co_u32_e32 v22, vcc, s96, v22
	s_nop 1
	v_addc_co_u32_e32 v23, vcc, 0, v23, vcc
	global_load_dwordx4 v[42:45], v[22:23], off
	global_load_dwordx4 v[46:49], v[22:23], off offset:64
	global_load_dwordx4 v[50:53], v[22:23], off offset:2048
	global_load_dwordx4 v[2:5], v[22:23], off offset:2112
	s_waitcnt lgkmcnt(4)
	v_mfma_f32_16x16x32_bf16 v[246:249], v[26:29], v[230:233], 0
	v_mfma_f32_16x16x32_bf16 v[250:253], v[34:37], v[230:233], 0
	v_mfma_f32_16x16x32_bf16 v[246:249], v[30:33], v[234:237], v[246:249]
	v_mfma_f32_16x16x32_bf16 v[250:253], v[38:41], v[234:237], v[250:253]
	ds_read_b128 v[230:233], v179
	ds_read_b128 v[234:237], v180
	ds_read_b32 v217, v137 offset:448
	s_waitcnt lgkmcnt(4)
	s_nop 1
	v_mfma_f32_16x16x32_bf16 v[206:209], v[26:29], v[238:241], 0
	v_max_f32_e32 v9, 0, v246
	v_max_f32_e32 v200, 0, v247
	v_max_f32_e32 v201, 0, v248
	v_max_f32_e32 v216, 0, v249
	v_mfma_f32_16x16x32_bf16 v[210:213], v[34:37], v[238:241], 0
	v_mul_f32_e32 v222, v6, v9
	v_mul_f32_e32 v221, v6, v200
	v_mul_f32_e32 v224, v6, v201
	v_mul_f32_e32 v223, v6, v216
	v_mfma_f32_16x16x32_bf16 v[206:209], v[30:33], v[242:245], v[206:209]
	v_max_f32_e32 v9, 0, v250
	v_max_f32_e32 v200, 0, v251
	v_max_f32_e32 v201, 0, v252
	v_max_f32_e32 v216, 0, v253
	v_mfma_f32_16x16x32_bf16 v[210:213], v[38:41], v[242:245], v[210:213]
	v_mul_f32_e32 v226, v6, v9
	v_mul_f32_e32 v225, v6, v200
	v_mul_f32_e32 v228, v6, v201
	v_mul_f32_e32 v227, v6, v216
	ds_read_b128 v[238:241], v176
	ds_read_b128 v[242:245], v159
	ds_read_b32 v6, v137 offset:512
	s_waitcnt lgkmcnt(4)
	v_mfma_f32_16x16x32_bf16 v[246:249], v[26:29], v[230:233], 0
	v_max_f32_e32 v9, 0, v206
	v_max_f32_e32 v200, 0, v207
	v_max_f32_e32 v201, 0, v208
	v_max_f32_e32 v216, 0, v209
	v_mfma_f32_16x16x32_bf16 v[250:253], v[34:37], v[230:233], 0
	v_fmac_f32_e32 v222, v7, v9
	v_fmac_f32_e32 v221, v7, v200
	v_fmac_f32_e32 v224, v7, v201
	v_fmac_f32_e32 v223, v7, v216
	v_mfma_f32_16x16x32_bf16 v[246:249], v[30:33], v[234:237], v[246:249]
	v_max_f32_e32 v9, 0, v210
	v_max_f32_e32 v200, 0, v211
	v_max_f32_e32 v201, 0, v212
	v_max_f32_e32 v216, 0, v213
	v_mfma_f32_16x16x32_bf16 v[250:253], v[38:41], v[234:237], v[250:253]
	v_fmac_f32_e32 v226, v7, v9
	v_fmac_f32_e32 v225, v7, v200
	v_fmac_f32_e32 v228, v7, v201
	v_fmac_f32_e32 v227, v7, v216
	ds_read_b128 v[230:233], v158
	ds_read_b128 v[234:237], v157
	ds_read_b32 v7, v137 offset:576
	s_waitcnt lgkmcnt(4)
	v_mfma_f32_16x16x32_bf16 v[206:209], v[26:29], v[238:241], 0
	v_max_f32_e32 v9, 0, v246
	v_max_f32_e32 v200, 0, v247
	v_max_f32_e32 v201, 0, v248
	v_max_f32_e32 v216, 0, v249
	v_mfma_f32_16x16x32_bf16 v[210:213], v[34:37], v[238:241], 0
	v_fmac_f32_e32 v222, v217, v9
	v_fmac_f32_e32 v221, v217, v200
	v_fmac_f32_e32 v224, v217, v201
	v_fmac_f32_e32 v223, v217, v216
	v_mfma_f32_16x16x32_bf16 v[206:209], v[30:33], v[242:245], v[206:209]
	v_max_f32_e32 v9, 0, v250
	v_max_f32_e32 v200, 0, v251
	v_max_f32_e32 v201, 0, v252
	v_max_f32_e32 v216, 0, v253
	v_mfma_f32_16x16x32_bf16 v[210:213], v[38:41], v[242:245], v[210:213]
	v_fmac_f32_e32 v226, v217, v9
	v_fmac_f32_e32 v225, v217, v200
	v_fmac_f32_e32 v228, v217, v201
	v_fmac_f32_e32 v227, v217, v216
	ds_read_b128 v[238:241], v156
	ds_read_b128 v[242:245], v155
	ds_read_b32 v217, v137 offset:640
	s_waitcnt lgkmcnt(4)
; #define LAS __attribute__((address_space(3)))
; __device__ __forceinline__ unsigned fkey(float f) { const unsigned u = __float_as_uint(f); return (u & 0x80000000u) ? ~u : (u | 0x80000000u); }
; #define SEL_HADD(idx_) __hip_atomic_fetch_add(&hist[(idx_)], 1u, __ATOMIC_RELAXED, __HIP_MEMORY_SCOPE_WORKGROUP)
; __device__ __forceinline__ void sel_unit(LAS char* lds, int b, int u, const bf16_t* QI, const bf16_t* KIDX, const float* WIDX, unsigned long long* MASK) {
;     ...
;     for (int j = 0; j < 8; ++j) {
;         if (j < nj) {
;             int t = wid + 8 * j; asm volatile("" : "+s"(t));
; #pragma unroll
;             for (int kh = 0; kh < 2; ++kh) {
;             bf16x8 kf[2][2];
; #pragma unroll
;             for (int kb = 0; kb < 2; ++kb)
; #pragma unroll
;                 for (int ks = 0; ks < 2; ++ks) kf[kb][ks] = *(const bf16x8*)(KIDX + (rowbase + 64 * t + 32 * kh + 16 * kb + q16) * 64 + 32 * ks + 8 * kg);
; #pragma unroll
;             for (int kb = 0; kb < 2; ++kb) {
;                 f32x4 s = (f32x4){0.f, 0.f, 0.f, 0.f};
; #pragma unroll
;                 for (int hh = 0; hh < 8; ++hh) {
;                     f32x4 a = (f32x4){0.f, 0.f, 0.f, 0.f};
; #pragma unroll
;                     for (int ks = 0; ks < 2; ++ks) {
;                         const bf16x8 qv = *(const LAS bf16x8*)(lds + L_QI + q16 * 1024 + (((hh * 8 + 4 * ks + kg) ^ q16) << 4));
;                         a = __builtin_amdgcn_mfma_f32_16x16x32_bf16(kf[kb][ks], qv, a, 0, 0, 0);
;                     }
;                     const float wh = wl[hh * 16];
; #pragma unroll
;                     for (int i = 0; i < 4; ++i) s[i] += wh * fmaxf(a[i], 0.f);
;                 }
;                 u32x4 kk; kk.x = fkey(s[0]); kk.y = fkey(s[1]); kk.z = fkey(s[2]); kk.w = fkey(s[3]);
;                 sc[j][2 * kh + kb] = kk;
; #pragma unroll
;                 for (int i = 0; i < 4; ++i) SEL_HADD((kk[i] >> 24) * 16 + q16);
;                 __builtin_amdgcn_sched_barrier(0);
;             }
	v_mfma_f32_16x16x32_bf16 v[246:249], v[26:29], v[230:233], 0
	v_max_f32_e32 v9, 0, v206
	v_max_f32_e32 v200, 0, v207
	v_max_f32_e32 v201, 0, v208
	v_max_f32_e32 v216, 0, v209
	v_mfma_f32_16x16x32_bf16 v[250:253], v[34:37], v[230:233], 0
	v_fmac_f32_e32 v222, v6, v9
	v_fmac_f32_e32 v221, v6, v200
	v_fmac_f32_e32 v224, v6, v201
	v_fmac_f32_e32 v223, v6, v216
	v_mfma_f32_16x16x32_bf16 v[246:249], v[30:33], v[234:237], v[246:249]
	v_max_f32_e32 v9, 0, v210
	v_max_f32_e32 v200, 0, v211
	v_max_f32_e32 v201, 0, v212
	v_max_f32_e32 v216, 0, v213
	v_mfma_f32_16x16x32_bf16 v[250:253], v[38:41], v[234:237], v[250:253]
	v_fmac_f32_e32 v226, v6, v9
	v_fmac_f32_e32 v225, v6, v200
	v_fmac_f32_e32 v228, v6, v201
	v_fmac_f32_e32 v227, v6, v216
	ds_read_b128 v[230:233], v154
	ds_read_b128 v[234:237], v153
	ds_read_b32 v6, v137 offset:704
	s_waitcnt lgkmcnt(4)
	v_mfma_f32_16x16x32_bf16 v[206:209], v[26:29], v[238:241], 0
	v_max_f32_e32 v9, 0, v246
	v_max_f32_e32 v200, 0, v247
	v_max_f32_e32 v201, 0, v248
	v_max_f32_e32 v216, 0, v249
	v_mfma_f32_16x16x32_bf16 v[210:213], v[34:37], v[238:241], 0
	v_fmac_f32_e32 v222, v7, v9
	v_fmac_f32_e32 v221, v7, v200
	v_fmac_f32_e32 v224, v7, v201
	v_fmac_f32_e32 v223, v7, v216
	v_mfma_f32_16x16x32_bf16 v[206:209], v[30:33], v[242:245], v[206:209]
	v_max_f32_e32 v9, 0, v250
	v_max_f32_e32 v200, 0, v251
	v_max_f32_e32 v201, 0, v252
	v_max_f32_e32 v216, 0, v253
	v_mfma_f32_16x16x32_bf16 v[210:213], v[38:41], v[242:245], v[210:213]
	v_fmac_f32_e32 v226, v7, v9
	v_fmac_f32_e32 v225, v7, v200
	v_fmac_f32_e32 v228, v7, v201
	v_fmac_f32_e32 v227, v7, v216
	ds_read_b128 v[238:241], v152
	ds_read_b128 v[242:245], v151
	ds_read_b32 v7, v137 offset:768
	s_waitcnt lgkmcnt(4)
	v_mfma_f32_16x16x32_bf16 v[246:249], v[26:29], v[230:233], 0
	v_max_f32_e32 v9, 0, v206
	v_max_f32_e32 v200, 0, v207
	v_max_f32_e32 v201, 0, v208
	v_max_f32_e32 v216, 0, v209
	v_mfma_f32_16x16x32_bf16 v[250:253], v[34:37], v[230:233], 0
	v_fmac_f32_e32 v222, v217, v9
	v_fmac_f32_e32 v221, v217, v200
	v_fmac_f32_e32 v224, v217, v201
	v_fmac_f32_e32 v223, v217, v216
	v_mfma_f32_16x16x32_bf16 v[246:249], v[30:33], v[234:237], v[246:249]
	v_max_f32_e32 v9, 0, v210
	v_max_f32_e32 v200, 0, v211
	v_max_f32_e32 v201, 0, v212
	v_max_f32_e32 v216, 0, v213
	v_mfma_f32_16x16x32_bf16 v[250:253], v[38:41], v[234:237], v[250:253]
	v_fmac_f32_e32 v226, v217, v9
	v_fmac_f32_e32 v225, v217, v200
	v_fmac_f32_e32 v228, v217, v201
	v_fmac_f32_e32 v227, v217, v216
	ds_read_b128 v[230:233], v182
	ds_read_b128 v[234:237], v183
	ds_read_b32 v217, v137 offset:320
	s_waitcnt lgkmcnt(4)
	v_mfma_f32_16x16x32_bf16 v[206:209], v[26:29], v[238:241], 0
	v_max_f32_e32 v9, 0, v246
	v_max_f32_e32 v200, 0, v247
	v_max_f32_e32 v201, 0, v248
	v_max_f32_e32 v216, 0, v249
	v_mfma_f32_16x16x32_bf16 v[210:213], v[34:37], v[238:241], 0
	v_fmac_f32_e32 v222, v6, v9
	v_fmac_f32_e32 v221, v6, v200
	v_fmac_f32_e32 v224, v6, v201
	v_fmac_f32_e32 v223, v6, v216
	v_mfma_f32_16x16x32_bf16 v[206:209], v[30:33], v[242:245], v[206:209]
	v_max_f32_e32 v9, 0, v250
	v_max_f32_e32 v200, 0, v251
	v_max_f32_e32 v201, 0, v252
	v_max_f32_e32 v216, 0, v253
	v_mfma_f32_16x16x32_bf16 v[210:213], v[38:41], v[242:245], v[210:213]
	v_fmac_f32_e32 v226, v6, v9
	v_fmac_f32_e32 v225, v6, v200
	v_fmac_f32_e32 v228, v6, v201
	v_fmac_f32_e32 v227, v6, v216
	ds_read_b128 v[238:241], v184
	ds_read_b128 v[242:245], v185
	ds_read_b32 v6, v137 offset:384
	s_waitcnt vmcnt(0)
	s_waitcnt lgkmcnt(4)
	v_mfma_f32_16x16x32_bf16 v[246:249], v[42:45], v[230:233], 0
	v_max_f32_e32 v9, 0, v206
	v_max_f32_e32 v200, 0, v207
	v_max_f32_e32 v201, 0, v208
	v_max_f32_e32 v216, 0, v209
	v_fmac_f32_e32 v222, v7, v9
	v_fmac_f32_e32 v221, v7, v200
	v_fmac_f32_e32 v224, v7, v201
	v_fmac_f32_e32 v223, v7, v216
	v_max_f32_e32 v9, 0, v210
	v_max_f32_e32 v200, 0, v211
	v_max_f32_e32 v201, 0, v212
	v_max_f32_e32 v216, 0, v213
	v_fmac_f32_e32 v226, v7, v9
	v_fmac_f32_e32 v225, v7, v200
	v_mfma_f32_16x16x32_bf16 v[250:253], v[50:53], v[230:233], 0
	v_fmac_f32_e32 v228, v7, v201
	v_fmac_f32_e32 v227, v7, v216
	v_ashrrev_i32_e32 v9, 31, v222
	v_bitop3_b32 v222, v9, v222, v8 bitop3:0x36
	v_ashrrev_i32_e32 v200, 31, v221
	v_bitop3_b32 v221, v200, v221, v8 bitop3:0x36
	v_ashrrev_i32_e32 v201, 31, v224
	v_bitop3_b32 v224, v201, v224, v8 bitop3:0x36
	v_ashrrev_i32_e32 v216, 31, v223
	v_bitop3_b32 v223, v216, v223, v8 bitop3:0x36
	v_ashrrev_i32_e32 v9, 31, v226
	v_bitop3_b32 v226, v9, v226, v8 bitop3:0x36
	v_ashrrev_i32_e32 v200, 31, v225
	v_bitop3_b32 v225, v200, v225, v8 bitop3:0x36
	v_mfma_f32_16x16x32_bf16 v[246:249], v[46:49], v[234:237], v[246:249]
	v_ashrrev_i32_e32 v201, 31, v228
	v_bitop3_b32 v228, v201, v228, v8 bitop3:0x36
	v_ashrrev_i32_e32 v216, 31, v227
	v_bitop3_b32 v227, v216, v227, v8 bitop3:0x36
	v_lshrrev_b32_e32 v9, 24, v222
	v_lshl_add_u32 v9, v9, 6, v0
	ds_add_u32 v9, v205 offset:16384
	v_lshrrev_b32_e32 v200, 24, v221
	v_lshl_add_u32 v200, v200, 6, v0
	ds_add_u32 v200, v205 offset:16384
	v_lshrrev_b32_e32 v201, 24, v224
	v_lshl_add_u32 v201, v201, 6, v0
	ds_add_u32 v201, v205 offset:16384
	v_lshrrev_b32_e32 v216, 24, v223
	v_mfma_f32_16x16x32_bf16 v[250:253], v[2:5], v[234:237], v[250:253]
	v_lshl_add_u32 v216, v216, 6, v0
	ds_add_u32 v216, v205 offset:16384
	v_lshrrev_b32_e32 v9, 24, v226
	v_lshl_add_u32 v9, v9, 6, v0
	ds_add_u32 v9, v205 offset:16384
	v_lshrrev_b32_e32 v200, 24, v225
	v_lshl_add_u32 v200, v200, 6, v0
	ds_add_u32 v200, v205 offset:16384
	v_lshrrev_b32_e32 v201, 24, v228
	v_lshl_add_u32 v201, v201, 6, v0
	ds_add_u32 v201, v205 offset:16384
	v_lshrrev_b32_e32 v216, 24, v227
	v_lshl_add_u32 v216, v216, 6, v0
	ds_add_u32 v216, v205 offset:16384
	ds_read_b128 v[230:233], v179
	ds_read_b128 v[234:237], v180
	ds_read_b32 v7, v137 offset:448
	s_waitcnt lgkmcnt(12)
; #define LAS __attribute__((address_space(3)))
; __device__ __forceinline__ unsigned fkey(float f) { const unsigned u = __float_as_uint(f); return (u & 0x80000000u) ? ~u : (u | 0x80000000u); }
; __device__ __forceinline__ void sel_unit(LAS char* lds, int b, int u, const bf16_t* QI, const bf16_t* KIDX, const float* WIDX, unsigned long long* MASK) {
;     ...
;             for (int kb = 0; kb < 2; ++kb) {
;                 f32x4 s = (f32x4){0.f, 0.f, 0.f, 0.f};
; #pragma unroll
;                 for (int hh = 0; hh < 8; ++hh) {
;                     f32x4 a = (f32x4){0.f, 0.f, 0.f, 0.f};
; #pragma unroll
;                     for (int ks = 0; ks < 2; ++ks) {
;                         const bf16x8 qv = *(const LAS bf16x8*)(lds + L_QI + q16 * 1024 + (((hh * 8 + 4 * ks + kg) ^ q16) << 4));
;                         a = __builtin_amdgcn_mfma_f32_16x16x32_bf16(kf[kb][ks], qv, a, 0, 0, 0);
;                     }
;                     const float wh = wl[hh * 16];
; #pragma unroll
;                     for (int i = 0; i < 4; ++i) s[i] += wh * fmaxf(a[i], 0.f);
;                 }
;                 u32x4 kk; kk.x = fkey(s[0]); kk.y = fkey(s[1]); kk.z = fkey(s[2]); kk.w = fkey(s[3]);
	v_mfma_f32_16x16x32_bf16 v[206:209], v[42:45], v[238:241], 0
	v_max_f32_e32 v9, 0, v246
	v_max_f32_e32 v200, 0, v247
	v_max_f32_e32 v201, 0, v248
	v_max_f32_e32 v216, 0, v249
	v_mfma_f32_16x16x32_bf16 v[210:213], v[50:53], v[238:241], 0
	v_mul_f32_e32 v11, v217, v9
	v_mul_f32_e32 v10, v217, v200
	v_mul_f32_e32 v13, v217, v201
	v_mul_f32_e32 v12, v217, v216
	v_mfma_f32_16x16x32_bf16 v[206:209], v[46:49], v[242:245], v[206:209]
	v_max_f32_e32 v9, 0, v250
	v_max_f32_e32 v200, 0, v251
	v_max_f32_e32 v201, 0, v252
	v_max_f32_e32 v216, 0, v253
	v_mfma_f32_16x16x32_bf16 v[210:213], v[2:5], v[242:245], v[210:213]
	v_mul_f32_e32 v15, v217, v9
	v_mul_f32_e32 v14, v217, v200
	v_mul_f32_e32 v17, v217, v201
	v_mul_f32_e32 v16, v217, v216
	ds_read_b128 v[238:241], v176
	ds_read_b128 v[242:245], v159
	ds_read_b32 v217, v137 offset:512
	s_waitcnt lgkmcnt(4)
	v_mfma_f32_16x16x32_bf16 v[246:249], v[42:45], v[230:233], 0
	v_max_f32_e32 v9, 0, v206
	v_max_f32_e32 v200, 0, v207
	v_max_f32_e32 v201, 0, v208
	v_max_f32_e32 v216, 0, v209
	v_mfma_f32_16x16x32_bf16 v[250:253], v[50:53], v[230:233], 0
	v_fmac_f32_e32 v11, v6, v9
	v_fmac_f32_e32 v10, v6, v200
	v_fmac_f32_e32 v13, v6, v201
	v_fmac_f32_e32 v12, v6, v216
	v_mfma_f32_16x16x32_bf16 v[246:249], v[46:49], v[234:237], v[246:249]
	v_max_f32_e32 v9, 0, v210
	v_max_f32_e32 v200, 0, v211
	v_max_f32_e32 v201, 0, v212
	v_max_f32_e32 v216, 0, v213
	v_mfma_f32_16x16x32_bf16 v[250:253], v[2:5], v[234:237], v[250:253]
	v_fmac_f32_e32 v15, v6, v9
	v_fmac_f32_e32 v14, v6, v200
	v_fmac_f32_e32 v17, v6, v201
	v_fmac_f32_e32 v16, v6, v216
	ds_read_b128 v[230:233], v158
	ds_read_b128 v[234:237], v157
	ds_read_b32 v6, v137 offset:576
	s_waitcnt lgkmcnt(4)
	v_mfma_f32_16x16x32_bf16 v[206:209], v[42:45], v[238:241], 0
	v_max_f32_e32 v9, 0, v246
	v_max_f32_e32 v200, 0, v247
	v_max_f32_e32 v201, 0, v248
	v_max_f32_e32 v216, 0, v249
	v_mfma_f32_16x16x32_bf16 v[210:213], v[50:53], v[238:241], 0
	v_fmac_f32_e32 v11, v7, v9
	v_fmac_f32_e32 v10, v7, v200
	v_fmac_f32_e32 v13, v7, v201
	v_fmac_f32_e32 v12, v7, v216
	v_mfma_f32_16x16x32_bf16 v[206:209], v[46:49], v[242:245], v[206:209]
	v_max_f32_e32 v9, 0, v250
	v_max_f32_e32 v200, 0, v251
	v_max_f32_e32 v201, 0, v252
	v_max_f32_e32 v216, 0, v253
	v_mfma_f32_16x16x32_bf16 v[210:213], v[2:5], v[242:245], v[210:213]
	v_fmac_f32_e32 v15, v7, v9
	v_fmac_f32_e32 v14, v7, v200
	v_fmac_f32_e32 v17, v7, v201
	v_fmac_f32_e32 v16, v7, v216
	ds_read_b128 v[238:241], v156
	ds_read_b128 v[242:245], v155
	ds_read_b32 v7, v137 offset:640
	s_waitcnt lgkmcnt(4)
	v_mfma_f32_16x16x32_bf16 v[246:249], v[42:45], v[230:233], 0
	v_max_f32_e32 v9, 0, v206
	v_max_f32_e32 v200, 0, v207
	v_max_f32_e32 v201, 0, v208
	v_max_f32_e32 v216, 0, v209
	v_mfma_f32_16x16x32_bf16 v[250:253], v[50:53], v[230:233], 0
	v_fmac_f32_e32 v11, v217, v9
	v_fmac_f32_e32 v10, v217, v200
	v_fmac_f32_e32 v13, v217, v201
	v_fmac_f32_e32 v12, v217, v216
	v_mfma_f32_16x16x32_bf16 v[246:249], v[46:49], v[234:237], v[246:249]
	v_max_f32_e32 v9, 0, v210
	v_max_f32_e32 v200, 0, v211
	v_max_f32_e32 v201, 0, v212
	v_max_f32_e32 v216, 0, v213
	v_mfma_f32_16x16x32_bf16 v[250:253], v[2:5], v[234:237], v[250:253]
	v_fmac_f32_e32 v15, v217, v9
	v_fmac_f32_e32 v14, v217, v200
	v_fmac_f32_e32 v17, v217, v201
	v_fmac_f32_e32 v16, v217, v216
	ds_read_b128 v[230:233], v154
	ds_read_b128 v[234:237], v153
	ds_read_b32 v217, v137 offset:704
	s_waitcnt lgkmcnt(4)
; #define LAS __attribute__((address_space(3)))
; #define SEL_HADD(idx_) __hip_atomic_fetch_add(&hist[(idx_)], 1u, __ATOMIC_RELAXED, __HIP_MEMORY_SCOPE_WORKGROUP)
; __device__ __forceinline__ unsigned fkey(float f) { const unsigned u = __float_as_uint(f); return (u & 0x80000000u) ? ~u : (u | 0x80000000u); }
; __device__ __forceinline__ void sel_unit(LAS char* lds, int b, int u, const bf16_t* QI, const bf16_t* KIDX, const float* WIDX, unsigned long long* MASK) {
;     ...
;             for (int kb = 0; kb < 2; ++kb) {
;                 f32x4 s = (f32x4){0.f, 0.f, 0.f, 0.f};
; #pragma unroll
;                 for (int hh = 0; hh < 8; ++hh) {
;                     f32x4 a = (f32x4){0.f, 0.f, 0.f, 0.f};
; #pragma unroll
;                     for (int ks = 0; ks < 2; ++ks) {
;                         const bf16x8 qv = *(const LAS bf16x8*)(lds + L_QI + q16 * 1024 + (((hh * 8 + 4 * ks + kg) ^ q16) << 4));
;                         a = __builtin_amdgcn_mfma_f32_16x16x32_bf16(kf[kb][ks], qv, a, 0, 0, 0);
;                     }
;                     const float wh = wl[hh * 16];
; #pragma unroll
;                     for (int i = 0; i < 4; ++i) s[i] += wh * fmaxf(a[i], 0.f);
;                 }
;                 u32x4 kk; kk.x = fkey(s[0]); kk.y = fkey(s[1]); kk.z = fkey(s[2]); kk.w = fkey(s[3]);
;                 sc[j][2 * kh + kb] = kk;
; #pragma unroll
;                 for (int i = 0; i < 4; ++i) SEL_HADD((kk[i] >> 24) * 16 + q16);
;                 __builtin_amdgcn_sched_barrier(0);
;             }
	v_mfma_f32_16x16x32_bf16 v[206:209], v[42:45], v[238:241], 0
	v_max_f32_e32 v9, 0, v246
	v_max_f32_e32 v200, 0, v247
	v_max_f32_e32 v201, 0, v248
	v_max_f32_e32 v216, 0, v249
	v_mfma_f32_16x16x32_bf16 v[210:213], v[50:53], v[238:241], 0
	v_fmac_f32_e32 v11, v6, v9
	v_fmac_f32_e32 v10, v6, v200
	v_fmac_f32_e32 v13, v6, v201
	v_fmac_f32_e32 v12, v6, v216
	v_mfma_f32_16x16x32_bf16 v[206:209], v[46:49], v[242:245], v[206:209]
	v_max_f32_e32 v9, 0, v250
	v_max_f32_e32 v200, 0, v251
	v_max_f32_e32 v201, 0, v252
	v_max_f32_e32 v216, 0, v253
	v_mfma_f32_16x16x32_bf16 v[210:213], v[2:5], v[242:245], v[210:213]
	v_fmac_f32_e32 v15, v6, v9
	v_fmac_f32_e32 v14, v6, v200
	v_fmac_f32_e32 v17, v6, v201
	v_fmac_f32_e32 v16, v6, v216
	ds_read_b128 v[238:241], v152
	ds_read_b128 v[242:245], v151
	ds_read_b32 v6, v137 offset:768
	s_waitcnt lgkmcnt(4)
	v_mfma_f32_16x16x32_bf16 v[246:249], v[42:45], v[230:233], 0
	v_max_f32_e32 v9, 0, v206
	v_max_f32_e32 v200, 0, v207
	v_max_f32_e32 v201, 0, v208
	v_max_f32_e32 v216, 0, v209
	v_mfma_f32_16x16x32_bf16 v[250:253], v[50:53], v[230:233], 0
	v_fmac_f32_e32 v11, v7, v9
	v_fmac_f32_e32 v10, v7, v200
	v_fmac_f32_e32 v13, v7, v201
	v_fmac_f32_e32 v12, v7, v216
	v_mfma_f32_16x16x32_bf16 v[246:249], v[46:49], v[234:237], v[246:249]
	v_max_f32_e32 v9, 0, v210
	v_max_f32_e32 v200, 0, v211
	v_max_f32_e32 v201, 0, v212
	v_max_f32_e32 v216, 0, v213
	v_mfma_f32_16x16x32_bf16 v[250:253], v[2:5], v[234:237], v[250:253]
	v_fmac_f32_e32 v15, v7, v9
	v_fmac_f32_e32 v14, v7, v200
	v_fmac_f32_e32 v17, v7, v201
	v_fmac_f32_e32 v16, v7, v216
	s_waitcnt lgkmcnt(1)
	v_mfma_f32_16x16x32_bf16 v[206:209], v[42:45], v[238:241], 0
	v_max_f32_e32 v9, 0, v246
	v_max_f32_e32 v200, 0, v247
	v_max_f32_e32 v201, 0, v248
	v_max_f32_e32 v216, 0, v249
	v_mfma_f32_16x16x32_bf16 v[210:213], v[50:53], v[238:241], 0
	v_fmac_f32_e32 v11, v217, v9
	v_fmac_f32_e32 v10, v217, v200
	v_fmac_f32_e32 v13, v217, v201
	v_fmac_f32_e32 v12, v217, v216
	v_mfma_f32_16x16x32_bf16 v[206:209], v[46:49], v[242:245], v[206:209]
	v_max_f32_e32 v9, 0, v250
	v_max_f32_e32 v200, 0, v251
	v_max_f32_e32 v201, 0, v252
	v_max_f32_e32 v216, 0, v253
	v_mfma_f32_16x16x32_bf16 v[210:213], v[2:5], v[242:245], v[210:213]
	v_fmac_f32_e32 v15, v217, v9
	v_fmac_f32_e32 v14, v217, v200
	v_fmac_f32_e32 v17, v217, v201
	v_fmac_f32_e32 v16, v217, v216
	s_waitcnt lgkmcnt(0)
	v_max_f32_e32 v9, 0, v206
	v_max_f32_e32 v200, 0, v207
	v_max_f32_e32 v201, 0, v208
	v_max_f32_e32 v216, 0, v209
	v_fmac_f32_e32 v11, v6, v9
	v_fmac_f32_e32 v10, v6, v200
	v_fmac_f32_e32 v13, v6, v201
	v_fmac_f32_e32 v12, v6, v216
	v_max_f32_e32 v9, 0, v210
	v_max_f32_e32 v200, 0, v211
	v_max_f32_e32 v201, 0, v212
	v_max_f32_e32 v216, 0, v213
	v_fmac_f32_e32 v15, v6, v9
	v_fmac_f32_e32 v14, v6, v200
	v_fmac_f32_e32 v17, v6, v201
	v_fmac_f32_e32 v16, v6, v216
	v_ashrrev_i32_e32 v9, 31, v11
	v_bitop3_b32 v11, v9, v11, v8 bitop3:0x36
	v_ashrrev_i32_e32 v200, 31, v10
	v_bitop3_b32 v10, v200, v10, v8 bitop3:0x36
	v_ashrrev_i32_e32 v201, 31, v13
	v_bitop3_b32 v13, v201, v13, v8 bitop3:0x36
	v_ashrrev_i32_e32 v216, 31, v12
	v_bitop3_b32 v12, v216, v12, v8 bitop3:0x36
	v_ashrrev_i32_e32 v9, 31, v15
	v_bitop3_b32 v15, v9, v15, v8 bitop3:0x36
	v_ashrrev_i32_e32 v200, 31, v14
	v_bitop3_b32 v14, v200, v14, v8 bitop3:0x36
	v_ashrrev_i32_e32 v201, 31, v17
	v_bitop3_b32 v17, v201, v17, v8 bitop3:0x36
	v_ashrrev_i32_e32 v216, 31, v16
	v_bitop3_b32 v16, v216, v16, v8 bitop3:0x36
	v_lshrrev_b32_e32 v9, 24, v11
	v_lshl_add_u32 v9, v9, 6, v0
	ds_add_u32 v9, v205 offset:16384
	v_lshrrev_b32_e32 v200, 24, v10
	v_lshl_add_u32 v200, v200, 6, v0
	ds_add_u32 v200, v205 offset:16384
	v_lshrrev_b32_e32 v201, 24, v13
	v_lshl_add_u32 v201, v201, 6, v0
	ds_add_u32 v201, v205 offset:16384
	v_lshrrev_b32_e32 v216, 24, v12
	v_lshl_add_u32 v216, v216, 6, v0
	ds_add_u32 v216, v205 offset:16384
	v_lshrrev_b32_e32 v9, 24, v15
	v_lshl_add_u32 v9, v9, 6, v0
	ds_add_u32 v9, v205 offset:16384
	v_lshrrev_b32_e32 v200, 24, v14
	v_lshl_add_u32 v200, v200, 6, v0
	ds_add_u32 v200, v205 offset:16384
	v_lshrrev_b32_e32 v201, 24, v17
	v_lshl_add_u32 v201, v201, 6, v0
	ds_add_u32 v201, v205 offset:16384
	v_lshrrev_b32_e32 v216, 24, v16
	v_lshl_add_u32 v216, v216, 6, v0
	ds_add_u32 v216, v205 offset:16384
